# GDN phase: f32->bf16 bit-trick roundings (bfe/add3/lshr/and_or) replaced by v_cvt_pk_bf16_f32 via a dataflow-checked peephole (46 packed pairs, 73 singles)
# baseline (speedup 1.0000x reference)
; #define LAS __attribute__((address_space(3)))
; DI unsigned pk2(float lo, float hi) { return f2bf(lo) | (f2bf(hi) << 16); }
; DI void lds_barrier() { asm volatile("s_waitcnt lgkmcnt(0)" ::: "memory"); __builtin_amdgcn_s_barrier(); asm volatile("" ::: "memory"); }
; #define MFMA16(a, b, c) __builtin_amdgcn_mfma_f32_16x16x32_bf16((a), (b), (c), 0, 0, 0)
; DI void gdn_unit(const Params& P, bf16_t* proj, const float* gb, int b, int h, LAS unsigned char* lds) {
;     ...
;             const float glast = __expf(gc_last);
;             bf16x8 vsb[2];
; #pragma unroll
;             for (int ks = 0; ks < 2; ++ks) vsb[ks] = ldsfrag(lds + VNS_OFF + (16 * wave + fr) * 144 + (ks * 32 + fq * 8) * 2);
; #pragma unroll
;             for (int dt = 0; dt < 8; ++dt) {
;                 f32x4 a = Sacc[dt] * glast;
;                 bf16x8 kf[2];
; #pragma unroll
;                 for (int ks = 0; ks < 2; ++ks) kf[ks] = ldsfrag(lds + KT_OFF + (dt * 16 + fr) * 144 + (ks * 32 + fq * 8) * 2);
; #pragma unroll
;                 for (int ks = 0; ks < 2; ++ks) a = MFMA16(kf[ks], vsb[ks], a);
;                 Sacc[dt] = a;
;             }
;         }
;         lds_barrier();
;         {
;             bf16_t* obase = proj + (size_t)t0 * PJ1 + 3072 + h * 128 + 16 * wave;
;             const int ooffl = fq * 4 * PJ1 + fr;
; #pragma unroll
;             for (int dt = 0; dt < 8; ++dt) {
;                 u32x2 p; p.x = pk2(Sacc[dt][0], Sacc[dt][1]); p.y = pk2(Sacc[dt][2], Sacc[dt][3]);
;                 *(LAS u32x2*)(lds + ST_OFF + (16 * wave + fr) * 272 + (dt * 16 + fq * 4) * 2) = p;
;             }
; #pragma unroll
;             for (int tt = 0; tt < 4; ++tt) {
;                 f32x4 pw[8];
; #pragma unroll
;                 for (int w = 0; w < 8; ++w) pw[w] = *(const LAS f32x4*)(part + w * 64 + tt * 16 + fq * 4);
.LBB0_414:
	s_or_b64 exec, exec, s[0:1]
	v_add_u32_e32 v139, v135, v150
	ds_read_b128 v[52:55], v139 offset:34816
	v_mul_f32_e32 v48, s18, v168
	v_exp_f32_e32 v138, v48
	v_add_u32_e32 v49, v151, v134
	ds_read_b128 v[56:59], v49
	ds_read_b128 v[48:51], v49 offset:64
	ds_read_b128 v[60:63], v139 offset:34880
	ds_read_b128 v[224:227], v139 offset:50944
	v_pk_mul_f32 v[2:3], v[2:3], v[138:139] op_sel_hi:[1,0]
	v_pk_mul_f32 v[0:1], v[0:1], v[138:139] op_sel_hi:[1,0]
	v_pk_mul_f32 v[6:7], v[6:7], v[138:139] op_sel_hi:[1,0]
	v_pk_mul_f32 v[4:5], v[4:5], v[138:139] op_sel_hi:[1,0]
	s_waitcnt lgkmcnt(3)
	v_mfma_f32_16x16x32_bf16 v[0:3], v[52:55], v[56:59], v[0:3]
	ds_read_b128 v[52:55], v139 offset:37120
	v_pk_mul_f32 v[10:11], v[10:11], v[138:139] op_sel_hi:[1,0]
	v_pk_mul_f32 v[8:9], v[8:9], v[138:139] op_sel_hi:[1,0]
	s_waitcnt lgkmcnt(2)
	v_mfma_f32_16x16x32_bf16 v[0:3], v[60:63], v[48:51], v[0:3]
	ds_read_b128 v[60:63], v139 offset:37184
	v_pk_mul_f32 v[14:15], v[14:15], v[138:139] op_sel_hi:[1,0]
	v_pk_mul_f32 v[12:13], v[12:13], v[138:139] op_sel_hi:[1,0]
	s_waitcnt lgkmcnt(1)
	v_mfma_f32_16x16x32_bf16 v[4:7], v[52:55], v[56:59], v[4:7]
	ds_read_b128 v[52:55], v139 offset:39424
	v_pk_mul_f32 v[18:19], v[18:19], v[138:139] op_sel_hi:[1,0]
	v_pk_mul_f32 v[16:17], v[16:17], v[138:139] op_sel_hi:[1,0]
	s_waitcnt lgkmcnt(1)
	v_mfma_f32_16x16x32_bf16 v[4:7], v[60:63], v[48:51], v[4:7]
	ds_read_b128 v[60:63], v139 offset:39488
	v_pk_mul_f32 v[26:27], v[26:27], v[138:139] op_sel_hi:[1,0]
	ds_read_b128 v[64:67], v139 offset:41792
	s_waitcnt lgkmcnt(2)
	v_mfma_f32_16x16x32_bf16 v[8:11], v[52:55], v[56:59], v[8:11]
	ds_read_b128 v[52:55], v139 offset:41728
	v_pk_mul_f32 v[24:25], v[24:25], v[138:139] op_sel_hi:[1,0]
	s_mov_b64 s[0:1], 0x18003800
	s_waitcnt lgkmcnt(2)
	v_mfma_f32_16x16x32_bf16 v[8:11], v[60:63], v[48:51], v[8:11]
	ds_read_b128 v[60:63], v139 offset:44032
	v_lshl_add_u64 v[134:135], v[118:119], 0, s[0:1]
	s_mov_b64 s[0:1], 0x18005800
	s_waitcnt lgkmcnt(1)
	v_mfma_f32_16x16x32_bf16 v[12:15], v[52:55], v[56:59], v[12:15]
	ds_read_b128 v[52:55], v139 offset:44096
	s_mov_b64 s[2:3], 0x18001800
	v_lshl_add_u64 v[148:149], v[118:119], 0, s[0:1]
	s_waitcnt lgkmcnt(1)
	v_mfma_f32_16x16x32_bf16 v[16:19], v[60:63], v[56:59], v[16:19]
	ds_read_b128 v[60:63], v139 offset:46336
	s_mov_b64 s[0:1], 0x18007800
	v_lshl_add_u64 v[152:153], v[118:119], 0, s[2:3]
	v_mfma_f32_16x16x32_bf16 v[12:15], v[64:67], v[48:51], v[12:15]
	ds_read_b128 v[64:67], v139 offset:46400
	v_lshl_add_u64 v[150:151], v[118:119], 0, s[0:1]
	v_lshl_add_u64 v[118:119], v[124:125], 0, s[2:3]
	s_waitcnt lgkmcnt(2)
	v_mfma_f32_16x16x32_bf16 v[16:19], v[52:55], v[48:51], v[16:19]
	ds_read_b128 v[52:55], v139 offset:48640
	v_pk_mul_f32 v[30:31], v[30:31], v[138:139] op_sel_hi:[1,0]
	v_pk_mul_f32 v[28:29], v[28:29], v[138:139] op_sel_hi:[1,0]
	s_waitcnt lgkmcnt(2)
	v_mfma_f32_16x16x32_bf16 v[24:27], v[60:63], v[56:59], v[24:27]
	ds_read_b128 v[60:63], v139 offset:48704
	v_pk_mul_f32 v[22:23], v[22:23], v[138:139] op_sel_hi:[1,0]
	v_pk_mul_f32 v[20:21], v[20:21], v[138:139] op_sel_hi:[1,0]
	s_waitcnt lgkmcnt(2)
	v_mfma_f32_16x16x32_bf16 v[24:27], v[64:67], v[48:51], v[24:27]
	v_lshl_add_u64 v[66:67], v[122:123], 0, s[2:3]
	ds_read_b128 v[122:125], v139 offset:51008
	s_waitcnt lgkmcnt(0)
	s_waitcnt lgkmcnt(2)
	v_mfma_f32_16x16x32_bf16 v[28:31], v[52:55], v[56:59], v[28:31]
	s_barrier
	v_lshl_add_u64 v[54:55], v[130:131], 0, s[2:3]
	v_mfma_f32_16x16x32_bf16 v[20:23], v[224:227], v[56:59], v[20:23]
	s_nop 0
	s_nop 0
	v_add_u32_e32 v56, v219, v207
	s_waitcnt lgkmcnt(1)
	v_mfma_f32_16x16x32_bf16 v[28:31], v[60:63], v[48:51], v[28:31]
	v_lshl_add_u64 v[60:61], v[128:129], 0, s[2:3]
	v_lshl_add_u64 v[58:59], v[126:127], 0, s[2:3]
	v_lshl_add_u64 v[120:121], v[120:121], 0, s[2:3]
	s_waitcnt lgkmcnt(0)
	v_mfma_f32_16x16x32_bf16 v[20:23], v[122:125], v[48:51], v[20:23]
	s_nop 0
	s_nop 0
	s_nop 0
	s_nop 0
	s_nop 0
	v_cvt_pk_bf16_f32 v48, v0, v1
	s_nop 0
	s_nop 0
	s_nop 0
	s_nop 0
	s_nop 0
	v_cvt_pk_bf16_f32 v49, v2, v3
	v_cvt_pk_bf16_f32 v50, v4, v5
	v_cvt_pk_bf16_f32 v51, v6, v7
	ds_write2_b64 v56, v[48:49], v[50:51] offset1:4
	v_cvt_pk_bf16_f32 v48, v8, v9
	v_cvt_pk_bf16_f32 v49, v10, v11
	v_cvt_pk_bf16_f32 v50, v12, v13
	v_cvt_pk_bf16_f32 v51, v14, v15
	ds_write2_b64 v56, v[48:49], v[50:51] offset0:8 offset1:12
	v_cvt_pk_bf16_f32 v48, v16, v17
	v_cvt_pk_bf16_f32 v49, v18, v19
	v_cvt_pk_bf16_f32 v50, v24, v25
	v_cvt_pk_bf16_f32 v51, v26, v27
	ds_write2_b64 v56, v[48:49], v[50:51] offset0:16 offset1:20
	v_cvt_pk_bf16_f32 v48, v28, v29
	v_cvt_pk_bf16_f32 v49, v30, v31
	v_cvt_pk_bf16_f32 v50, v20, v21
	v_cvt_pk_bf16_f32 v51, v22, v23
	ds_write2_b64 v56, v[48:49], v[50:51] offset0:24 offset1:28
	v_lshl_add_u32 v48, v205, 2, 0
	v_add_u32_e32 v122, 0x25000, v48
	ds_read_b128 v[124:127], v122
	ds_read_b128 v[128:131], v122 offset:256
	ds_read_b128 v[224:227], v122 offset:512
	ds_read_b128 v[228:231], v122 offset:768
	ds_read_b128 v[232:235], v122 offset:1024
	ds_read_b128 v[236:239], v122 offset:1280
	ds_read_b128 v[240:243], v122 offset:1536
	ds_read_b128 v[244:247], v122 offset:1792
	v_lshl_add_u64 v[116:117], v[116:117], 0, s[2:3]
	v_lshl_add_u64 v[52:53], v[132:133], 0, s[2:3]
	v_lshl_add_u64 v[62:63], v[108:109], 0, s[2:3]
	v_lshl_add_u64 v[56:57], v[110:111], 0, s[2:3]
	v_lshl_add_u64 v[50:51], v[112:113], 0, s[2:3]
	v_lshl_add_u64 v[48:49], v[114:115], 0, s[2:3]
	s_waitcnt vmcnt(15)
	v_lshlrev_b32_e32 v112, 16, v223
	v_mul_f32_e32 v111, 0xbfb8aa3b, v112
	v_exp_f32_e32 v113, v111
	s_waitcnt lgkmcnt(7)
	v_mov_b32_e32 v64, v124
	s_waitcnt lgkmcnt(3)
	v_mov_b32_e32 v65, v232
	v_mov_b32_e32 v108, v128
	s_waitcnt lgkmcnt(2)
; #define LAS __attribute__((address_space(3)))
; DI unsigned f2bf(float f) { unsigned u = __float_as_uint(f); u += 0x7FFFu + ((u >> 16) & 1u); return u >> 16; }
; DI float bf2f(unsigned b) { return __uint_as_float(b << 16); }
; DI float siluf_(float x) { return x * __builtin_amdgcn_rcpf(1.0f + __expf(-x)); }
; DI void gdn_unit(const Params& P, bf16_t* proj, const float* gb, int b, int h, LAS unsigned char* lds) {
;     ...
;             for (int tt = 0; tt < 4; ++tt) {
;                 f32x4 pw[8];
; #pragma unroll
;                 for (int w = 0; w < 8; ++w) pw[w] = *(const LAS f32x4*)(part + w * 64 + tt * 16 + fq * 4);
;                 __builtin_amdgcn_sched_barrier(0);
;                 const f32x4 ss = ((pw[0] + pw[1]) + (pw[2] + pw[3])) + ((pw[4] + pw[5]) + (pw[6] + pw[7]));
; #pragma unroll
;                 for (int jj = 0; jj < 4; ++jj) {
;                     const float rstd = rsqrtf(ss[jj] * (1.0f / 128.0f) + 1e-6f);
;                     const float z = bf2f(zr[tt][jj]);
;                     const float o = oacc[tt][jj] * rstd * ng * siluf_(z);
;                     obase[(tt * 16 + jj) * PJ1 + ooffl] = (bf16_t)f2bf(o);
;                 }
;             }
	v_mov_b32_e32 v109, v236
	v_pk_add_f32 v[64:65], v[64:65], v[108:109]
	v_mov_b32_e32 v108, v224
	s_waitcnt lgkmcnt(1)
	v_mov_b32_e32 v109, v240
	v_mov_b32_e32 v110, v228
	s_waitcnt lgkmcnt(0)
	v_mov_b32_e32 v111, v244
	v_pk_add_f32 v[108:109], v[108:109], v[110:111]
	v_mov_b32_e32 v232, v125
	v_pk_add_f32 v[64:65], v[64:65], v[108:109]
	v_add_f32_e32 v108, 1.0, v113
	v_mov_b32_e32 v236, v129
	v_mov_b32_e32 v240, v225
	v_mov_b32_e32 v244, v229
	v_rcp_f32_e32 v113, v108
	v_pk_add_f32 v[108:109], v[232:233], v[236:237]
	v_pk_add_f32 v[110:111], v[240:241], v[244:245]
	s_brev_b32 s2, 60
	v_pk_add_f32 v[108:109], v[108:109], v[110:111]
	v_mov_b32_e32 v111, v64
	v_mov_b32_e32 v110, v108
	v_mov_b32_e32 v64, v109
	v_pk_add_f32 v[108:109], v[110:111], v[64:65]
	v_mov_b64_e32 v[64:65], s[72:73]
	v_pk_fma_f32 v[108:109], v[108:109], s[2:3], v[64:65] op_sel_hi:[1,0,0]
	s_mov_b32 s0, 0x800000
	v_mul_f32_e32 v110, 0x4b800000, v109
	v_cmp_gt_f32_e32 vcc, s0, v109
	s_waitcnt vmcnt(13)
	v_lshlrev_b32_e32 v114, 16, v221
	v_cndmask_b32_e32 v109, v109, v110, vcc
	v_rsq_f32_e32 v109, v109
	v_mul_f32_e32 v110, v113, v112
	v_mul_f32_e32 v111, 0x45800000, v109
	v_cndmask_b32_e32 v109, v109, v111, vcc
	v_mul_f32_e32 v44, v44, v109
	v_mul_f32_e32 v44, v155, v44
	v_mul_f32_e32 v44, v110, v44
	v_mul_f32_e32 v110, 0x4b800000, v108
	v_cmp_gt_f32_e32 vcc, s0, v108
	s_nop 0
	v_cvt_pk_bf16_f32 v44, v44, v44
	v_cndmask_b32_e32 v108, v108, v110, vcc
	v_lshlrev_b32_e32 v110, 16, v222
	v_mul_f32_e32 v111, 0xbfb8aa3b, v110
	v_exp_f32_e32 v111, v111
	v_rsq_f32_e32 v108, v108
	global_store_short_d16_hi v[152:153], v44, off
	v_add_f32_e32 v109, 1.0, v111
	v_rcp_f32_e32 v109, v109
	v_mul_f32_e32 v44, 0x45800000, v108
	v_cndmask_b32_e32 v44, v108, v44, vcc
	v_mul_f32_e32 v44, v45, v44
	v_mul_f32_e32 v111, 0xbfb8aa3b, v114
	v_mul_f32_e32 v44, v155, v44
	v_mul_f32_e32 v45, v109, v110
	v_exp_f32_e32 v115, v111
	v_mul_f32_e32 v112, v45, v44
	v_mov_b32_e32 v44, v126
	v_mov_b32_e32 v45, v234
	v_mov_b32_e32 v108, v130
	v_mov_b32_e32 v109, v238
	v_pk_add_f32 v[44:45], v[44:45], v[108:109]
	v_mov_b32_e32 v108, v226
	v_mov_b32_e32 v109, v242
	v_mov_b32_e32 v110, v230
	v_mov_b32_e32 v111, v246
	v_pk_add_f32 v[108:109], v[108:109], v[110:111]
	v_mov_b32_e32 v234, v127
	v_pk_add_f32 v[44:45], v[44:45], v[108:109]
	v_add_f32_e32 v108, 1.0, v115
	v_mov_b32_e32 v238, v131
	v_mov_b32_e32 v242, v227
	v_mov_b32_e32 v246, v231
	v_rcp_f32_e32 v115, v108
	v_pk_add_f32 v[108:109], v[234:235], v[238:239]
	v_pk_add_f32 v[110:111], v[242:243], v[246:247]
	s_nop 0
	v_pk_add_f32 v[108:109], v[108:109], v[110:111]
	v_mov_b32_e32 v111, v44
	v_mov_b32_e32 v110, v108
	v_mov_b32_e32 v44, v109
	v_pk_add_f32 v[44:45], v[110:111], v[44:45]
	s_nop 0
	v_pk_fma_f32 v[44:45], v[44:45], s[2:3], v[64:65] op_sel_hi:[1,0,0]
	s_nop 0
	v_mul_f32_e32 v108, 0x4b800000, v45
	v_cmp_gt_f32_e32 vcc, s0, v45
	s_nop 1
	v_cndmask_b32_e32 v45, v45, v108, vcc
	v_rsq_f32_e32 v45, v45
	v_cvt_pk_bf16_f32 v108, v112, v112
	global_store_short_d16_hi v[134:135], v108, off
	v_mul_f32_e32 v108, v115, v114
	v_mul_f32_e32 v109, 0x45800000, v45
	v_cndmask_b32_e32 v45, v45, v109, vcc
	v_mul_f32_e32 v45, v46, v45
	v_mul_f32_e32 v45, v155, v45
	v_mul_f32_e32 v45, v108, v45
	v_mul_f32_e32 v108, 0x4b800000, v44
	v_cmp_gt_f32_e32 vcc, s0, v44
	s_nop 0
	v_cvt_pk_bf16_f32 v45, v45, v45
	v_cndmask_b32_e32 v44, v44, v108, vcc
	s_waitcnt vmcnt(14)
	v_lshlrev_b32_e32 v108, 16, v220
	v_mul_f32_e32 v109, 0xbfb8aa3b, v108
	v_exp_f32_e32 v109, v109
	v_rsq_f32_e32 v44, v44
	global_store_short_d16_hi v[148:149], v45, off
	v_add_f32_e32 v46, 1.0, v109
	v_rcp_f32_e32 v46, v46
	v_mul_f32_e32 v45, 0x45800000, v44
	v_cndmask_b32_e32 v44, v44, v45, vcc
	v_mul_f32_e32 v44, v47, v44
	v_mul_f32_e32 v123, v155, v44
	v_mul_f32_e32 v138, v46, v108
	ds_read_b128 v[44:47], v122 offset:64
	ds_read_b128 v[108:111], v122 offset:320
	ds_read_b128 v[112:115], v122 offset:576
	ds_read_b128 v[124:127], v122 offset:832
	ds_read_b128 v[128:131], v122 offset:1088
	ds_read_b128 v[132:135], v122 offset:1344
	ds_read_b128 v[220:223], v122 offset:1600
	ds_read_b128 v[224:227], v122 offset:1856
	v_mul_f32_e32 v123, v138, v123
	s_nop 0
	v_cvt_pk_bf16_f32 v123, v123, v123
	global_store_short_d16_hi v[150:151], v123, off
	s_waitcnt lgkmcnt(7)
	v_mov_b32_e32 v138, v44
	s_waitcnt lgkmcnt(3)
	v_mov_b32_e32 v139, v128
	v_mov_b32_e32 v140, v108
	s_waitcnt lgkmcnt(2)
	v_mov_b32_e32 v141, v132
	v_pk_add_f32 v[138:139], v[138:139], v[140:141]
	v_mov_b32_e32 v140, v112
	s_waitcnt vmcnt(15)
	v_lshlrev_b32_e32 v112, 16, v218
	v_mul_f32_e32 v44, 0xbfb8aa3b, v112
	v_exp_f32_e32 v44, v44
	s_waitcnt lgkmcnt(1)
	v_mov_b32_e32 v141, v220
	v_mov_b32_e32 v144, v124
	s_waitcnt lgkmcnt(0)
	v_mov_b32_e32 v145, v224
	v_add_f32_e32 v44, 1.0, v44
	v_mov_b32_e32 v128, v45
	v_mov_b32_e32 v132, v109
	v_mov_b32_e32 v220, v113
	v_mov_b32_e32 v224, v125
	v_pk_add_f32 v[140:141], v[140:141], v[144:145]
	v_rcp_f32_e32 v123, v44
	v_pk_add_f32 v[44:45], v[128:129], v[132:133]
	v_pk_add_f32 v[108:109], v[220:221], v[224:225]
	v_pk_add_f32 v[138:139], v[138:139], v[140:141]
	v_pk_add_f32 v[44:45], v[44:45], v[108:109]
	v_mov_b32_e32 v109, v138
	v_mov_b32_e32 v108, v44
	v_mov_b32_e32 v138, v45
	v_pk_add_f32 v[44:45], v[108:109], v[138:139]
	s_nop 0
	v_pk_fma_f32 v[44:45], v[44:45], s[2:3], v[64:65] op_sel_hi:[1,0,0]
	s_nop 0
	v_mul_f32_e32 v108, 0x4b800000, v45
	v_cmp_gt_f32_e32 vcc, s0, v45
	s_nop 1
	v_cndmask_b32_e32 v45, v45, v108, vcc
	v_rsq_f32_e32 v45, v45
	v_mul_f32_e32 v108, v123, v112
	v_mul_f32_e32 v109, 0x45800000, v45
	v_cndmask_b32_e32 v45, v45, v109, vcc
	v_mul_f32_e32 v40, v40, v45
	v_mul_f32_e32 v40, v155, v40
	v_mul_f32_e32 v40, v108, v40
	v_mul_f32_e32 v108, 0x4b800000, v44
	v_cmp_gt_f32_e32 vcc, s0, v44
	s_nop 0
	v_cvt_pk_bf16_f32 v40, v40, v40
	v_cndmask_b32_e32 v44, v44, v108, vcc
	s_waitcnt vmcnt(14)
; #define LAS __attribute__((address_space(3)))
; DI unsigned f2bf(float f) { unsigned u = __float_as_uint(f); u += 0x7FFFu + ((u >> 16) & 1u); return u >> 16; }
; DI float bf2f(unsigned b) { return __uint_as_float(b << 16); }
; DI float siluf_(float x) { return x * __builtin_amdgcn_rcpf(1.0f + __expf(-x)); }
; DI void gdn_unit(const Params& P, bf16_t* proj, const float* gb, int b, int h, LAS unsigned char* lds) {
;     ...
;             for (int tt = 0; tt < 4; ++tt) {
;                 f32x4 pw[8];
; #pragma unroll
;                 for (int w = 0; w < 8; ++w) pw[w] = *(const LAS f32x4*)(part + w * 64 + tt * 16 + fq * 4);
;                 __builtin_amdgcn_sched_barrier(0);
;                 const f32x4 ss = ((pw[0] + pw[1]) + (pw[2] + pw[3])) + ((pw[4] + pw[5]) + (pw[6] + pw[7]));
; #pragma unroll
;                 for (int jj = 0; jj < 4; ++jj) {
;                     const float rstd = rsqrtf(ss[jj] * (1.0f / 128.0f) + 1e-6f);
;                     const float z = bf2f(zr[tt][jj]);
;                     const float o = oacc[tt][jj] * rstd * ng * siluf_(z);
;                     obase[(tt * 16 + jj) * PJ1 + ooffl] = (bf16_t)f2bf(o);
;                 }
;             }
	v_lshlrev_b32_e32 v108, 16, v217
	v_mul_f32_e32 v109, 0xbfb8aa3b, v108
	v_exp_f32_e32 v109, v109
	v_rsq_f32_e32 v44, v44
	global_store_short_d16_hi v[120:121], v40, off
	v_add_f32_e32 v45, 1.0, v109
	v_rcp_f32_e32 v45, v45
	v_mul_f32_e32 v40, 0x45800000, v44
	v_cndmask_b32_e32 v40, v44, v40, vcc
	v_mul_f32_e32 v40, v41, v40
	v_mul_f32_e32 v40, v155, v40
	v_mul_f32_e32 v41, v45, v108
	v_mov_b32_e32 v44, v110
	s_waitcnt vmcnt(14)
	v_lshlrev_b32_e32 v110, 16, v216
	v_mul_f32_e32 v112, v41, v40
	v_mov_b32_e32 v40, v46
	v_mul_f32_e32 v46, 0xbfb8aa3b, v110
	v_exp_f32_e32 v46, v46
	v_mov_b32_e32 v41, v130
	v_mov_b32_e32 v45, v134
	v_pk_add_f32 v[40:41], v[40:41], v[44:45]
	v_mov_b32_e32 v44, v114
	v_mov_b32_e32 v45, v222
	v_mov_b32_e32 v108, v126
	v_mov_b32_e32 v109, v226
	v_pk_add_f32 v[44:45], v[44:45], v[108:109]
	v_mov_b32_e32 v130, v47
	v_pk_add_f32 v[40:41], v[40:41], v[44:45]
	v_add_f32_e32 v44, 1.0, v46
	v_mov_b32_e32 v134, v111
	v_mov_b32_e32 v222, v115
	v_mov_b32_e32 v226, v127
	v_rcp_f32_e32 v108, v44
	v_pk_add_f32 v[44:45], v[130:131], v[134:135]
	v_pk_add_f32 v[46:47], v[222:223], v[226:227]
	s_nop 0
	v_pk_add_f32 v[44:45], v[44:45], v[46:47]
	v_mov_b32_e32 v47, v40
	v_mov_b32_e32 v46, v44
	v_mov_b32_e32 v40, v45
	v_pk_add_f32 v[40:41], v[46:47], v[40:41]
	s_nop 0
	v_pk_fma_f32 v[40:41], v[40:41], s[2:3], v[64:65] op_sel_hi:[1,0,0]
	s_nop 0
	v_mul_f32_e32 v44, 0x4b800000, v41
	v_cmp_gt_f32_e32 vcc, s0, v41
	s_nop 1
	v_cndmask_b32_e32 v41, v41, v44, vcc
	v_rsq_f32_e32 v41, v41
	v_cvt_pk_bf16_f32 v44, v112, v112
	global_store_short_d16_hi v[118:119], v44, off
	v_mul_f32_e32 v44, v108, v110
	v_mul_f32_e32 v45, 0x45800000, v41
	v_cndmask_b32_e32 v41, v41, v45, vcc
	v_mul_f32_e32 v41, v42, v41
	v_mul_f32_e32 v41, v155, v41
	v_mul_f32_e32 v41, v44, v41
	v_mul_f32_e32 v44, 0x4b800000, v40
	v_cmp_gt_f32_e32 vcc, s0, v40
	s_nop 0
	v_cvt_pk_bf16_f32 v41, v41, v41
	v_cndmask_b32_e32 v40, v40, v44, vcc
	s_waitcnt vmcnt(14)
	v_lshlrev_b32_e32 v44, 16, v215
	v_mul_f32_e32 v45, 0xbfb8aa3b, v44
	v_exp_f32_e32 v45, v45
	v_rsq_f32_e32 v40, v40
	global_store_short_d16_hi v[116:117], v41, off
	v_add_f32_e32 v42, 1.0, v45
	v_rcp_f32_e32 v42, v42
	v_mul_f32_e32 v41, 0x45800000, v40
	v_cndmask_b32_e32 v40, v40, v41, vcc
	v_mul_f32_e32 v40, v43, v40
	v_mul_f32_e32 v120, v155, v40
	v_mul_f32_e32 v121, v42, v44
	ds_read_b128 v[40:43], v122 offset:128
	ds_read_b128 v[44:47], v122 offset:384
	ds_read_b128 v[108:111], v122 offset:640
	ds_read_b128 v[112:115], v122 offset:896
	ds_read_b128 v[116:119], v122 offset:1152
	ds_read_b128 v[124:127], v122 offset:1408
	ds_read_b128 v[128:131], v122 offset:1664
	ds_read_b128 v[132:135], v122 offset:1920
	v_mul_f32_e32 v120, v121, v120
	s_nop 0
	v_cvt_pk_bf16_f32 v120, v120, v120
	global_store_short_d16_hi v[66:67], v120, off
	s_waitcnt lgkmcnt(7)
	v_mov_b32_e32 v66, v40
	s_waitcnt lgkmcnt(3)
	v_mov_b32_e32 v67, v116
	v_mov_b32_e32 v120, v44
	s_waitcnt lgkmcnt(2)
	v_mov_b32_e32 v121, v124
	v_pk_add_f32 v[66:67], v[66:67], v[120:121]
	v_mov_b32_e32 v120, v108
	s_waitcnt vmcnt(15)
	v_lshlrev_b32_e32 v108, 16, v214
	v_mul_f32_e32 v40, 0xbfb8aa3b, v108
	v_exp_f32_e32 v40, v40
	s_waitcnt lgkmcnt(1)
	v_mov_b32_e32 v121, v128
	v_mov_b32_e32 v138, v112
	s_waitcnt lgkmcnt(0)
	v_mov_b32_e32 v139, v132
	v_add_f32_e32 v40, 1.0, v40
	v_mov_b32_e32 v116, v41
	v_mov_b32_e32 v124, v45
	v_mov_b32_e32 v128, v109
	v_mov_b32_e32 v132, v113
	v_pk_add_f32 v[120:121], v[120:121], v[138:139]
	v_rcp_f32_e32 v112, v40
	v_pk_add_f32 v[40:41], v[116:117], v[124:125]
	v_pk_add_f32 v[44:45], v[128:129], v[132:133]
	v_pk_add_f32 v[66:67], v[66:67], v[120:121]
	v_pk_add_f32 v[40:41], v[40:41], v[44:45]
	v_mov_b32_e32 v45, v66
	v_mov_b32_e32 v44, v40
	v_mov_b32_e32 v66, v41
	v_pk_add_f32 v[40:41], v[44:45], v[66:67]
	s_nop 0
	v_pk_fma_f32 v[40:41], v[40:41], s[2:3], v[64:65] op_sel_hi:[1,0,0]
	s_nop 0
	v_mul_f32_e32 v44, 0x4b800000, v41
	v_cmp_gt_f32_e32 vcc, s0, v41
	s_nop 1
	v_cndmask_b32_e32 v41, v41, v44, vcc
	v_rsq_f32_e32 v41, v41
	v_mul_f32_e32 v44, v112, v108
	v_mul_f32_e32 v45, 0x45800000, v41
	v_cndmask_b32_e32 v41, v41, v45, vcc
	v_mul_f32_e32 v36, v36, v41
	v_mul_f32_e32 v36, v155, v36
	v_mul_f32_e32 v36, v44, v36
	v_mul_f32_e32 v44, 0x4b800000, v40
	v_cmp_gt_f32_e32 vcc, s0, v40
	s_nop 0
	v_cvt_pk_bf16_f32 v36, v36, v36
	v_cndmask_b32_e32 v40, v40, v44, vcc
	s_waitcnt vmcnt(14)
	v_lshlrev_b32_e32 v44, 16, v213
	v_mul_f32_e32 v45, 0xbfb8aa3b, v44
	v_exp_f32_e32 v45, v45
	v_rsq_f32_e32 v40, v40
	global_store_short_d16_hi v[60:61], v36, off
	v_add_f32_e32 v41, 1.0, v45
	v_rcp_f32_e32 v41, v41
	v_mul_f32_e32 v36, 0x45800000, v40
	v_cndmask_b32_e32 v36, v40, v36, vcc
	v_mul_f32_e32 v36, v37, v36
	v_mul_f32_e32 v36, v155, v36
	v_mul_f32_e32 v37, v41, v44
	v_mov_b32_e32 v40, v46
	s_waitcnt vmcnt(14)
	v_lshlrev_b32_e32 v46, 16, v212
	v_mul_f32_e32 v60, v37, v36
	v_mov_b32_e32 v36, v42
	v_mul_f32_e32 v42, 0xbfb8aa3b, v46
	v_exp_f32_e32 v42, v42
	v_mov_b32_e32 v37, v118
	v_mov_b32_e32 v41, v126
	v_pk_add_f32 v[36:37], v[36:37], v[40:41]
	v_mov_b32_e32 v40, v110
	v_mov_b32_e32 v41, v130
	v_mov_b32_e32 v44, v114
	v_mov_b32_e32 v45, v134
	v_pk_add_f32 v[40:41], v[40:41], v[44:45]
	v_mov_b32_e32 v118, v43
	v_pk_add_f32 v[36:37], v[36:37], v[40:41]
	v_add_f32_e32 v40, 1.0, v42
	v_mov_b32_e32 v126, v47
	v_mov_b32_e32 v130, v111
	v_mov_b32_e32 v134, v115
	v_rcp_f32_e32 v44, v40
	v_pk_add_f32 v[40:41], v[118:119], v[126:127]
	v_pk_add_f32 v[42:43], v[130:131], v[134:135]
	s_nop 0
	v_pk_add_f32 v[40:41], v[40:41], v[42:43]
	v_mov_b32_e32 v43, v36
	v_mov_b32_e32 v42, v40
	v_mov_b32_e32 v36, v41
	v_pk_add_f32 v[36:37], v[42:43], v[36:37]
	s_nop 0
	v_pk_fma_f32 v[36:37], v[36:37], s[2:3], v[64:65] op_sel_hi:[1,0,0]
	s_nop 0
	v_mul_f32_e32 v40, 0x4b800000, v37
	v_cmp_gt_f32_e32 vcc, s0, v37
	s_nop 1
	v_cndmask_b32_e32 v37, v37, v40, vcc
	v_rsq_f32_e32 v37, v37
	v_cvt_pk_bf16_f32 v40, v60, v60
	global_store_short_d16_hi v[58:59], v40, off
	v_mul_f32_e32 v40, v44, v46
	v_mul_f32_e32 v41, 0x45800000, v37
	v_cndmask_b32_e32 v37, v37, v41, vcc
	v_mul_f32_e32 v37, v38, v37
	v_mul_f32_e32 v37, v155, v37
	v_mul_f32_e32 v37, v40, v37
	v_mul_f32_e32 v40, 0x4b800000, v36
	v_cmp_gt_f32_e32 vcc, s0, v36
	s_nop 0
	v_cvt_pk_bf16_f32 v37, v37, v37
	v_cndmask_b32_e32 v36, v36, v40, vcc
	s_waitcnt vmcnt(14)
; #define LAS __attribute__((address_space(3)))
; DI unsigned f2bf(float f) { unsigned u = __float_as_uint(f); u += 0x7FFFu + ((u >> 16) & 1u); return u >> 16; }
; DI float bf2f(unsigned b) { return __uint_as_float(b << 16); }
; DI float siluf_(float x) { return x * __builtin_amdgcn_rcpf(1.0f + __expf(-x)); }
; DI void gdn_unit(const Params& P, bf16_t* proj, const float* gb, int b, int h, LAS unsigned char* lds) {
;     ...
;             for (int tt = 0; tt < 4; ++tt) {
;                 f32x4 pw[8];
; #pragma unroll
;                 for (int w = 0; w < 8; ++w) pw[w] = *(const LAS f32x4*)(part + w * 64 + tt * 16 + fq * 4);
;                 __builtin_amdgcn_sched_barrier(0);
;                 const f32x4 ss = ((pw[0] + pw[1]) + (pw[2] + pw[3])) + ((pw[4] + pw[5]) + (pw[6] + pw[7]));
; #pragma unroll
;                 for (int jj = 0; jj < 4; ++jj) {
;                     const float rstd = rsqrtf(ss[jj] * (1.0f / 128.0f) + 1e-6f);
;                     const float z = bf2f(zr[tt][jj]);
;                     const float o = oacc[tt][jj] * rstd * ng * siluf_(z);
;                     obase[(tt * 16 + jj) * PJ1 + ooffl] = (bf16_t)f2bf(o);
;                 }
;             }
	v_lshlrev_b32_e32 v40, 16, v211
	v_mul_f32_e32 v41, 0xbfb8aa3b, v40
	v_exp_f32_e32 v41, v41
	v_rsq_f32_e32 v36, v36
	global_store_short_d16_hi v[54:55], v37, off
	v_add_f32_e32 v38, 1.0, v41
	v_rcp_f32_e32 v38, v38
	v_mul_f32_e32 v37, 0x45800000, v36
	v_cndmask_b32_e32 v36, v36, v37, vcc
	v_mul_f32_e32 v36, v39, v36
	v_mul_f32_e32 v54, v155, v36
	v_mul_f32_e32 v55, v38, v40
	ds_read_b128 v[36:39], v122 offset:192
	ds_read_b128 v[40:43], v122 offset:448
	ds_read_b128 v[44:47], v122 offset:704
	ds_read_b128 v[58:61], v122 offset:960
	ds_read_b128 v[108:111], v122 offset:1216
	ds_read_b128 v[112:115], v122 offset:1472
	ds_read_b128 v[116:119], v122 offset:1728
	ds_read_b128 v[120:123], v122 offset:1984
	v_mul_f32_e32 v54, v55, v54
	s_nop 0
	v_cvt_pk_bf16_f32 v54, v54, v54
	global_store_short_d16_hi v[52:53], v54, off
	s_waitcnt lgkmcnt(7)
	v_mov_b32_e32 v52, v36
	s_waitcnt lgkmcnt(3)
	v_mov_b32_e32 v53, v108
	v_mov_b32_e32 v54, v40
	s_waitcnt lgkmcnt(2)
	v_mov_b32_e32 v55, v112
	v_pk_add_f32 v[52:53], v[52:53], v[54:55]
	v_mov_b32_e32 v54, v44
	s_waitcnt vmcnt(15)
	v_lshlrev_b32_e32 v44, 16, v210
	v_mul_f32_e32 v36, 0xbfb8aa3b, v44
	v_exp_f32_e32 v36, v36
	s_waitcnt lgkmcnt(1)
	v_mov_b32_e32 v55, v116
	v_mov_b32_e32 v66, v58
	s_waitcnt lgkmcnt(0)
	v_mov_b32_e32 v67, v120
	v_pk_add_f32 v[54:55], v[54:55], v[66:67]
	v_add_f32_e32 v36, 1.0, v36
	v_mov_b32_e32 v108, v37
	v_mov_b32_e32 v112, v41
	v_mov_b32_e32 v116, v45
	v_mov_b32_e32 v120, v59
	v_pk_add_f32 v[52:53], v[52:53], v[54:55]
	v_rcp_f32_e32 v54, v36
	v_pk_add_f32 v[36:37], v[108:109], v[112:113]
	v_pk_add_f32 v[40:41], v[116:117], v[120:121]
	s_add_u32 s14, s14, 0x80000
	v_pk_add_f32 v[36:37], v[36:37], v[40:41]
	v_mov_b32_e32 v41, v52
	v_mov_b32_e32 v40, v36
	v_mov_b32_e32 v52, v37
	v_pk_add_f32 v[36:37], v[40:41], v[52:53]
	s_addc_u32 s15, s15, 0
	v_pk_fma_f32 v[36:37], v[36:37], s[2:3], v[64:65] op_sel_hi:[1,0,0]
	s_add_i32 s42, s42, 64
	v_mul_f32_e32 v40, 0x4b800000, v37
	v_cmp_gt_f32_e32 vcc, s0, v37
	s_mov_b32 s18, 0x800000
	s_cmp_lg_u32 s14, 0x1000000
	v_cndmask_b32_e32 v37, v37, v40, vcc
	v_rsq_f32_e32 v37, v37
	v_mul_f32_e32 v40, v54, v44
	v_mul_f32_e32 v41, 0x45800000, v37
	v_cndmask_b32_e32 v37, v37, v41, vcc
	v_mul_f32_e32 v32, v32, v37
	v_mul_f32_e32 v32, v155, v32
	v_mul_f32_e32 v32, v40, v32
	v_mul_f32_e32 v40, 0x4b800000, v36
	v_cmp_gt_f32_e32 vcc, s0, v36
	s_nop 0
	v_cvt_pk_bf16_f32 v32, v32, v32
	v_cndmask_b32_e32 v36, v36, v40, vcc
	s_waitcnt vmcnt(14)
	v_lshlrev_b32_e32 v40, 16, v209
	v_mul_f32_e32 v41, 0xbfb8aa3b, v40
	v_exp_f32_e32 v41, v41
	v_rsq_f32_e32 v36, v36
	global_store_short_d16_hi v[62:63], v32, off
	v_add_f32_e32 v37, 1.0, v41
	v_rcp_f32_e32 v37, v37
	v_mul_f32_e32 v32, 0x45800000, v36
	v_cndmask_b32_e32 v32, v36, v32, vcc
	v_mul_f32_e32 v32, v33, v32
	v_mul_f32_e32 v32, v155, v32
	v_mul_f32_e32 v33, v37, v40
	v_mov_b32_e32 v36, v42
	s_waitcnt vmcnt(14)
	v_lshlrev_b32_e32 v42, 16, v208
	v_mul_f32_e32 v44, v33, v32
	v_mov_b32_e32 v32, v38
	v_mul_f32_e32 v38, 0xbfb8aa3b, v42
	v_exp_f32_e32 v38, v38
	v_mov_b32_e32 v33, v110
	v_mov_b32_e32 v37, v114
	v_pk_add_f32 v[32:33], v[32:33], v[36:37]
	v_mov_b32_e32 v36, v46
	v_mov_b32_e32 v37, v118
	v_mov_b32_e32 v40, v60
	v_mov_b32_e32 v41, v122
	v_pk_add_f32 v[36:37], v[36:37], v[40:41]
	v_mov_b32_e32 v110, v39
	v_pk_add_f32 v[32:33], v[32:33], v[36:37]
	v_add_f32_e32 v36, 1.0, v38
	v_mov_b32_e32 v114, v43
	v_mov_b32_e32 v118, v47
	v_mov_b32_e32 v122, v61
	v_rcp_f32_e32 v40, v36
	v_pk_add_f32 v[36:37], v[110:111], v[114:115]
	v_pk_add_f32 v[38:39], v[118:119], v[122:123]
	v_bfe_u32 v45, v44, 16, 1
	v_pk_add_f32 v[36:37], v[36:37], v[38:39]
	v_mov_b32_e32 v39, v32
	v_mov_b32_e32 v38, v36
	v_mov_b32_e32 v32, v37
	v_pk_add_f32 v[32:33], v[38:39], v[32:33]
	s_nop 0
	v_pk_fma_f32 v[32:33], v[32:33], s[2:3], v[64:65] op_sel_hi:[1,0,0]
	s_nop 0
	v_mul_f32_e32 v36, 0x4b800000, v33
	v_cmp_gt_f32_e32 vcc, s0, v33
	s_nop 1
	v_cndmask_b32_e32 v33, v33, v36, vcc
	v_rsq_f32_e32 v33, v33
	v_add3_u32 v36, v44, v45, s68
	global_store_short_d16_hi v[56:57], v36, off
	v_mul_f32_e32 v36, v40, v42
	v_mul_f32_e32 v37, 0x45800000, v33
	v_cndmask_b32_e32 v33, v33, v37, vcc
	v_mul_f32_e32 v33, v34, v33
	v_mul_f32_e32 v33, v155, v33
	v_mul_f32_e32 v33, v36, v33
	v_mul_f32_e32 v36, 0x4b800000, v32
	v_cmp_gt_f32_e32 vcc, s0, v32
	s_nop 0
	v_cvt_pk_bf16_f32 v33, v33, v33
	v_cndmask_b32_e32 v32, v32, v36, vcc
	s_waitcnt vmcnt(14)
	v_lshlrev_b32_e32 v36, 16, v206
	v_mul_f32_e32 v37, 0xbfb8aa3b, v36
	v_exp_f32_e32 v37, v37
	v_rsq_f32_e32 v32, v32
	global_store_short_d16_hi v[50:51], v33, off
	v_add_f32_e32 v34, 1.0, v37
	v_rcp_f32_e32 v34, v34
	v_mul_f32_e32 v33, 0x45800000, v32
	v_cndmask_b32_e32 v32, v32, v33, vcc
	v_mul_f32_e32 v32, v35, v32
	v_mul_f32_e32 v32, v155, v32
	v_mul_f32_e32 v33, v34, v36
	v_mul_f32_e32 v32, v33, v32
	v_bfe_u32 v33, v32, 16, 1
	v_add3_u32 v32, v32, v33, s68
	global_store_short_d16_hi v[48:49], v32, off
	s_cbranch_scc0 .LBB0_336

; DI float bflo(unsigned w) { return __uint_as_float(w << 16); }
; DI float bfhi(unsigned w) { return __uint_as_float(w & 0xffff0000u); }
; DI float siluf_(float x) { return x * __builtin_amdgcn_rcpf(1.0f + __expf(-x)); }
; DI float wave_sum(float v) { v = row16_sum(v); return (rdlane(v, 0) + rdlane(v, 16)) + (rdlane(v, 32) + rdlane(v, 48)); }
; DI void gdn_unit(const Params& P, bf16_t* proj, const float* gb, int b, int h, LAS unsigned char* lds) {
;     ...
;         for (int w = 0; w < 3; ++w) {
;             const f32x2 (&cw)[4] = cwr[w];
;             const unsigned (&raw)[11] = rawq[w];
;             float o0[8], o1[8];
; #pragma unroll
;             for (int i = 0; i < 8; ++i) {
;                 float a0 = 0.f, a1 = 0.f;
; #pragma unroll
;                 for (int j = 0; j < 4; ++j) { a0 += cw[j][0] * bflo(raw[i + j]); a1 += cw[j][1] * bfhi(raw[i + j]); }
;                 a0 = siluf_(a0); a1 = siluf_(a1);
;                 if (w < 2) {
;                     const float ss = wave_sum(a0 * a0 + a1 * a1);
;                     const float rs = rsqrtf(ss + 1e-6f) * (w == 0 ? 0.08838834764831845f : 1.0f);
;                     a0 *= rs; a1 *= rs;
;                 }
;                 o0[i] = a0; o1[i] = a1;
;             }
.LBB0_423:
	v_and_b32_e32 v63, 0xffff0000, v136
	v_lshlrev_b32_e32 v62, 16, v136
	v_and_b32_e32 v57, 0xffff0000, v157
	v_lshlrev_b32_e32 v56, 16, v157
	v_pk_fma_f32 v[62:63], v[68:69], v[62:63], 0 op_sel_hi:[1,1,0]
	v_and_b32_e32 v59, 0xffff0000, v156
	v_lshlrev_b32_e32 v58, 16, v156
	v_pk_fma_f32 v[110:111], v[68:69], v[56:57], 0 op_sel_hi:[1,1,0]
	v_pk_fma_f32 v[56:57], v[70:71], v[56:57], v[62:63]
	v_and_b32_e32 v61, 0xffff0000, v160
	v_lshlrev_b32_e32 v60, 16, v160
	v_pk_fma_f32 v[56:57], v[72:73], v[58:59], v[56:57]
	v_pk_fma_f32 v[64:65], v[68:69], v[58:59], 0 op_sel_hi:[1,1,0]
	v_pk_fma_f32 v[56:57], v[74:75], v[60:61], v[56:57]
	v_pk_fma_f32 v[110:111], v[70:71], v[58:59], v[110:111]
	v_mul_f32_e32 v58, 0xbfb8aa3b, v57
	v_exp_f32_e32 v58, v58
	s_movk_i32 s0, 0x11c
	v_mul_lo_u32 v55, v67, s0
	s_mov_b32 s26, 0x800000
	v_add_f32_e32 v58, 1.0, v58
	v_rcp_f32_e32 v59, v58
	v_mul_f32_e32 v58, 0xbfb8aa3b, v56
	v_exp_f32_e32 v58, v58
	v_and_b32_e32 v53, 0xffff0000, v159
	v_lshlrev_b32_e32 v52, 16, v159
	v_pk_fma_f32 v[50:51], v[68:69], v[60:61], 0 op_sel_hi:[1,1,0]
	v_add_f32_e32 v58, 1.0, v58
	v_rcp_f32_e32 v58, v58
	v_pk_fma_f32 v[64:65], v[70:71], v[60:61], v[64:65]
	v_and_b32_e32 v49, 0xffff0000, v158
	v_lshlrev_b32_e32 v48, 16, v158
	v_pk_mul_f32 v[58:59], v[56:57], v[58:59]
	v_pk_fma_f32 v[46:47], v[68:69], v[52:53], 0 op_sel_hi:[1,1,0]
	v_pk_mul_f32 v[56:57], v[58:59], v[58:59]
	v_pk_fma_f32 v[50:51], v[70:71], v[52:53], v[50:51]
	v_add_f32_e32 v56, v57, v56
	v_and_b32_e32 v45, 0xffff0000, v176
	v_lshlrev_b32_e32 v44, 16, v176
	v_add_f32_dpp v56, v56, v56 quad_perm:[1,0,3,2] row_mask:0xf bank_mask:0xf bound_ctrl:1
	v_pk_fma_f32 v[42:43], v[68:69], v[48:49], 0 op_sel_hi:[1,1,0]
	v_pk_fma_f32 v[46:47], v[70:71], v[48:49], v[46:47]
	v_add_f32_dpp v56, v56, v56 quad_perm:[2,3,0,1] row_mask:0xf bank_mask:0xf bound_ctrl:1
	v_and_b32_e32 v33, 0xffff0000, v161
	v_lshlrev_b32_e32 v32, 16, v161
	v_add_f32_dpp v56, v56, v56 row_half_mirror row_mask:0xf bank_mask:0xf bound_ctrl:1
	v_pk_fma_f32 v[40:41], v[68:69], v[44:45], 0 op_sel_hi:[1,1,0]
	v_pk_fma_f32 v[42:43], v[70:71], v[44:45], v[42:43]
	v_add_f32_dpp v56, v56, v56 row_mirror row_mask:0xf bank_mask:0xf bound_ctrl:1
	v_and_b32_e32 v35, 0xffff0000, v179
	v_readlane_b32 s2, v56, 16
	v_readlane_b32 s3, v56, 48
	v_readlane_b32 s0, v56, 0
	v_readlane_b32 s1, v56, 32
	v_mov_b32_e32 v56, s2
	v_mov_b32_e32 v57, s3
	v_pk_add_f32 v[56:57], s[0:1], v[56:57]
	v_lshlrev_b32_e32 v34, 16, v179
	v_add_f32_e32 v56, v56, v57
	v_add_f32_e32 v56, 0x358637bd, v56
	v_cmp_gt_f32_e32 vcc, s26, v56
	v_mul_f32_e32 v57, 0x4b800000, v56
	v_pk_fma_f32 v[42:43], v[72:73], v[32:33], v[42:43]
	v_cndmask_b32_e32 v56, v56, v57, vcc
	v_rsq_f32_e32 v56, v56
	v_pk_fma_f32 v[42:43], v[74:75], v[34:35], v[42:43]
	v_pk_fma_f32 v[40:41], v[70:71], v[32:33], v[40:41]
	v_and_b32_e32 v37, 0xffff0000, v178
	v_mul_f32_e32 v57, 0x45800000, v56
	v_cndmask_b32_e32 v56, v56, v57, vcc
	v_mul_f32_e32 v56, 0x3db504f3, v56
	v_mul_f32_e32 v57, v58, v56
	v_mul_f32_e32 v56, v59, v56
	v_pk_fma_f32 v[58:59], v[72:73], v[60:61], v[110:111]
	v_lshlrev_b32_e32 v36, 16, v178
	v_pk_fma_f32 v[58:59], v[74:75], v[52:53], v[58:59]
	v_pk_fma_f32 v[52:53], v[72:73], v[52:53], v[64:65]
	v_mul_f32_e32 v60, 0xbfb8aa3b, v59
	v_exp_f32_e32 v60, v60
	v_pk_fma_f32 v[52:53], v[74:75], v[48:49], v[52:53]
	v_pk_fma_f32 v[48:49], v[72:73], v[48:49], v[50:51]
	v_pk_fma_f32 v[40:41], v[72:73], v[34:35], v[40:41]
	v_add_f32_e32 v60, 1.0, v60
	v_rcp_f32_e32 v61, v60
	v_mul_f32_e32 v60, 0xbfb8aa3b, v58
	v_exp_f32_e32 v60, v60
	v_pk_fma_f32 v[48:49], v[74:75], v[44:45], v[48:49]
	v_pk_fma_f32 v[44:45], v[72:73], v[44:45], v[46:47]
	v_mul_f32_e32 v50, 0xbfb8aa3b, v49
	v_add_f32_e32 v60, 1.0, v60
	v_rcp_f32_e32 v60, v60
	v_exp_f32_e32 v50, v50
	v_pk_fma_f32 v[44:45], v[74:75], v[32:33], v[44:45]
	v_pk_fma_f32 v[40:41], v[74:75], v[36:37], v[40:41]
	v_pk_mul_f32 v[60:61], v[58:59], v[60:61]
	v_add_f32_e32 v50, 1.0, v50
	v_pk_mul_f32 v[58:59], v[60:61], v[60:61]
	v_rcp_f32_e32 v51, v50
	v_add_f32_e32 v58, v59, v58
	v_mul_f32_e32 v50, 0xbfb8aa3b, v48
	v_exp_f32_e32 v50, v50
	v_add_f32_dpp v58, v58, v58 quad_perm:[1,0,3,2] row_mask:0xf bank_mask:0xf bound_ctrl:1
	v_mul_f32_e32 v46, 0xbfb8aa3b, v45
	v_exp_f32_e32 v46, v46
	v_add_f32_dpp v58, v58, v58 quad_perm:[2,3,0,1] row_mask:0xf bank_mask:0xf bound_ctrl:1
	v_add_f32_e32 v50, 1.0, v50
	v_rcp_f32_e32 v50, v50
	v_add_f32_dpp v58, v58, v58 row_half_mirror row_mask:0xf bank_mask:0xf bound_ctrl:1
	v_add_f32_e32 v46, 1.0, v46
	v_rcp_f32_e32 v47, v46
	v_add_f32_dpp v58, v58, v58 row_mirror row_mask:0xf bank_mask:0xf bound_ctrl:1
	v_mul_f32_e32 v46, 0xbfb8aa3b, v44
	v_readlane_b32 s2, v58, 16
	v_readlane_b32 s3, v58, 48
	v_readlane_b32 s0, v58, 0
	v_readlane_b32 s1, v58, 32
	v_mov_b32_e32 v58, s2
	v_mov_b32_e32 v59, s3
	v_pk_add_f32 v[58:59], s[0:1], v[58:59]
	v_exp_f32_e32 v46, v46
	v_add_f32_e32 v58, v58, v59
	v_add_f32_e32 v58, 0x358637bd, v58
	v_cmp_gt_f32_e32 vcc, s26, v58
	v_mul_f32_e32 v59, 0x4b800000, v58
	v_pk_mul_f32 v[48:49], v[48:49], v[50:51]
	v_cndmask_b32_e32 v58, v58, v59, vcc
	v_rsq_f32_e32 v58, v58
	v_pk_mul_f32 v[50:51], v[48:49], v[48:49]
	v_add_f32_e32 v46, 1.0, v46
	v_add_f32_e32 v50, v51, v50
	v_mul_f32_e32 v59, 0x45800000, v58
	v_cndmask_b32_e32 v58, v58, v59, vcc
	v_mul_f32_e32 v58, 0x3db504f3, v58
	v_mul_f32_e32 v59, v60, v58
	v_mul_f32_e32 v60, 0xbfb8aa3b, v53
	v_exp_f32_e32 v60, v60
	v_mul_f32_e32 v58, v61, v58
	v_add_f32_dpp v50, v50, v50 quad_perm:[1,0,3,2] row_mask:0xf bank_mask:0xf bound_ctrl:1
	v_rcp_f32_e32 v46, v46
	v_add_f32_e32 v60, 1.0, v60
	v_rcp_f32_e32 v61, v60
	v_mul_f32_e32 v60, 0xbfb8aa3b, v52
; DI float bflo(unsigned w) { return __uint_as_float(w << 16); }
; DI float bfhi(unsigned w) { return __uint_as_float(w & 0xffff0000u); }
; DI float siluf_(float x) { return x * __builtin_amdgcn_rcpf(1.0f + __expf(-x)); }
; DI float wave_sum(float v) { v = row16_sum(v); return (rdlane(v, 0) + rdlane(v, 16)) + (rdlane(v, 32) + rdlane(v, 48)); }
; DI void gdn_unit(const Params& P, bf16_t* proj, const float* gb, int b, int h, LAS unsigned char* lds) {
;     ...
;             float o0[8], o1[8];
; #pragma unroll
;             for (int i = 0; i < 8; ++i) {
;                 float a0 = 0.f, a1 = 0.f;
; #pragma unroll
;                 for (int j = 0; j < 4; ++j) { a0 += cw[j][0] * bflo(raw[i + j]); a1 += cw[j][1] * bfhi(raw[i + j]); }
;                 a0 = siluf_(a0); a1 = siluf_(a1);
;                 if (w < 2) {
;                     const float ss = wave_sum(a0 * a0 + a1 * a1);
;                     const float rs = rsqrtf(ss + 1e-6f) * (w == 0 ? 0.08838834764831845f : 1.0f);
;                     a0 *= rs; a1 *= rs;
;                 }
;                 o0[i] = a0; o1[i] = a1;
;             }
	v_exp_f32_e32 v60, v60
	v_add_f32_dpp v50, v50, v50 quad_perm:[2,3,0,1] row_mask:0xf bank_mask:0xf bound_ctrl:1
	v_pk_mul_f32 v[44:45], v[44:45], v[46:47]
	v_pk_fma_f32 v[32:33], v[68:69], v[32:33], 0 op_sel_hi:[1,1,0]
	v_add_f32_e32 v60, 1.0, v60
	v_rcp_f32_e32 v60, v60
	v_add_f32_dpp v50, v50, v50 row_half_mirror row_mask:0xf bank_mask:0xf bound_ctrl:1
	v_pk_mul_f32 v[46:47], v[44:45], v[44:45]
	v_pk_fma_f32 v[32:33], v[70:71], v[34:35], v[32:33]
	v_pk_mul_f32 v[60:61], v[52:53], v[60:61]
	v_add_f32_dpp v50, v50, v50 row_mirror row_mask:0xf bank_mask:0xf bound_ctrl:1
	v_pk_mul_f32 v[52:53], v[60:61], v[60:61]
	v_add_f32_e32 v46, v47, v46
	v_add_f32_e32 v52, v53, v52
	v_and_b32_e32 v39, 0xffff0000, v182
	v_add_f32_dpp v46, v46, v46 quad_perm:[1,0,3,2] row_mask:0xf bank_mask:0xf bound_ctrl:1
	v_add_f32_dpp v52, v52, v52 quad_perm:[1,0,3,2] row_mask:0xf bank_mask:0xf bound_ctrl:1
	v_lshlrev_b32_e32 v38, 16, v182
	v_add_f32_dpp v46, v46, v46 quad_perm:[2,3,0,1] row_mask:0xf bank_mask:0xf bound_ctrl:1
	v_add_f32_dpp v52, v52, v52 quad_perm:[2,3,0,1] row_mask:0xf bank_mask:0xf bound_ctrl:1
	v_pk_fma_f32 v[32:33], v[72:73], v[36:37], v[32:33]
	v_add_f32_dpp v46, v46, v46 row_half_mirror row_mask:0xf bank_mask:0xf bound_ctrl:1
	v_add_f32_dpp v52, v52, v52 row_half_mirror row_mask:0xf bank_mask:0xf bound_ctrl:1
	v_pk_fma_f32 v[32:33], v[74:75], v[38:39], v[32:33]
	v_add_f32_dpp v46, v46, v46 row_mirror row_mask:0xf bank_mask:0xf bound_ctrl:1
	v_add_f32_dpp v52, v52, v52 row_mirror row_mask:0xf bank_mask:0xf bound_ctrl:1
	v_mul_f32_e32 v34, 0xbfb8aa3b, v33
	v_readlane_b32 s2, v52, 16
	v_readlane_b32 s3, v52, 48
	v_readlane_b32 s0, v52, 0
	v_readlane_b32 s1, v52, 32
	v_mov_b32_e32 v52, s2
	v_mov_b32_e32 v53, s3
	v_pk_add_f32 v[52:53], s[0:1], v[52:53]
	v_readlane_b32 s2, v50, 16
	v_add_f32_e32 v52, v52, v53
	v_add_f32_e32 v52, 0x358637bd, v52
	v_cmp_gt_f32_e32 vcc, s26, v52
	v_mul_f32_e32 v53, 0x4b800000, v52
	v_readlane_b32 s3, v50, 48
	v_cndmask_b32_e32 v52, v52, v53, vcc
	v_rsq_f32_e32 v52, v52
	v_readlane_b32 s0, v50, 0
	v_readlane_b32 s1, v50, 32
	v_mov_b32_e32 v50, s2
	v_mov_b32_e32 v51, s3
	v_pk_add_f32 v[50:51], s[0:1], v[50:51]
	v_mul_f32_e32 v53, 0x45800000, v52
	v_add_f32_e32 v50, v50, v51
	v_add_f32_e32 v50, 0x358637bd, v50
	v_cndmask_b32_e32 v52, v52, v53, vcc
	v_cmp_gt_f32_e32 vcc, s26, v50
	v_mul_f32_e32 v51, 0x4b800000, v50
	v_readlane_b32 s2, v46, 16
	v_cndmask_b32_e32 v50, v50, v51, vcc
	v_rsq_f32_e32 v50, v50
	v_readlane_b32 s3, v46, 48
	v_readlane_b32 s0, v46, 0
	v_readlane_b32 s1, v46, 32
	v_mov_b32_e32 v46, s2
	v_mov_b32_e32 v47, s3
	v_pk_add_f32 v[46:47], s[0:1], v[46:47]
	v_mul_f32_e32 v51, 0x45800000, v50
	v_add_f32_e32 v46, v46, v47
	v_add_f32_e32 v46, 0x358637bd, v46
	v_cndmask_b32_e32 v50, v50, v51, vcc
	v_cmp_gt_f32_e32 vcc, s26, v46
	v_mul_f32_e32 v47, 0x4b800000, v46
	v_exp_f32_e32 v34, v34
	v_cndmask_b32_e32 v46, v46, v47, vcc
	v_rsq_f32_e32 v46, v46
	v_bfe_u32 v36, v58, 16, 1
	v_add_f32_e32 v34, 1.0, v34
	v_rcp_f32_e32 v35, v34
	v_mul_f32_e32 v47, 0x45800000, v46
	v_cndmask_b32_e32 v46, v46, v47, vcc
	v_mul_f32_e32 v46, 0x3db504f3, v46
	v_mul_f32_e32 v47, v44, v46
	v_mul_f32_e32 v44, 0xbfb8aa3b, v43
	v_exp_f32_e32 v44, v44
	v_mul_f32_e32 v46, v45, v46
	v_mul_f32_e32 v34, 0xbfb8aa3b, v32
	v_exp_f32_e32 v34, v34
	v_add_f32_e32 v44, 1.0, v44
	v_rcp_f32_e32 v45, v44
	v_mul_f32_e32 v44, 0xbfb8aa3b, v42
	v_exp_f32_e32 v44, v44
	v_add_f32_e32 v34, 1.0, v34
	v_rcp_f32_e32 v34, v34
	v_mul_f32_e32 v52, 0x3db504f3, v52
	v_add_f32_e32 v44, 1.0, v44
	v_rcp_f32_e32 v44, v44
	v_pk_mul_f32 v[32:33], v[32:33], v[34:35]
	v_add3_u32 v36, v58, v36, s68
	v_pk_mul_f32 v[34:35], v[32:33], v[32:33]
	v_pk_mul_f32 v[42:43], v[42:43], v[44:45]
	v_add_f32_e32 v34, v35, v34
	v_pk_mul_f32 v[44:45], v[42:43], v[42:43]
	v_mul_f32_e32 v53, v60, v52
	v_add_f32_e32 v44, v45, v44
	v_add_f32_dpp v34, v34, v34 quad_perm:[1,0,3,2] row_mask:0xf bank_mask:0xf bound_ctrl:1
	v_mul_f32_e32 v52, v61, v52
	v_add_f32_dpp v44, v44, v44 quad_perm:[1,0,3,2] row_mask:0xf bank_mask:0xf bound_ctrl:1
	v_add_f32_dpp v34, v34, v34 quad_perm:[2,3,0,1] row_mask:0xf bank_mask:0xf bound_ctrl:1
	v_mul_f32_e32 v50, 0x3db504f3, v50
	v_add_f32_dpp v44, v44, v44 quad_perm:[2,3,0,1] row_mask:0xf bank_mask:0xf bound_ctrl:1
	v_add_f32_dpp v34, v34, v34 row_half_mirror row_mask:0xf bank_mask:0xf bound_ctrl:1
	v_mul_f32_e32 v48, v48, v50
	v_add_f32_dpp v44, v44, v44 row_half_mirror row_mask:0xf bank_mask:0xf bound_ctrl:1
	v_add_f32_dpp v34, v34, v34 row_mirror row_mask:0xf bank_mask:0xf bound_ctrl:1
	v_mul_f32_e32 v49, v49, v50
	v_add_f32_dpp v44, v44, v44 row_mirror row_mask:0xf bank_mask:0xf bound_ctrl:1
	v_and_b32_e32 v50, 0xffff0000, v181
	v_readlane_b32 s2, v44, 16
	v_readlane_b32 s3, v44, 48
	v_readlane_b32 s0, v44, 0
	v_readlane_b32 s1, v44, 32
	v_mov_b32_e32 v44, s2
	v_mov_b32_e32 v45, s3
	v_pk_add_f32 v[44:45], s[0:1], v[44:45]
	v_lshlrev_b32_e32 v60, 16, v180
	v_add_f32_e32 v44, v44, v45
	v_add_f32_e32 v44, 0x358637bd, v44
	v_cmp_gt_f32_e32 vcc, s26, v44
	v_mul_f32_e32 v45, 0x4b800000, v44
	v_lshlrev_b32_e32 v38, 16, v184
	v_cndmask_b32_e32 v44, v44, v45, vcc
	v_rsq_f32_e32 v44, v44
	v_lshlrev_b32_e32 v62, 16, v177
	v_mov_b32_e32 v63, v60
	v_lshlrev_b32_e32 v58, 16, v181
	v_mul_f32_e32 v45, 0x45800000, v44
	v_cndmask_b32_e32 v44, v44, v45, vcc
	v_mul_f32_e32 v44, 0x3db504f3, v44
	v_mul_f32_e32 v45, v42, v44
	v_mul_f32_e32 v42, 0xbfb8aa3b, v41
	v_exp_f32_e32 v42, v42
	v_mul_f32_e32 v44, v43, v44
	v_pk_fma_f32 v[62:63], v[98:99], v[62:63], 0 op_sel_hi:[1,1,0]
	v_lshlrev_b32_e32 v61, 16, v183
	v_add_f32_e32 v42, 1.0, v42
	v_rcp_f32_e32 v43, v42
	v_mul_f32_e32 v42, 0xbfb8aa3b, v40
; #define LAS __attribute__((address_space(3)))
; DI unsigned pk2(float lo, float hi) { return f2bf(lo) | (f2bf(hi) << 16); }
; DI float bflo(unsigned w) { return __uint_as_float(w << 16); }
; DI float bfhi(unsigned w) { return __uint_as_float(w & 0xffff0000u); }
; DI float siluf_(float x) { return x * __builtin_amdgcn_rcpf(1.0f + __expf(-x)); }
; DI float wave_sum(float v) { v = row16_sum(v); return (rdlane(v, 0) + rdlane(v, 16)) + (rdlane(v, 32) + rdlane(v, 48)); }
; DI void gdn_unit(const Params& P, bf16_t* proj, const float* gb, int b, int h, LAS unsigned char* lds) {
;     ...
; #pragma unroll
;             for (int i = 0; i < 8; ++i) {
;                 float a0 = 0.f, a1 = 0.f;
; #pragma unroll
;                 for (int j = 0; j < 4; ++j) { a0 += cw[j][0] * bflo(raw[i + j]); a1 += cw[j][1] * bfhi(raw[i + j]); }
;                 a0 = siluf_(a0); a1 = siluf_(a1);
;                 if (w < 2) {
;                     const float ss = wave_sum(a0 * a0 + a1 * a1);
;                     const float rs = rsqrtf(ss + 1e-6f) * (w == 0 ? 0.08838834764831845f : 1.0f);
;                     a0 *= rs; a1 *= rs;
;                 }
;                 o0[i] = a0; o1[i] = a1;
;             }
;             if (w < 2) {
;                 const int off = (w == 0) ? Q_OFF : K_OFF;
; #pragma unroll
;                 for (int i = 0; i < 8; ++i) *(LAS unsigned*)(lds + off + (wave * 8 + i) * 272 + lane * 4) = pk2(o0[i], o1[i]);
;             }
	v_exp_f32_e32 v42, v42
	v_lshlrev_b32_e32 v39, 16, v186
	s_mov_b32 s76, 0x358637bd
	s_mov_b32 s78, 0x45800000
	v_add_f32_e32 v42, 1.0, v42
	v_rcp_f32_e32 v42, v42
	v_lshlrev_b32_e32 v37, 16, v190
	s_mov_b32 s72, 0x358637bd
	s_cmp_eq_u32 s14, 0xf80000
	v_pk_mul_f32 v[40:41], v[40:41], v[42:43]
	s_nop 0
	v_pk_mul_f32 v[42:43], v[40:41], v[40:41]
	s_nop 0
	v_add_f32_e32 v42, v43, v42
	s_nop 1
	v_add_f32_dpp v42, v42, v42 quad_perm:[1,0,3,2] row_mask:0xf bank_mask:0xf bound_ctrl:1
	s_nop 1
	v_add_f32_dpp v42, v42, v42 quad_perm:[2,3,0,1] row_mask:0xf bank_mask:0xf bound_ctrl:1
	s_nop 1
	v_add_f32_dpp v42, v42, v42 row_half_mirror row_mask:0xf bank_mask:0xf bound_ctrl:1
	s_nop 1
	v_add_f32_dpp v42, v42, v42 row_mirror row_mask:0xf bank_mask:0xf bound_ctrl:1
	s_nop 0
	v_readlane_b32 s2, v42, 16
	v_readlane_b32 s3, v42, 48
	v_readlane_b32 s0, v42, 0
	v_readlane_b32 s1, v42, 32
	v_mov_b32_e32 v42, s2
	v_mov_b32_e32 v43, s3
	v_pk_add_f32 v[42:43], s[0:1], v[42:43]
	v_readlane_b32 s2, v34, 16
	v_add_f32_e32 v42, v42, v43
	v_add_f32_e32 v42, 0x358637bd, v42
	v_cmp_gt_f32_e32 vcc, s26, v42
	v_mul_f32_e32 v43, 0x4b800000, v42
	v_readlane_b32 s3, v34, 48
	v_cndmask_b32_e32 v42, v42, v43, vcc
	v_rsq_f32_e32 v42, v42
	v_readlane_b32 s0, v34, 0
	v_readlane_b32 s1, v34, 32
	v_mov_b32_e32 v34, s2
	v_mov_b32_e32 v35, s3
	v_pk_add_f32 v[34:35], s[0:1], v[34:35]
	v_mul_f32_e32 v43, 0x45800000, v42
	v_add_f32_e32 v34, v34, v35
	v_add_f32_e32 v34, 0x358637bd, v34
	v_cndmask_b32_e32 v42, v42, v43, vcc
	v_cmp_gt_f32_e32 vcc, s26, v34
	v_mul_f32_e32 v35, 0x4b800000, v34
	v_mul_f32_e32 v42, 0x3db504f3, v42
	v_cndmask_b32_e32 v34, v34, v35, vcc
	v_rsq_f32_e32 v34, v34
	v_mul_f32_e32 v40, v40, v42
	v_mul_f32_e32 v41, v41, v42
	v_and_b32_e32 v42, 0xffff0000, v184
	v_mul_f32_e32 v35, 0x45800000, v34
	v_cndmask_b32_e32 v34, v34, v35, vcc
	v_mul_f32_e32 v34, 0x3db504f3, v34
	v_mul_f32_e32 v32, v32, v34
	v_mul_f32_e32 v33, v33, v34
	s_nop 0
	v_cvt_pk_bf16_f32 v34, v57, v56
	v_cvt_pk_bf16_f32 v35, v59, v59
	v_lshrrev_b32_e32 v35, 16, v35
	v_add_u32_e32 v56, s92, v54
	v_and_or_b32 v35, v36, s39, v35
	ds_write2_b32 v56, v34, v35 offset1:68
	v_cvt_pk_bf16_f32 v34, v53, v52
	v_cvt_pk_bf16_f32 v35, v48, v49
	ds_write2_b32 v56, v34, v35 offset0:136 offset1:204
	v_cvt_pk_bf16_f32 v34, v47, v46
	v_cvt_pk_bf16_f32 v35, v45, v44
	v_add_u32_e32 v36, 0x400, v56
	ds_write2_b32 v36, v34, v35 offset0:16 offset1:84
	v_cvt_pk_bf16_f32 v34, v40, v41
	v_cvt_pk_bf16_f32 v32, v32, v33
	ds_write2_b32 v36, v34, v32 offset0:152 offset1:220
	v_and_b32_e32 v32, 0xffff0000, v177
	v_and_b32_e32 v48, 0xffff0000, v183
	v_mov_b32_e32 v33, v42
	v_and_b32_e32 v49, 0xffff0000, v186
	v_pk_fma_f32 v[32:33], v[76:77], v[32:33], 0 op_sel_hi:[1,1,0]
	v_mov_b32_e32 v51, v48
	v_and_b32_e32 v52, 0xffff0000, v180
	v_mov_b32_e32 v53, v49
	v_pk_fma_f32 v[32:33], v[92:93], v[50:51], v[32:33]
	v_and_b32_e32 v43, 0xffff0000, v185
	v_pk_fma_f32 v[32:33], v[94:95], v[52:53], v[32:33]
	v_mov_b32_e32 v51, v52
	v_pk_fma_f32 v[32:33], v[96:97], v[42:43], v[32:33]
	v_pk_fma_f32 v[50:51], v[76:77], v[50:51], 0 op_sel_hi:[1,1,0]
	v_mul_f32_e32 v34, 0xbfb8aa3b, v32
	v_exp_f32_e32 v34, v34
	v_mov_b32_e32 v53, v42
	v_mov_b32_e32 v64, v42
	v_mov_b32_e32 v65, v48
	v_add_f32_e32 v34, 1.0, v34
	v_rcp_f32_e32 v110, v34
	v_mul_f32_e32 v34, 0xbfb8aa3b, v33
	v_exp_f32_e32 v34, v34
	v_pk_fma_f32 v[50:51], v[92:93], v[52:53], v[50:51]
	v_mov_b32_e32 v59, v38
	v_pk_fma_f32 v[50:51], v[94:95], v[64:65], v[50:51]
	v_add_f32_e32 v34, 1.0, v34
	v_pk_fma_f32 v[50:51], v[96:97], v[48:49], v[50:51]
	v_rcp_f32_e32 v111, v34
	v_mul_f32_e32 v34, 0xbfb8aa3b, v50
	v_exp_f32_e32 v34, v34
	v_pk_fma_f32 v[62:63], v[78:79], v[58:59], v[62:63]
	v_pk_fma_f32 v[58:59], v[98:99], v[58:59], 0 op_sel_hi:[1,1,0]
	v_pk_fma_f32 v[62:63], v[80:81], v[60:61], v[62:63]
	v_add_f32_e32 v34, 1.0, v34
	v_rcp_f32_e32 v52, v34
	v_mul_f32_e32 v34, 0xbfb8aa3b, v51
	v_exp_f32_e32 v34, v34
	v_pk_fma_f32 v[62:63], v[82:83], v[38:39], v[62:63]
	v_pk_fma_f32 v[58:59], v[78:79], v[60:61], v[58:59]
	v_mul_f32_e32 v57, 0xbfb8aa3b, v62
	v_exp_f32_e32 v57, v57
	v_add_f32_e32 v34, 1.0, v34
	v_lshlrev_b32_e32 v35, 16, v185
	v_rcp_f32_e32 v53, v34
	v_mov_b32_e32 v34, v61
	v_pk_fma_f32 v[58:59], v[80:81], v[38:39], v[58:59]
	v_add_f32_e32 v57, 1.0, v57
	v_pk_fma_f32 v[58:59], v[82:83], v[34:35], v[58:59]
	v_rcp_f32_e32 v64, v57
	v_mul_f32_e32 v38, 0xbfb8aa3b, v58
	v_mul_f32_e32 v57, 0xbfb8aa3b, v63
	v_exp_f32_e32 v38, v38
	v_exp_f32_e32 v57, v57
	v_pk_mul_f32 v[32:33], v[32:33], v[110:111]
	v_pk_mul_f32 v[52:53], v[50:51], v[52:53]
	v_add_f32_e32 v38, 1.0, v38
	v_add_f32_e32 v57, 1.0, v57
	v_rcp_f32_e32 v60, v38
	v_mul_f32_e32 v38, 0xbfb8aa3b, v59
	v_rcp_f32_e32 v65, v57
	v_exp_f32_e32 v38, v38
	v_mov_b32_e32 v112, v33
	v_mov_b32_e32 v110, v53
	v_pk_mul_f32 v[62:63], v[62:63], v[64:65]
	v_add_f32_e32 v38, 1.0, v38
	v_mov_b32_e32 v64, v32
	v_mov_b32_e32 v65, v62
	v_rcp_f32_e32 v61, v38
	v_pk_mul_f32 v[64:65], v[64:65], v[64:65]
	v_mov_b32_e32 v111, v63
	v_add_f32_e32 v38, v64, v65
	v_pk_mul_f32 v[58:59], v[58:59], v[60:61]
	v_mov_b32_e32 v60, v52
	v_add_f32_dpp v38, v38, v38 quad_perm:[1,0,3,2] row_mask:0xf bank_mask:0xf bound_ctrl:1
	v_mov_b32_e32 v113, v59
	v_pk_mul_f32 v[112:113], v[112:113], v[112:113]
	v_add_f32_dpp v38, v38, v38 quad_perm:[2,3,0,1] row_mask:0xf bank_mask:0xf bound_ctrl:1
	v_mov_b32_e32 v61, v58
	v_pk_mul_f32 v[60:61], v[60:61], v[60:61]
	v_add_f32_dpp v38, v38, v38 row_half_mirror row_mask:0xf bank_mask:0xf bound_ctrl:1
	v_pk_mul_f32 v[110:111], v[110:111], v[110:111]
	v_and_b32_e32 v44, 0xffff0000, v187
	v_add_f32_dpp v38, v38, v38 row_mirror row_mask:0xf bank_mask:0xf bound_ctrl:1
; #define LAS __attribute__((address_space(3)))
; DI unsigned pk2(float lo, float hi) { return f2bf(lo) | (f2bf(hi) << 16); }
; DI float bflo(unsigned w) { return __uint_as_float(w << 16); }
; DI float bfhi(unsigned w) { return __uint_as_float(w & 0xffff0000u); }
; DI float siluf_(float x) { return x * __builtin_amdgcn_rcpf(1.0f + __expf(-x)); }
; DI float wave_sum(float v) { v = row16_sum(v); return (rdlane(v, 0) + rdlane(v, 16)) + (rdlane(v, 32) + rdlane(v, 48)); }
; DI void gdn_unit(const Params& P, bf16_t* proj, const float* gb, int b, int h, LAS unsigned char* lds) {
;     ...
; #pragma unroll
;             for (int i = 0; i < 8; ++i) {
;                 float a0 = 0.f, a1 = 0.f;
; #pragma unroll
;                 for (int j = 0; j < 4; ++j) { a0 += cw[j][0] * bflo(raw[i + j]); a1 += cw[j][1] * bfhi(raw[i + j]); }
;                 a0 = siluf_(a0); a1 = siluf_(a1);
;                 if (w < 2) {
;                     const float ss = wave_sum(a0 * a0 + a1 * a1);
;                     const float rs = rsqrtf(ss + 1e-6f) * (w == 0 ? 0.08838834764831845f : 1.0f);
;                     a0 *= rs; a1 *= rs;
;                 }
;                 o0[i] = a0; o1[i] = a1;
;             }
;             if (w < 2) {
;                 const int off = (w == 0) ? Q_OFF : K_OFF;
; #pragma unroll
;                 for (int i = 0; i < 8; ++i) *(LAS unsigned*)(lds + off + (wave * 8 + i) * 272 + lane * 4) = pk2(o0[i], o1[i]);
;             }
;             if (w >= 1) {
;                 const int off = (w == 1) ? KT_OFF : VT_OFF;
;                 u32x4 w0, w1;
;                 w0.x = pk2(o0[0], o0[1]); w0.y = pk2(o0[2], o0[3]); w0.z = pk2(o0[4], o0[5]); w0.w = pk2(o0[6], o0[7]);
;                 w1.x = pk2(o1[0], o1[1]); w1.y = pk2(o1[2], o1[3]); w1.z = pk2(o1[4], o1[5]); w1.w = pk2(o1[6], o1[7]);
;                 *(LAS u32x4*)(lds + off + (2 * lane) * 144 + wave * 16) = w0;
;                 *(LAS u32x4*)(lds + off + (2 * lane + 1) * 144 + wave * 16) = w1;
;             }
	v_and_b32_e32 v47, 0xffff0000, v190
	v_readlane_b32 s0, v38, 0
	v_readlane_b32 s3, v38, 16
	v_readlane_b32 s2, v38, 32
	v_readlane_b32 s16, v38, 48
	v_add_f32_e32 v38, v112, v113
	v_mov_b32_e32 v64, s3
	v_mov_b32_e32 v112, s16
	v_add_f32_dpp v38, v38, v38 quad_perm:[1,0,3,2] row_mask:0xf bank_mask:0xf bound_ctrl:1
	v_and_b32_e32 v46, 0xffff0000, v188
	v_mov_b32_e32 v50, v49
	v_add_f32_dpp v38, v38, v38 quad_perm:[2,3,0,1] row_mask:0xf bank_mask:0xf bound_ctrl:1
	v_and_b32_e32 v45, 0xffff0000, v189
	v_mov_b32_e32 v51, v43
	v_add_f32_dpp v38, v38, v38 row_half_mirror row_mask:0xf bank_mask:0xf bound_ctrl:1
	v_lshlrev_b32_e32 v36, 16, v187
	v_lshlrev_b32_e32 v40, 16, v188
	v_add_f32_dpp v38, v38, v38 row_mirror row_mask:0xf bank_mask:0xf bound_ctrl:1
	v_lshlrev_b32_e32 v41, 16, v189
	v_readlane_b32 s17, v38, 16
	v_readlane_b32 s1, v38, 0
	v_readlane_b32 s3, v38, 32
	v_mov_b32_e32 v65, s17
	v_pk_add_f32 v[64:65], s[0:1], v[64:65]
	v_readlane_b32 s0, v38, 48
	s_nop 1
	v_mov_b32_e32 v113, s0
	v_pk_add_f32 v[112:113], s[2:3], v[112:113]
	s_nop 0
	v_pk_add_f32 v[64:65], v[64:65], v[112:113]
	s_nop 0
	v_pk_add_f32 v[64:65], v[64:65], s[76:77] op_sel_hi:[1,0]
	s_nop 0
	v_mul_f32_e32 v38, 0x4b800000, v64
	v_cmp_gt_f32_e64 s[0:1], s26, v64
	v_cmp_gt_f32_e32 vcc, s26, v65
	s_nop 0
	v_cndmask_b32_e64 v38, v64, v38, s[0:1]
	v_rsq_f32_e32 v64, v38
	v_mul_f32_e32 v38, 0x4b800000, v65
	v_cndmask_b32_e32 v38, v65, v38, vcc
	v_rsq_f32_e32 v65, v38
	v_add_f32_e32 v38, v60, v61
	v_pk_mul_f32 v[112:113], v[64:65], s[78:79] op_sel_hi:[1,0]
	s_nop 0
	v_add_f32_dpp v38, v38, v38 quad_perm:[1,0,3,2] row_mask:0xf bank_mask:0xf bound_ctrl:1
	v_cndmask_b32_e64 v64, v64, v112, s[0:1]
	v_cndmask_b32_e32 v65, v65, v113, vcc
	v_add_f32_dpp v38, v38, v38 quad_perm:[2,3,0,1] row_mask:0xf bank_mask:0xf bound_ctrl:1
	v_pk_mul_f32 v[32:33], v[32:33], v[64:65]
	s_nop 0
	v_add_f32_dpp v38, v38, v38 row_half_mirror row_mask:0xf bank_mask:0xf bound_ctrl:1
	v_and_b32_sdwa v57, v32, v166 dst_sel:DWORD dst_unused:UNUSED_PAD src0_sel:WORD_1 src1_sel:DWORD
	v_add3_u32 v32, v32, v57, s68
	v_add_f32_dpp v38, v38, v38 row_mirror row_mask:0xf bank_mask:0xf bound_ctrl:1
	s_nop 0
	v_readlane_b32 s0, v38, 0
	v_readlane_b32 s3, v38, 16
	v_readlane_b32 s2, v38, 32
	v_readlane_b32 s16, v38, 48
	v_add_f32_e32 v38, v110, v111
	v_mov_b32_e32 v60, s3
	v_mov_b32_e32 v110, s16
	v_add_f32_dpp v38, v38, v38 quad_perm:[1,0,3,2] row_mask:0xf bank_mask:0xf bound_ctrl:1
	s_nop 1
	v_add_f32_dpp v38, v38, v38 quad_perm:[2,3,0,1] row_mask:0xf bank_mask:0xf bound_ctrl:1
	s_nop 1
	v_add_f32_dpp v38, v38, v38 row_half_mirror row_mask:0xf bank_mask:0xf bound_ctrl:1
	s_nop 1
	v_add_f32_dpp v38, v38, v38 row_mirror row_mask:0xf bank_mask:0xf bound_ctrl:1
	s_nop 0
	v_readlane_b32 s17, v38, 16
	v_readlane_b32 s1, v38, 0
	v_readlane_b32 s3, v38, 32
	v_mov_b32_e32 v61, s17
	v_pk_add_f32 v[60:61], s[0:1], v[60:61]
	v_readlane_b32 s0, v38, 48
	s_nop 1
	v_mov_b32_e32 v111, s0
	v_pk_add_f32 v[110:111], s[2:3], v[110:111]
	s_nop 0
	v_pk_add_f32 v[60:61], v[60:61], v[110:111]
	s_nop 0
	v_pk_add_f32 v[60:61], v[60:61], s[76:77] op_sel_hi:[1,0]
	s_nop 0
	v_mul_f32_e32 v38, 0x4b800000, v60
	v_cmp_gt_f32_e64 s[0:1], s26, v60
	v_cmp_gt_f32_e32 vcc, s26, v61
	s_nop 0
	v_cndmask_b32_e64 v38, v60, v38, s[0:1]
	v_rsq_f32_e32 v60, v38
	v_mul_f32_e32 v38, 0x4b800000, v61
	v_cndmask_b32_e32 v38, v61, v38, vcc
	v_rsq_f32_e32 v61, v38
	s_nop 0
	v_cvt_pk_bf16_f32 v33, v33, v33
	v_and_b32_e32 v33, 0xffff0000, v33
	v_pk_mul_f32 v[110:111], v[60:61], s[78:79] op_sel_hi:[1,0]
	s_nop 0
	v_cndmask_b32_e32 v61, v61, v111, vcc
	v_cndmask_b32_e64 v60, v60, v110, s[0:1]
	v_mov_b32_e32 v111, v61
	v_pk_mul_f32 v[52:53], v[52:53], v[60:61]
	v_mov_b32_e32 v61, v65
	v_mov_b32_e32 v110, v64
	v_pk_mul_f32 v[58:59], v[58:59], v[60:61]
	v_pk_mul_f32 v[62:63], v[62:63], v[110:111]
	v_and_b32_sdwa v61, v59, v166 dst_sel:DWORD dst_unused:UNUSED_PAD src0_sel:WORD_1 src1_sel:DWORD
	v_add3_u32 v61, v59, v61, s68
	v_cvt_pk_bf16_f32 v57, v62, v62
	v_and_b32_sdwa v62, v58, v166 dst_sel:DWORD dst_unused:UNUSED_PAD src0_sel:WORD_1 src1_sel:DWORD
	v_cvt_pk_bf16_f32 v52, v52, v52
	v_cvt_pk_bf16_f32 v38, v63, v63
	v_lshrrev_b32_e32 v57, 16, v57
	v_add3_u32 v62, v58, v62, s68
	v_and_b32_sdwa v58, v53, v166 dst_sel:DWORD dst_unused:UNUSED_PAD src0_sel:WORD_1 src1_sel:DWORD
	v_and_b32_e32 v52, 0xffff0000, v52
	v_lshrrev_b32_e32 v60, 16, v38
	v_and_or_b32 v38, v32, s39, v57
	v_add3_u32 v53, v53, v58, s68
	v_or_b32_sdwa v58, v52, v62 dst_sel:DWORD dst_unused:UNUSED_PAD src0_sel:DWORD src1_sel:WORD_1
	v_add_u32_e32 v59, 0x4400, v56
	ds_write2_b32 v59, v38, v58 offset1:68
	v_and_or_b32 v38, v53, s39, v60
	v_or_b32_sdwa v58, v33, v61 dst_sel:DWORD dst_unused:UNUSED_PAD src0_sel:DWORD src1_sel:WORD_1
	ds_write2_b32 v59, v38, v58 offset0:136 offset1:204
	v_mov_b32_e32 v58, v48
	v_mov_b32_e32 v59, v44
	v_pk_fma_f32 v[58:59], v[76:77], v[58:59], 0 op_sel_hi:[1,1,0]
	v_pk_mov_b32 v[48:49], v[48:49], v[46:47] op_sel:[1,0]
	v_or_b32_sdwa v32, v32, v52 dst_sel:DWORD dst_unused:UNUSED_PAD src0_sel:WORD_1 src1_sel:DWORD
	v_pk_fma_f32 v[48:49], v[92:93], v[48:49], v[58:59]
	v_mov_b32_e32 v58, v43
	v_mov_b32_e32 v59, v47
	v_pk_fma_f32 v[48:49], v[94:95], v[58:59], v[48:49]
	v_mov_b32_e32 v52, v44
	v_pk_fma_f32 v[48:49], v[96:97], v[44:45], v[48:49]
	v_pk_mov_b32 v[42:43], v[42:43], v[44:45] op_sel:[1,0]
	v_mul_f32_e32 v38, 0xbfb8aa3b, v49
	v_exp_f32_e32 v38, v38
	v_pk_fma_f32 v[44:45], v[76:77], v[50:51], 0 op_sel_hi:[1,1,0]
	v_or_b32_sdwa v33, v33, v53 dst_sel:DWORD dst_unused:UNUSED_PAD src0_sel:DWORD src1_sel:WORD_1
	v_mov_b32_e32 v53, v46
	v_add_f32_e32 v38, 1.0, v38
	v_rcp_f32_e32 v59, v38
; DI float bflo(unsigned w) { return __uint_as_float(w << 16); }
; DI float bfhi(unsigned w) { return __uint_as_float(w & 0xffff0000u); }
; DI float siluf_(float x) { return x * __builtin_amdgcn_rcpf(1.0f + __expf(-x)); }
; DI float wave_sum(float v) { v = row16_sum(v); return (rdlane(v, 0) + rdlane(v, 16)) + (rdlane(v, 32) + rdlane(v, 48)); }
; DI void gdn_unit(const Params& P, bf16_t* proj, const float* gb, int b, int h, LAS unsigned char* lds) {
;     ...
; #pragma unroll
;             for (int i = 0; i < 8; ++i) {
;                 float a0 = 0.f, a1 = 0.f;
; #pragma unroll
;                 for (int j = 0; j < 4; ++j) { a0 += cw[j][0] * bflo(raw[i + j]); a1 += cw[j][1] * bfhi(raw[i + j]); }
;                 a0 = siluf_(a0); a1 = siluf_(a1);
;                 if (w < 2) {
;                     const float ss = wave_sum(a0 * a0 + a1 * a1);
;                     const float rs = rsqrtf(ss + 1e-6f) * (w == 0 ? 0.08838834764831845f : 1.0f);
;                     a0 *= rs; a1 *= rs;
;                 }
;                 o0[i] = a0; o1[i] = a1;
;             }
	v_mul_f32_e32 v38, 0xbfb8aa3b, v48
	v_exp_f32_e32 v38, v38
	v_pk_fma_f32 v[42:43], v[92:93], v[42:43], v[44:45]
	v_lshlrev_b32_e32 v50, 16, v195
	v_pk_fma_f32 v[42:43], v[94:95], v[52:53], v[42:43]
	v_add_f32_e32 v38, 1.0, v38
	v_pk_fma_f32 v[42:43], v[96:97], v[46:47], v[42:43]
	v_rcp_f32_e32 v58, v38
	v_mul_f32_e32 v38, 0xbfb8aa3b, v42
	v_exp_f32_e32 v38, v38
	v_pk_mov_b32 v[46:47], v[34:35], v[40:41] op_sel:[1,0]
	v_pk_fma_f32 v[34:35], v[98:99], v[34:35], 0 op_sel_hi:[1,1,0]
	v_pk_mul_f32 v[48:49], v[48:49], v[58:59]
	v_add_f32_e32 v38, 1.0, v38
	v_rcp_f32_e32 v44, v38
	v_mul_f32_e32 v38, 0xbfb8aa3b, v43
	v_exp_f32_e32 v38, v38
	v_lshlrev_b32_e32 v51, 16, v197
	v_lshlrev_b32_e32 v53, 16, v196
	v_add_f32_e32 v38, 1.0, v38
	v_rcp_f32_e32 v45, v38
	v_pk_mov_b32 v[38:39], v[38:39], v[36:37] op_sel:[1,0]
	v_pk_mul_f32 v[42:43], v[42:43], v[44:45]
	v_pk_fma_f32 v[44:45], v[98:99], v[38:39], 0 op_sel_hi:[1,1,0]
	v_pk_fma_f32 v[34:35], v[78:79], v[38:39], v[34:35]
	v_pk_fma_f32 v[44:45], v[78:79], v[46:47], v[44:45]
	v_pk_fma_f32 v[34:35], v[80:81], v[46:47], v[34:35]
	v_pk_fma_f32 v[44:45], v[80:81], v[36:37], v[44:45]
	v_pk_fma_f32 v[34:35], v[82:83], v[36:37], v[34:35]
	v_pk_fma_f32 v[40:41], v[82:83], v[40:41], v[44:45]
	v_mul_f32_e32 v36, 0xbfb8aa3b, v34
	v_mul_f32_e32 v44, 0xbfb8aa3b, v41
	v_exp_f32_e32 v44, v44
	v_mul_f32_e32 v37, 0xbfb8aa3b, v35
	v_exp_f32_e32 v36, v36
	v_exp_f32_e32 v37, v37
	v_add_f32_e32 v44, 1.0, v44
	v_rcp_f32_e32 v45, v44
	v_mul_f32_e32 v44, 0xbfb8aa3b, v40
	v_exp_f32_e32 v44, v44
	v_add_f32_e32 v36, 1.0, v36
	v_add_f32_e32 v37, 1.0, v37
	v_rcp_f32_e32 v36, v36
	v_add_f32_e32 v44, 1.0, v44
	v_rcp_f32_e32 v44, v44
	v_rcp_f32_e32 v37, v37
	v_mov_b32_e32 v38, v42
	v_mov_b32_e32 v46, v43
	v_pk_mul_f32 v[40:41], v[40:41], v[44:45]
	v_mov_b32_e32 v44, v49
	v_mov_b32_e32 v45, v41
	v_pk_mul_f32 v[34:35], v[34:35], v[36:37]
	v_pk_mul_f32 v[44:45], v[44:45], v[44:45]
	v_mov_b32_e32 v36, v48
	v_mov_b32_e32 v37, v34
	v_pk_mul_f32 v[36:37], v[36:37], v[36:37]
	v_add_f32_e32 v44, v44, v45
	v_add_f32_e32 v36, v36, v37
	v_mov_b32_e32 v39, v40
	v_add_f32_dpp v44, v44, v44 quad_perm:[1,0,3,2] row_mask:0xf bank_mask:0xf bound_ctrl:1
	v_add_f32_dpp v36, v36, v36 quad_perm:[1,0,3,2] row_mask:0xf bank_mask:0xf bound_ctrl:1
	v_pk_mul_f32 v[38:39], v[38:39], v[38:39]
	v_add_f32_dpp v44, v44, v44 quad_perm:[2,3,0,1] row_mask:0xf bank_mask:0xf bound_ctrl:1
	v_add_f32_dpp v36, v36, v36 quad_perm:[2,3,0,1] row_mask:0xf bank_mask:0xf bound_ctrl:1
	v_add_f32_e32 v38, v38, v39
	v_add_f32_dpp v44, v44, v44 row_half_mirror row_mask:0xf bank_mask:0xf bound_ctrl:1
	v_add_f32_dpp v36, v36, v36 row_half_mirror row_mask:0xf bank_mask:0xf bound_ctrl:1
	v_add_f32_dpp v38, v38, v38 quad_perm:[1,0,3,2] row_mask:0xf bank_mask:0xf bound_ctrl:1
	v_add_f32_dpp v44, v44, v44 row_mirror row_mask:0xf bank_mask:0xf bound_ctrl:1
	v_mov_b32_e32 v47, v35
	v_readlane_b32 s1, v44, 0
	v_readlane_b32 s2, v44, 16
	v_readlane_b32 s3, v44, 32
	v_readlane_b32 s16, v44, 48
	v_add_f32_dpp v44, v36, v36 row_mirror row_mask:0xf bank_mask:0xf bound_ctrl:1
	v_mov_b32_e32 v37, s2
	v_readlane_b32 s17, v44, 16
	v_readlane_b32 s0, v44, 0
	v_readlane_b32 s2, v44, 32
	v_mov_b32_e32 v36, s17
	v_pk_add_f32 v[36:37], s[0:1], v[36:37]
	v_readlane_b32 s0, v44, 48
	v_mov_b32_e32 v45, s16
	v_add_f32_dpp v38, v38, v38 quad_perm:[2,3,0,1] row_mask:0xf bank_mask:0xf bound_ctrl:1
	v_mov_b32_e32 v44, s0
	v_pk_add_f32 v[44:45], s[2:3], v[44:45]
	v_add_f32_dpp v38, v38, v38 row_half_mirror row_mask:0xf bank_mask:0xf bound_ctrl:1
	v_pk_add_f32 v[36:37], v[36:37], v[44:45]
	v_pk_mul_f32 v[46:47], v[46:47], v[46:47]
	v_pk_add_f32 v[36:37], v[36:37], s[76:77] op_sel_hi:[1,0]
	v_add_f32_dpp v38, v38, v38 row_mirror row_mask:0xf bank_mask:0xf bound_ctrl:1
	v_mul_f32_e32 v44, 0x4b800000, v37
	v_cmp_gt_f32_e64 s[0:1], s26, v37
	v_cmp_gt_f32_e32 vcc, s26, v36
	v_readlane_b32 s3, v38, 16
	v_cndmask_b32_e64 v37, v37, v44, s[0:1]
	v_mul_f32_e32 v44, 0x4b800000, v36
	v_cndmask_b32_e32 v36, v36, v44, vcc
	v_rsq_f32_e32 v37, v37
	v_rsq_f32_e32 v36, v36
	v_readlane_b32 s2, v38, 32
	v_readlane_b32 s16, v38, 48
	v_pk_mul_f32 v[44:45], v[36:37], s[78:79] op_sel_hi:[1,0]
	s_nop 0
	v_cndmask_b32_e64 v37, v37, v45, s[0:1]
	v_readlane_b32 s0, v38, 0
	v_add_f32_e32 v38, v46, v47
	v_cndmask_b32_e32 v36, v36, v44, vcc
	v_mov_b32_e32 v47, v50
	v_add_f32_dpp v38, v38, v38 quad_perm:[1,0,3,2] row_mask:0xf bank_mask:0xf bound_ctrl:1
	s_nop 1
	v_add_f32_dpp v38, v38, v38 quad_perm:[2,3,0,1] row_mask:0xf bank_mask:0xf bound_ctrl:1
	s_nop 1
	v_add_f32_dpp v38, v38, v38 row_half_mirror row_mask:0xf bank_mask:0xf bound_ctrl:1
	s_nop 1
	v_add_f32_dpp v44, v38, v38 row_mirror row_mask:0xf bank_mask:0xf bound_ctrl:1
	v_mov_b32_e32 v38, s3
	v_readlane_b32 s17, v44, 16
	v_readlane_b32 s1, v44, 0
	v_readlane_b32 s3, v44, 32
	v_mov_b32_e32 v39, s17
	v_pk_add_f32 v[38:39], s[0:1], v[38:39]
	v_readlane_b32 s0, v44, 48
	v_mov_b32_e32 v44, s16
	s_nop 0
	v_mov_b32_e32 v45, s0
	v_pk_add_f32 v[44:45], s[2:3], v[44:45]
	s_nop 0
	v_pk_add_f32 v[38:39], v[38:39], v[44:45]
	s_nop 0
	v_pk_add_f32 v[38:39], v[38:39], s[76:77] op_sel_hi:[1,0]
	s_nop 0
	v_mul_f32_e32 v44, 0x4b800000, v38
	v_cmp_gt_f32_e64 s[0:1], s26, v38
	v_cmp_gt_f32_e32 vcc, s26, v39
	s_nop 0
	v_cndmask_b32_e64 v38, v38, v44, s[0:1]
	v_mul_f32_e32 v44, 0x4b800000, v39
	v_cndmask_b32_e32 v39, v39, v44, vcc
	v_rsq_f32_e32 v38, v38
	v_rsq_f32_e32 v39, v39
	s_nop 0
	v_pk_mul_f32 v[44:45], v[38:39], s[78:79] op_sel_hi:[1,0]
	s_nop 0
	v_cndmask_b32_e64 v38, v38, v44, s[0:1]
	v_cndmask_b32_e32 v39, v39, v45, vcc
	v_mov_b32_e32 v44, v38
	v_mov_b32_e32 v45, v37
	v_pk_mul_f32 v[40:41], v[40:41], v[44:45]
; #define LAS __attribute__((address_space(3)))
; DI unsigned pk2(float lo, float hi) { return f2bf(lo) | (f2bf(hi) << 16); }
; DI float bflo(unsigned w) { return __uint_as_float(w << 16); }
; DI float bfhi(unsigned w) { return __uint_as_float(w & 0xffff0000u); }
; DI float siluf_(float x) { return x * __builtin_amdgcn_rcpf(1.0f + __expf(-x)); }
; DI float wave_sum(float v) { v = row16_sum(v); return (rdlane(v, 0) + rdlane(v, 16)) + (rdlane(v, 32) + rdlane(v, 48)); }
; DI void gdn_unit(const Params& P, bf16_t* proj, const float* gb, int b, int h, LAS unsigned char* lds) {
;     ...
;         for (int w = 0; w < 3; ++w) {
;             const f32x2 (&cw)[4] = cwr[w];
;             const unsigned (&raw)[11] = rawq[w];
;             float o0[8], o1[8];
; #pragma unroll
;             for (int i = 0; i < 8; ++i) {
;                 float a0 = 0.f, a1 = 0.f;
; #pragma unroll
;                 for (int j = 0; j < 4; ++j) { a0 += cw[j][0] * bflo(raw[i + j]); a1 += cw[j][1] * bfhi(raw[i + j]); }
;                 a0 = siluf_(a0); a1 = siluf_(a1);
;                 if (w < 2) {
;                     const float ss = wave_sum(a0 * a0 + a1 * a1);
;                     const float rs = rsqrtf(ss + 1e-6f) * (w == 0 ? 0.08838834764831845f : 1.0f);
;                     a0 *= rs; a1 *= rs;
;                 }
;                 o0[i] = a0; o1[i] = a1;
;             }
;             if (w < 2) {
;                 const int off = (w == 0) ? Q_OFF : K_OFF;
; #pragma unroll
;                 for (int i = 0; i < 8; ++i) *(LAS unsigned*)(lds + off + (wave * 8 + i) * 272 + lane * 4) = pk2(o0[i], o1[i]);
;             }
;             if (w >= 1) {
;                 const int off = (w == 1) ? KT_OFF : VT_OFF;
;                 u32x4 w0, w1;
;                 w0.x = pk2(o0[0], o0[1]); w0.y = pk2(o0[2], o0[3]); w0.z = pk2(o0[4], o0[5]); w0.w = pk2(o0[6], o0[7]);
;                 w1.x = pk2(o1[0], o1[1]); w1.y = pk2(o1[2], o1[3]); w1.z = pk2(o1[4], o1[5]); w1.w = pk2(o1[6], o1[7]);
;                 *(LAS u32x4*)(lds + off + (2 * lane) * 144 + wave * 16) = w0;
;                 *(LAS u32x4*)(lds + off + (2 * lane + 1) * 144 + wave * 16) = w1;
;             }
	s_nop 0
	v_and_b32_sdwa v44, v41, v166 dst_sel:DWORD dst_unused:UNUSED_PAD src0_sel:WORD_1 src1_sel:DWORD
	v_and_b32_sdwa v45, v40, v166 dst_sel:DWORD dst_unused:UNUSED_PAD src0_sel:WORD_1 src1_sel:DWORD
	v_add3_u32 v45, v40, v45, s68
	v_add3_u32 v44, v41, v44, s68
	v_pk_mul_f32 v[40:41], v[48:49], v[36:37]
	v_lshlrev_b32_e32 v48, 16, v193
	v_cvt_pk_bf16_f32 v37, v41, v41
	v_and_b32_e32 v41, 0xffff0000, v37
	v_mov_b32_e32 v37, v39
	v_pk_mul_f32 v[34:35], v[34:35], v[36:37]
	v_pk_mul_f32 v[36:37], v[42:43], v[38:39]
	v_and_b32_sdwa v46, v40, v166 dst_sel:DWORD dst_unused:UNUSED_PAD src0_sel:WORD_1 src1_sel:DWORD
	v_cvt_pk_bf16_f32 v34, v34, v34
	v_cvt_pk_bf16_f32 v36, v36, v36
	v_add3_u32 v40, v40, v46, s68
	v_cvt_pk_bf16_f32 v35, v35, v35
	v_lshrrev_b32_e32 v34, 16, v34
	v_and_b32_sdwa v39, v37, v166 dst_sel:DWORD dst_unused:UNUSED_PAD src0_sel:WORD_1 src1_sel:DWORD
	v_and_b32_e32 v42, 0xffff0000, v36
	v_lshrrev_b32_e32 v35, 16, v35
	v_and_or_b32 v38, v40, s39, v34
	v_add3_u32 v43, v37, v39, s68
	v_or_b32_sdwa v36, v42, v45 dst_sel:DWORD dst_unused:UNUSED_PAD src0_sel:DWORD src1_sel:WORD_1
	v_add_u32_e32 v37, 0x4800, v56
	v_or_b32_sdwa v46, v41, v44 dst_sel:DWORD dst_unused:UNUSED_PAD src0_sel:DWORD src1_sel:WORD_1
	ds_write2_b32 v37, v38, v36 offset0:16 offset1:84
	v_and_or_b32 v36, v43, s39, v35
	ds_write2_b32 v37, v36, v46 offset0:152 offset1:220
	v_lshlrev_b32_e32 v46, 16, v191
	v_lshlrev_b32_e32 v49, 16, v194
	v_pk_fma_f32 v[46:47], v[84:85], v[46:47], 0 op_sel_hi:[1,1,0]
	v_mov_b32_e32 v52, v49
	v_pk_fma_f32 v[46:47], v[86:87], v[48:49], v[46:47]
	v_and_or_b32 v39, v44, s39, v35
	v_pk_fma_f32 v[46:47], v[88:89], v[50:51], v[46:47]
	v_or_b32_sdwa v35, v41, v43 dst_sel:DWORD dst_unused:UNUSED_PAD src0_sel:DWORD src1_sel:WORD_1
	v_pk_fma_f32 v[46:47], v[90:91], v[52:53], v[46:47]
	v_pk_fma_f32 v[48:49], v[84:85], v[48:49], 0 op_sel_hi:[1,1,0]
	v_mul_f32_e32 v41, 0xbfb8aa3b, v46
	v_exp_f32_e32 v41, v41
	v_pk_fma_f32 v[48:49], v[86:87], v[50:51], v[48:49]
	v_and_or_b32 v36, v62, s39, v57
	v_lshlrev_b32_e32 v57, 16, v198
	v_mov_b32_e32 v56, v51
	v_pk_fma_f32 v[48:49], v[88:89], v[52:53], v[48:49]
	v_add_f32_e32 v41, 1.0, v41
	v_pk_fma_f32 v[48:49], v[90:91], v[56:57], v[48:49]
	v_rcp_f32_e32 v58, v41
	v_mul_f32_e32 v41, 0xbfb8aa3b, v48
	v_exp_f32_e32 v41, v41
	v_add3_u32 v62, v54, v55, s4
	v_lshlrev_b32_e32 v54, 16, v199
	v_lshlrev_b32_e32 v55, 16, v200
	v_add_f32_e32 v41, 1.0, v41
	v_rcp_f32_e32 v50, v41
	v_mul_f32_e32 v41, 0xbfb8aa3b, v47
	v_exp_f32_e32 v41, v41
	v_pk_mov_b32 v[52:53], v[52:53], v[54:55] op_sel:[1,0]
	v_and_or_b32 v37, v61, s39, v60
	v_and_or_b32 v38, v45, s39, v34
	v_add_f32_e32 v41, 1.0, v41
	v_rcp_f32_e32 v59, v41
	v_mul_f32_e32 v41, 0xbfb8aa3b, v49
	v_exp_f32_e32 v41, v41
	v_or_b32_sdwa v34, v40, v42 dst_sel:DWORD dst_unused:UNUSED_PAD src0_sel:WORD_1 src1_sel:DWORD
	v_pk_mul_f32 v[46:47], v[46:47], v[58:59]
	v_pk_fma_f32 v[58:59], v[84:85], v[52:53], 0 op_sel_hi:[1,1,0]
	v_add_f32_e32 v41, 1.0, v41
	v_rcp_f32_e32 v51, v41
	v_and_b32_e32 v42, 0xffff0000, v195
	ds_write_b128 v62, v[36:39] offset:34816
	ds_write_b128 v62, v[32:35] offset:34960
	v_and_b32_e32 v44, 0xffff0000, v191
	v_pk_mul_f32 v[48:49], v[48:49], v[50:51]
	v_lshlrev_b32_e32 v50, 16, v201
	v_lshlrev_b32_e32 v51, 16, v202
	v_pk_mov_b32 v[60:61], v[56:57], v[50:51] op_sel:[1,0]
	v_pk_fma_f32 v[56:57], v[84:85], v[56:57], 0 op_sel_hi:[1,1,0]
	v_pk_fma_f32 v[58:59], v[86:87], v[60:61], v[58:59]
	v_pk_fma_f32 v[52:53], v[86:87], v[52:53], v[56:57]
	v_pk_fma_f32 v[58:59], v[88:89], v[54:55], v[58:59]
	v_pk_fma_f32 v[52:53], v[88:89], v[60:61], v[52:53]
	v_pk_fma_f32 v[50:51], v[90:91], v[50:51], v[58:59]
	v_pk_fma_f32 v[52:53], v[90:91], v[54:55], v[52:53]
	v_mul_f32_e32 v41, 0xbfb8aa3b, v51
	v_exp_f32_e32 v41, v41
	s_nop 0
	s_nop 0
	s_nop 0
	v_add_f32_e32 v41, 1.0, v41
	v_rcp_f32_e32 v59, v41
	v_mul_f32_e32 v41, 0xbfb8aa3b, v52
	v_exp_f32_e32 v41, v41
	s_nop 0
	s_nop 0
	v_and_b32_e32 v36, 0xffff0000, v194
	v_add_f32_e32 v41, 1.0, v41
	v_rcp_f32_e32 v54, v41
	v_mul_f32_e32 v41, 0xbfb8aa3b, v50
	v_exp_f32_e32 v41, v41
	v_cvt_pk_bf16_f32 v47, v47, v49
	v_mov_b32_e32 v45, v42
	v_and_b32_e32 v40, 0xffff0000, v193
	v_add_f32_e32 v41, 1.0, v41
	v_rcp_f32_e32 v58, v41
	v_mul_f32_e32 v41, 0xbfb8aa3b, v53
	v_exp_f32_e32 v41, v41
	v_and_b32_e32 v32, 0xffff0000, v197
	v_pk_mul_f32 v[50:51], v[50:51], v[58:59]
	v_pk_fma_f32 v[44:45], v[100:101], v[44:45], 0 op_sel_hi:[1,1,0]
	v_add_f32_e32 v41, 1.0, v41
	v_rcp_f32_e32 v55, v41
	s_nop 0
	s_nop 0
	s_nop 0
	v_pk_mul_f32 v[52:53], v[52:53], v[54:55]
	v_cvt_pk_bf16_f32 v54, v48, v48
	v_bfe_u32 v48, v46, 16, 1
	v_add3_u32 v46, v46, v48, s68
	v_cvt_pk_bf16_f32 v49, v53, v51
	v_mov_b32_e32 v41, v36
	v_cvt_pk_bf16_f32 v48, v52, v50
	v_mov_b32_e32 v43, v32
	v_pk_fma_f32 v[44:45], v[102:103], v[40:41], v[44:45]
	v_and_b32_e32 v37, 0xffff0000, v196
	v_pk_fma_f32 v[44:45], v[104:105], v[42:43], v[44:45]
	v_pk_fma_f32 v[40:41], v[100:101], v[40:41], 0 op_sel_hi:[1,1,0]
	v_pk_fma_f32 v[44:45], v[106:107], v[36:37], v[44:45]
	v_pk_fma_f32 v[40:41], v[102:103], v[42:43], v[40:41]
	v_mul_f32_e32 v43, 0xbfb8aa3b, v45
	v_exp_f32_e32 v43, v43
	v_and_b32_e32 v33, 0xffff0000, v198
	v_pk_fma_f32 v[40:41], v[104:105], v[36:37], v[40:41]
	v_mul_f32_e32 v50, 0xbfb8aa3b, v44
	v_pk_fma_f32 v[40:41], v[106:107], v[32:33], v[40:41]
	v_add_f32_e32 v43, 1.0, v43
	v_mul_f32_e32 v42, 0xbfb8aa3b, v40
	v_rcp_f32_e32 v51, v43
	v_mul_f32_e32 v43, 0xbfb8aa3b, v41
	v_exp_f32_e32 v50, v50
	v_exp_f32_e32 v42, v42
	v_exp_f32_e32 v43, v43
	v_and_b32_e32 v35, 0xffff0000, v200
	v_add_f32_e32 v50, 1.0, v50
	v_add_f32_e32 v42, 1.0, v42
	v_add_f32_e32 v43, 1.0, v43
; #define LAS __attribute__((address_space(3)))
; DI unsigned pk2(float lo, float hi) { return f2bf(lo) | (f2bf(hi) << 16); }
; DI void gdn_unit(const Params& P, bf16_t* proj, const float* gb, int b, int h, LAS unsigned char* lds) {
;     ...
;             if (w >= 1) {
;                 const int off = (w == 1) ? KT_OFF : VT_OFF;
;                 u32x4 w0, w1;
;                 w0.x = pk2(o0[0], o0[1]); w0.y = pk2(o0[2], o0[3]); w0.z = pk2(o0[4], o0[5]); w0.w = pk2(o0[6], o0[7]);
;                 w1.x = pk2(o1[0], o1[1]); w1.y = pk2(o1[2], o1[3]); w1.z = pk2(o1[4], o1[5]); w1.w = pk2(o1[6], o1[7]);
;                 *(LAS u32x4*)(lds + off + (2 * lane) * 144 + wave * 16) = w0;
;                 *(LAS u32x4*)(lds + off + (2 * lane + 1) * 144 + wave * 16) = w1;
;             }
;         }
;         if (n + 1 < 32) {
; #pragma unroll
;             for (int w = 0; w < 3; ++w) {
;                 const bf16_t* rbase = proj + (size_t)(t0 + 64 + wave * 8 - 3) * PJ1 + w * 1024 + h * 128;
; #pragma unroll
;                 for (int i = 0; i < 11; ++i) rawq[w][i] = *(const unsigned*)(rbase + i * PJ1 + 2 * lane);
;             }
;             gbl = gb[(size_t)(t0 + 64 + lane) * 16 + h]; gai = gb[(size_t)(t0 + 64 + lane) * 16 + 8 + h];
;         }
	v_rcp_f32_e32 v50, v50
	v_rcp_f32_e32 v42, v42
	v_rcp_f32_e32 v43, v43
	v_and_b32_e32 v34, 0xffff0000, v199
	v_and_b32_e32 v39, 0xffff0000, v202
	v_and_b32_e32 v38, 0xffff0000, v201
	v_pk_mov_b32 v[36:37], v[36:37], v[34:35] op_sel:[1,0]
	v_pk_mul_f32 v[44:45], v[44:45], v[50:51]
	v_pk_mul_f32 v[40:41], v[40:41], v[42:43]
	v_pk_fma_f32 v[42:43], v[100:101], v[36:37], 0 op_sel_hi:[1,1,0]
	v_pk_mov_b32 v[50:51], v[32:33], v[38:39] op_sel:[1,0]
	v_pk_fma_f32 v[32:33], v[100:101], v[32:33], 0 op_sel_hi:[1,1,0]
	v_pk_fma_f32 v[42:43], v[102:103], v[50:51], v[42:43]
	v_pk_fma_f32 v[32:33], v[102:103], v[36:37], v[32:33]
	v_pk_fma_f32 v[42:43], v[104:105], v[34:35], v[42:43]
	v_pk_fma_f32 v[32:33], v[104:105], v[50:51], v[32:33]
	v_pk_fma_f32 v[38:39], v[106:107], v[38:39], v[42:43]
	v_pk_fma_f32 v[32:33], v[106:107], v[34:35], v[32:33]
	v_mul_f32_e32 v42, 0xbfb8aa3b, v39
	v_mul_f32_e32 v35, 0xbfb8aa3b, v38
	v_exp_f32_e32 v42, v42
	v_exp_f32_e32 v35, v35
	v_mul_f32_e32 v34, 0xbfb8aa3b, v32
	v_exp_f32_e32 v34, v34
	v_add_f32_e32 v42, 1.0, v42
	v_add_f32_e32 v35, 1.0, v35
	v_rcp_f32_e32 v43, v42
	v_rcp_f32_e32 v42, v35
	v_mul_f32_e32 v35, 0xbfb8aa3b, v33
	v_exp_f32_e32 v35, v35
	v_add_f32_e32 v34, 1.0, v34
	v_rcp_f32_e32 v34, v34
	v_pk_mul_f32 v[36:37], v[38:39], v[42:43]
	v_add_f32_e32 v35, 1.0, v35
	v_rcp_f32_e32 v35, v35
	s_nop 0
	s_nop 0
	v_cvt_pk_bf16_f32 v38, v41, v41
	v_pk_mul_f32 v[32:33], v[32:33], v[34:35]
	v_bfe_u32 v35, v36, 16, 1
	v_add3_u32 v36, v36, v35, s68
	v_cvt_pk_bf16_f32 v34, v37, v37
	v_cvt_pk_bf16_f32 v37, v40, v40
	v_bfe_u32 v41, v45, 16, 1
	v_lshrrev_b32_e32 v46, 16, v46
	v_cvt_pk_bf16_f32 v33, v33, v33
	v_cvt_pk_bf16_f32 v32, v32, v32
	v_add3_u32 v35, v45, v41, s68
	v_cvt_pk_bf16_f32 v39, v44, v44
	v_and_or_b32 v46, v54, s39, v46
	v_lshrrev_b32_e32 v32, 16, v32
	v_lshrrev_b32_e32 v33, 16, v33
	v_lshrrev_b32_e32 v39, 16, v39
	v_lshrrev_b32_e32 v40, 16, v35
	v_lshlrev_b32_e32 v60, 1, v67
	v_and_or_b32 v35, v34, s39, v33
	v_and_or_b32 v34, v36, s39, v32
	v_and_or_b32 v33, v38, s39, v40
	v_and_or_b32 v32, v37, s39, v39
	ds_write_b128 v62, v[46:49] offset:53248
	ds_write_b128 v62, v[32:35] offset:53392
	s_cbranch_scc1 .LBB0_425
	s_add_i32 s0, s41, s42
	s_add_i32 s0, s0, -3
	s_ashr_i32 s1, s0, 31
	s_lshl_b64 s[0:1], s[0:1], 13
	s_add_u32 s0, s43, s0
	s_addc_u32 s1, s44, s1
	v_ashrrev_i32_e32 v61, 31, v60
	v_lshl_add_u64 v[32:33], v[60:61], 1, s[0:1]
	s_movk_i32 s0, 0x2000
	v_add_co_u32_e32 v34, vcc, s0, v32
	s_movk_i32 s0, 0x3000
	s_nop 0
	v_addc_co_u32_e32 v35, vcc, 0, v33, vcc
	v_add_co_u32_e32 v36, vcc, s0, v32
	s_movk_i32 s0, 0x4000
	s_nop 0
	v_addc_co_u32_e32 v37, vcc, 0, v33, vcc
	v_add_co_u32_e32 v38, vcc, s0, v32
	s_movk_i32 s0, 0x5000
	s_nop 0
	v_addc_co_u32_e32 v39, vcc, 0, v33, vcc
	v_add_co_u32_e32 v40, vcc, s0, v32
	s_movk_i32 s0, 0x6000
	s_nop 0
	v_addc_co_u32_e32 v41, vcc, 0, v33, vcc
	v_add_co_u32_e32 v42, vcc, s0, v32
	s_movk_i32 s0, 0x7000
	s_nop 0
	v_addc_co_u32_e32 v43, vcc, 0, v33, vcc
	v_add_co_u32_e32 v44, vcc, s0, v32
	s_mov_b32 s0, 0x8000
	s_nop 0
	v_addc_co_u32_e32 v45, vcc, 0, v33, vcc
	v_add_co_u32_e32 v46, vcc, s0, v32
	s_mov_b32 s0, 0x9000
	s_nop 0
	v_addc_co_u32_e32 v47, vcc, 0, v33, vcc
	v_add_co_u32_e32 v48, vcc, s0, v32
	s_mov_b32 s0, 0xa000
	s_nop 0
	v_addc_co_u32_e32 v49, vcc, 0, v33, vcc
	v_add_co_u32_e32 v50, vcc, s0, v32
	s_mov_b32 s0, 0xb000
	s_nop 0
	v_addc_co_u32_e32 v51, vcc, 0, v33, vcc
	v_add_co_u32_e32 v52, vcc, s0, v32
	s_mov_b32 s0, 0xc000
	s_nop 0
	v_addc_co_u32_e32 v53, vcc, 0, v33, vcc
	v_add_co_u32_e32 v54, vcc, s0, v32
	s_mov_b32 s0, 0xd000
	s_nop 0
	v_addc_co_u32_e32 v55, vcc, 0, v33, vcc
	v_add_co_u32_e32 v56, vcc, s0, v32
	s_mov_b32 s0, 0xe000
	s_nop 0
	v_addc_co_u32_e32 v57, vcc, 0, v33, vcc
	v_add_co_u32_e32 v58, vcc, s0, v32
	s_mov_b32 s0, 0xf000
	s_nop 0
	v_addc_co_u32_e32 v59, vcc, 0, v33, vcc
	v_add_co_u32_e32 v62, vcc, s0, v32
	s_mov_b32 s0, 0x10000
	s_nop 0
	v_addc_co_u32_e32 v63, vcc, 0, v33, vcc
	v_add_co_u32_e32 v64, vcc, s0, v32
	s_mov_b32 s0, 0x11000
	s_nop 0
	v_addc_co_u32_e32 v65, vcc, 0, v33, vcc
	v_add_co_u32_e32 v110, vcc, s0, v32
	s_mov_b32 s0, 0x12000
	s_nop 0
	v_addc_co_u32_e32 v111, vcc, 0, v33, vcc
	v_add_co_u32_e32 v112, vcc, s0, v32
	s_mov_b32 s0, 0x14000
	s_nop 0
	v_addc_co_u32_e32 v113, vcc, 0, v33, vcc
	v_add_co_u32_e32 v114, vcc, s0, v32
	s_movk_i32 s0, 0x1000
	s_nop 0
	v_addc_co_u32_e32 v115, vcc, 0, v33, vcc
	global_load_dword v136, v[32:33], off
	global_load_dword v177, v[32:33], off offset:2048
	global_load_dword v181, v[34:35], off offset:2048
	global_load_dword v180, v[38:39], off offset:2048
	global_load_dword v184, v[42:43], off offset:2048
	global_load_dword v183, v[46:47], off offset:2048
	global_load_dword v186, v[50:51], off offset:2048
	global_load_dword v185, v[54:55], off offset:2048
	v_add_co_u32_e32 v34, vcc, s0, v32
	s_nop 1
	v_addc_co_u32_e32 v35, vcc, 0, v33, vcc
	v_add_co_u32_e32 v38, vcc, 0x13000, v32
	s_nop 1
	v_addc_co_u32_e32 v39, vcc, 0, v33, vcc
	global_load_dword v178, v[112:113], off
	global_load_dword v182, v[114:115], off
	global_load_dword v187, v[58:59], off offset:2048
	global_load_dword v189, v[114:115], off offset:2048
	global_load_dword v191, v[34:35], off
	global_load_dword v200, v[38:39], off
	global_load_dword v190, v[112:113], off offset:2048
	global_load_dword v188, v[64:65], off offset:2048
	global_load_dword v159, v[48:49], off offset:-4096
	global_load_dword v158, v[52:53], off offset:-4096
	global_load_dword v176, v[56:57], off offset:-4096
	global_load_dword v161, v[62:63], off offset:-4096
	global_load_dword v198, v[56:57], off
	global_load_dword v196, v[52:53], off
	global_load_dword v197, v[48:49], off
	global_load_dword v194, v[44:45], off
	global_load_dword v179, v[110:111], off offset:-4096
	global_load_dword v201, v[110:111], off
	global_load_dword v199, v[62:63], off
	v_add_u32_e32 v34, s42, v67
	v_ashrrev_i32_e32 v35, 31, v34
	v_add_co_u32_e32 v32, vcc, 0x15000, v32
	v_lshlrev_b64 v[34:35], 6, v[34:35]
	s_nop 0
	v_addc_co_u32_e32 v33, vcc, 0, v33, vcc
	v_lshl_add_u64 v[34:35], s[6:7], 0, v[34:35]
	global_load_dword v157, v[36:37], off offset:-4096
	global_load_dword v156, v[40:41], off offset:-4096
	global_load_dword v160, v[44:45], off offset:-4096
	global_load_dword v195, v[40:41], off
	global_load_dword v193, v[36:37], off
	global_load_dword v202, v[32:33], off
	global_load_dword v203, v[34:35], off
	global_load_dword v204, v[34:35], off offset:32

; #define LAS __attribute__((address_space(3)))
; DI unsigned pk2(float lo, float hi) { return f2bf(lo) | (f2bf(hi) << 16); }
; DI void gdn_unit(const Params& P, bf16_t* proj, const float* gb, int b, int h, LAS unsigned char* lds) {
;     ...
;         if (wave == 0) {
;             const int blk = lane >> 5, cl = lane & 31;
;             LAS unsigned char* Lbytes = lds + L_OFF;
;             LAS unsigned char* L21b = (LAS unsigned char*)part;
;             {
;                 const int r = lane >> 1, hh = lane & 1;
;                 f32x4 x[4];
; #pragma unroll
;                 for (int q = 0; q < 4; ++q) x[q] = *(const LAS f32x4*)(Lm + (32 + r) * 64 + hh * 16 + q * 4);
;                 u32x4 w0, w1;
;                 w0.x = pk2(x[0][0], x[0][1]); w0.y = pk2(x[0][2], x[0][3]); w0.z = pk2(x[1][0], x[1][1]); w0.w = pk2(x[1][2], x[1][3]);
;                 w1.x = pk2(x[2][0], x[2][1]); w1.y = pk2(x[2][2], x[2][3]); w1.z = pk2(x[3][0], x[3][1]); w1.w = pk2(x[3][2], x[3][3]);
;                 *(LAS u32x4*)(L21b + r * 64 + hh * 32) = w0; *(LAS u32x4*)(L21b + r * 64 + hh * 32 + 16) = w1;
;             }
;             const LAS float* Lblk = Lm + blk * (32 * 64 + 32);
;             float Tc[32];
; #pragma unroll
;             for (int i = 0; i < 32; ++i) {
;                 float s0 = (cl == i) ? 1.0f : 0.0f, s1 = 0.f, s2 = 0.f, s3 = 0.f;
;                 f32x4 lr[8];
; #pragma unroll
;                 for (int j4 = 0; j4 < (i + 3) / 4; ++j4) lr[j4] = *(const LAS f32x4*)(Lblk + i * 64 + j4 * 4);
;                 __builtin_amdgcn_sched_barrier(0);
; #pragma unroll
;                 for (int j4 = 0; j4 < (i + 3) / 4; ++j4) {
;                     const f32x4 l4 = lr[j4];
;                     if (j4 * 4 + 0 < i) s0 -= l4[0] * Tc[j4 * 4 + 0];
;                     if (j4 * 4 + 1 < i) s1 -= l4[1] * Tc[j4 * 4 + 1];
;                     if (j4 * 4 + 2 < i) s2 -= l4[2] * Tc[j4 * 4 + 2];
;                     if (j4 * 4 + 3 < i) s3 -= l4[3] * Tc[j4 * 4 + 3];
;                 }
;                 Tc[i] = (s0 + s1) + (s2 + s3);
;             }
.LBB0_491:
	s_andn2_b64 vcc, exec, s[0:1]
	s_cbranch_vccnz .LBB0_499
	v_ashrrev_i32_e32 v32, 1, v67
	v_and_b32_e32 v34, 1, v67
	v_lshlrev_b32_e32 v33, 8, v32
	v_lshlrev_b32_e32 v35, 6, v34
	v_readlane_b32 s1, v255, 7
	v_lshlrev_b32_e32 v32, 6, v32
	s_add_i32 s2, 0, 0x25000
	v_add3_u32 v33, s1, v33, v35
	ds_read_b128 v[44:47], v33 offset:8192
	ds_read_b128 v[48:51], v33 offset:8208
	ds_read_b128 v[52:55], v33 offset:8224
	ds_read_b128 v[56:59], v33 offset:8240
	v_lshlrev_b32_e32 v34, 5, v34
	s_waitcnt lgkmcnt(3)
	v_cvt_pk_bf16_f32 v44, v44, v45
	v_cvt_pk_bf16_f32 v45, v46, v47
	s_waitcnt lgkmcnt(2)
	v_cvt_pk_bf16_f32 v46, v48, v49
	v_cvt_pk_bf16_f32 v47, v50, v51
	s_waitcnt lgkmcnt(1)
	v_cvt_pk_bf16_f32 v48, v52, v53
	v_cvt_pk_bf16_f32 v49, v54, v55
	s_waitcnt lgkmcnt(0)
	v_cvt_pk_bf16_f32 v50, v56, v57
	v_ashrrev_i32_e32 v36, 5, v67
	v_and_b32_e32 v33, 31, v67
	s_nop 0
	v_add3_u32 v32, s2, v32, v34
	s_movk_i32 s0, 0x2080
	v_cvt_pk_bf16_f32 v51, v58, v59
	ds_write_b128 v32, v[44:47]
	ds_write_b128 v32, v[48:51] offset:16
	v_mul_lo_u32 v32, v36, s0
	v_cmp_eq_u32_e32 vcc, 0, v33
	v_add_u32_e32 v49, s1, v32
	v_mov_b32_e32 v174, v49
	ds_read_b128 v[44:47], v174 offset:256
	v_mov_b64_e32 v[124:125], 0
	v_mov_b64_e32 v[126:127], 0
	v_mov_b64_e32 v[128:129], 0
	v_mov_b64_e32 v[130:131], 0
	v_mov_b64_e32 v[150:151], 0
	v_mov_b64_e32 v[152:153], 0
	v_mov_b64_e32 v[206:207], 0
	v_mov_b64_e32 v[208:209], 0
	v_mov_b64_e32 v[210:211], 0
	v_mov_b64_e32 v[212:213], 0
	v_mov_b64_e32 v[214:215], 0
	v_mov_b64_e32 v[216:217], 0
	v_mov_b64_e32 v[218:219], 0
	v_mov_b64_e32 v[220:221], 0
	v_mov_b64_e32 v[146:147], 0
	v_mov_b64_e32 v[172:173], 0
	v_cndmask_b32_e64 v124, 0, 1.0, vcc
	v_cmp_eq_u32_e32 vcc, 1, v33
	v_mov_b32_e32 v35, 0
	v_mov_b64_e32 v[38:39], 0
	v_cndmask_b32_e64 v34, 0, 1.0, vcc
	v_cmp_eq_u32_e32 vcc, 2, v33
	s_waitcnt lgkmcnt(0)
	v_pk_fma_f32 v[34:35], v[124:125], v[44:45], v[34:35] neg_lo:[1,0,0] neg_hi:[1,0,0]
	v_pk_fma_f32 v[38:39], v[126:127], v[46:47], v[38:39] neg_lo:[1,0,0] neg_hi:[1,0,0]
	ds_read_b128 v[44:47], v174 offset:512
	v_cndmask_b32_e64 v132, 0, 1.0, vcc
	v_mov_b32_e32 v133, 0
	v_mov_b64_e32 v[144:145], 0
	v_add_f32_e32 v122, v34, v35
	v_add_f32_e32 v123, v38, v39
	v_add_f32_e32 v125, v122, v123
	v_cmp_eq_u32_e32 vcc, 3, v33
	s_waitcnt lgkmcnt(0)
	v_pk_fma_f32 v[132:133], v[124:125], v[44:45], v[132:133] neg_lo:[1,0,0] neg_hi:[1,0,0]
	v_pk_fma_f32 v[144:145], v[126:127], v[46:47], v[144:145] neg_lo:[1,0,0] neg_hi:[1,0,0]
	ds_read_b128 v[44:47], v174 offset:768
	v_cndmask_b32_e64 v34, 0, 1.0, vcc
	v_mov_b32_e32 v35, 0
	v_mov_b64_e32 v[38:39], 0
	v_add_f32_e32 v122, v132, v133
	v_add_f32_e32 v123, v144, v145
	v_add_f32_e32 v126, v122, v123
	v_cmp_eq_u32_e32 vcc, 4, v33
	s_waitcnt lgkmcnt(0)
	v_pk_fma_f32 v[34:35], v[124:125], v[44:45], v[34:35] neg_lo:[1,0,0] neg_hi:[1,0,0]
	v_pk_fma_f32 v[38:39], v[126:127], v[46:47], v[38:39] neg_lo:[1,0,0] neg_hi:[1,0,0]
	ds_read_b128 v[44:47], v174 offset:1024
	v_cndmask_b32_e64 v132, 0, 1.0, vcc
	v_mov_b32_e32 v133, 0
	v_mov_b64_e32 v[144:145], 0
	v_add_f32_e32 v122, v34, v35
	v_add_f32_e32 v123, v38, v39
	v_add_f32_e32 v127, v122, v123
	ds_read_b128 v[48:51], v174 offset:1296
	v_cmp_eq_u32_e32 vcc, 5, v33
	s_waitcnt lgkmcnt(1)
	v_pk_fma_f32 v[132:133], v[124:125], v[44:45], v[132:133] neg_lo:[1,0,0] neg_hi:[1,0,0]
	v_pk_fma_f32 v[144:145], v[126:127], v[46:47], v[144:145] neg_lo:[1,0,0] neg_hi:[1,0,0]
	ds_read_b128 v[44:47], v174 offset:1280
	v_cndmask_b32_e64 v34, 0, 1.0, vcc
	v_mov_b32_e32 v35, 0
	v_mov_b64_e32 v[38:39], 0
	v_add_f32_e32 v122, v132, v133
	v_add_f32_e32 v123, v144, v145
	v_add_f32_e32 v128, v122, v123
	v_cmp_eq_u32_e32 vcc, 6, v33
	s_waitcnt lgkmcnt(0)
	v_pk_fma_f32 v[34:35], v[124:125], v[44:45], v[34:35] neg_lo:[1,0,0] neg_hi:[1,0,0]
	v_pk_fma_f32 v[38:39], v[126:127], v[46:47], v[38:39] neg_lo:[1,0,0] neg_hi:[1,0,0]
	ds_read_b128 v[44:47], v174 offset:1536
	v_cndmask_b32_e64 v132, 0, 1.0, vcc
	v_mov_b32_e32 v133, 0
	v_mov_b64_e32 v[144:145], 0
	s_waitcnt lgkmcnt(2)
	v_pk_fma_f32 v[34:35], v[128:129], v[48:49], v[34:35] neg_lo:[1,0,0] neg_hi:[1,0,0]
	v_pk_fma_f32 v[38:39], v[130:131], v[50:51], v[38:39] neg_lo:[1,0,0] neg_hi:[1,0,0]
	ds_read_b128 v[48:51], v174 offset:1552
	v_add_f32_e32 v122, v34, v35
	v_add_f32_e32 v123, v38, v39
	v_add_f32_e32 v129, v122, v123
	v_cmp_eq_u32_e32 vcc, 7, v33
	s_waitcnt lgkmcnt(1)
	v_pk_fma_f32 v[132:133], v[124:125], v[44:45], v[132:133] neg_lo:[1,0,0] neg_hi:[1,0,0]
	v_pk_fma_f32 v[144:145], v[126:127], v[46:47], v[144:145] neg_lo:[1,0,0] neg_hi:[1,0,0]
	ds_read_b128 v[44:47], v174 offset:1792
	v_cndmask_b32_e64 v34, 0, 1.0, vcc
	v_mov_b32_e32 v35, 0
	v_mov_b64_e32 v[38:39], 0
	s_waitcnt lgkmcnt(1)
	v_pk_fma_f32 v[132:133], v[128:129], v[48:49], v[132:133] neg_lo:[1,0,0] neg_hi:[1,0,0]
	v_pk_fma_f32 v[144:145], v[130:131], v[50:51], v[144:145] neg_lo:[1,0,0] neg_hi:[1,0,0]
	ds_read_b128 v[48:51], v174 offset:1808
	v_add_f32_e32 v122, v132, v133
	v_add_f32_e32 v123, v144, v145
	v_add_f32_e32 v130, v122, v123
	v_cmp_eq_u32_e32 vcc, 8, v33
	s_waitcnt lgkmcnt(1)
	v_pk_fma_f32 v[34:35], v[124:125], v[44:45], v[34:35] neg_lo:[1,0,0] neg_hi:[1,0,0]
	v_pk_fma_f32 v[38:39], v[126:127], v[46:47], v[38:39] neg_lo:[1,0,0] neg_hi:[1,0,0]
	ds_read_b128 v[44:47], v174 offset:2048
	v_cndmask_b32_e64 v132, 0, 1.0, vcc
	v_mov_b32_e32 v133, 0
	v_mov_b64_e32 v[144:145], 0
	s_waitcnt lgkmcnt(1)
	v_pk_fma_f32 v[34:35], v[128:129], v[48:49], v[34:35] neg_lo:[1,0,0] neg_hi:[1,0,0]
	v_pk_fma_f32 v[38:39], v[130:131], v[50:51], v[38:39] neg_lo:[1,0,0] neg_hi:[1,0,0]
	ds_read_b128 v[48:51], v174 offset:2064
	v_add_f32_e32 v122, v34, v35
	v_add_f32_e32 v123, v38, v39
	v_add_f32_e32 v131, v122, v123
	ds_read_b128 v[52:55], v174 offset:2336
	v_cmp_eq_u32_e32 vcc, 9, v33
	s_waitcnt lgkmcnt(2)
; #define LAS __attribute__((address_space(3)))
; DI void gdn_unit(const Params& P, bf16_t* proj, const float* gb, int b, int h, LAS unsigned char* lds) {
;     ...
;             const LAS float* Lblk = Lm + blk * (32 * 64 + 32);
;             float Tc[32];
; #pragma unroll
;             for (int i = 0; i < 32; ++i) {
;                 float s0 = (cl == i) ? 1.0f : 0.0f, s1 = 0.f, s2 = 0.f, s3 = 0.f;
;                 f32x4 lr[8];
; #pragma unroll
;                 for (int j4 = 0; j4 < (i + 3) / 4; ++j4) lr[j4] = *(const LAS f32x4*)(Lblk + i * 64 + j4 * 4);
;                 __builtin_amdgcn_sched_barrier(0);
; #pragma unroll
;                 for (int j4 = 0; j4 < (i + 3) / 4; ++j4) {
;                     const f32x4 l4 = lr[j4];
;                     if (j4 * 4 + 0 < i) s0 -= l4[0] * Tc[j4 * 4 + 0];
;                     if (j4 * 4 + 1 < i) s1 -= l4[1] * Tc[j4 * 4 + 1];
;                     if (j4 * 4 + 2 < i) s2 -= l4[2] * Tc[j4 * 4 + 2];
;                     if (j4 * 4 + 3 < i) s3 -= l4[3] * Tc[j4 * 4 + 3];
;                 }
;                 Tc[i] = (s0 + s1) + (s2 + s3);
;             }
	v_pk_fma_f32 v[132:133], v[124:125], v[44:45], v[132:133] neg_lo:[1,0,0] neg_hi:[1,0,0]
	v_pk_fma_f32 v[144:145], v[126:127], v[46:47], v[144:145] neg_lo:[1,0,0] neg_hi:[1,0,0]
	ds_read_b128 v[44:47], v174 offset:2304
	v_cndmask_b32_e64 v34, 0, 1.0, vcc
	v_mov_b32_e32 v35, 0
	v_mov_b64_e32 v[38:39], 0
	s_waitcnt lgkmcnt(2)
	v_pk_fma_f32 v[132:133], v[128:129], v[48:49], v[132:133] neg_lo:[1,0,0] neg_hi:[1,0,0]
	v_pk_fma_f32 v[144:145], v[130:131], v[50:51], v[144:145] neg_lo:[1,0,0] neg_hi:[1,0,0]
	ds_read_b128 v[48:51], v174 offset:2320
	v_add_f32_e32 v122, v132, v133
	v_add_f32_e32 v123, v144, v145
	v_add_f32_e32 v150, v122, v123
	v_cmp_eq_u32_e32 vcc, 10, v33
	s_waitcnt lgkmcnt(1)
	v_pk_fma_f32 v[34:35], v[124:125], v[44:45], v[34:35] neg_lo:[1,0,0] neg_hi:[1,0,0]
	v_pk_fma_f32 v[38:39], v[126:127], v[46:47], v[38:39] neg_lo:[1,0,0] neg_hi:[1,0,0]
	ds_read_b128 v[44:47], v174 offset:2560
	v_cndmask_b32_e64 v132, 0, 1.0, vcc
	v_mov_b32_e32 v133, 0
	v_mov_b64_e32 v[144:145], 0
	s_waitcnt lgkmcnt(1)
	v_pk_fma_f32 v[34:35], v[128:129], v[48:49], v[34:35] neg_lo:[1,0,0] neg_hi:[1,0,0]
	v_pk_fma_f32 v[38:39], v[130:131], v[50:51], v[38:39] neg_lo:[1,0,0] neg_hi:[1,0,0]
	ds_read_b128 v[48:51], v174 offset:2576
	s_waitcnt lgkmcnt(4)
	v_pk_fma_f32 v[34:35], v[150:151], v[52:53], v[34:35] neg_lo:[1,0,0] neg_hi:[1,0,0]
	v_pk_fma_f32 v[38:39], v[152:153], v[54:55], v[38:39] neg_lo:[1,0,0] neg_hi:[1,0,0]
	ds_read_b128 v[52:55], v174 offset:2592
	v_add_f32_e32 v122, v34, v35
	v_add_f32_e32 v123, v38, v39
	v_add_f32_e32 v151, v122, v123
	v_cmp_eq_u32_e32 vcc, 11, v33
	s_waitcnt lgkmcnt(2)
	v_pk_fma_f32 v[132:133], v[124:125], v[44:45], v[132:133] neg_lo:[1,0,0] neg_hi:[1,0,0]
	v_pk_fma_f32 v[144:145], v[126:127], v[46:47], v[144:145] neg_lo:[1,0,0] neg_hi:[1,0,0]
	ds_read_b128 v[44:47], v174 offset:2816
	v_cndmask_b32_e64 v34, 0, 1.0, vcc
	v_mov_b32_e32 v35, 0
	v_mov_b64_e32 v[38:39], 0
	s_waitcnt lgkmcnt(2)
	v_pk_fma_f32 v[132:133], v[128:129], v[48:49], v[132:133] neg_lo:[1,0,0] neg_hi:[1,0,0]
	v_pk_fma_f32 v[144:145], v[130:131], v[50:51], v[144:145] neg_lo:[1,0,0] neg_hi:[1,0,0]
	ds_read_b128 v[48:51], v174 offset:2832
	s_waitcnt lgkmcnt(2)
	v_pk_fma_f32 v[132:133], v[150:151], v[52:53], v[132:133] neg_lo:[1,0,0] neg_hi:[1,0,0]
	v_pk_fma_f32 v[144:145], v[152:153], v[54:55], v[144:145] neg_lo:[1,0,0] neg_hi:[1,0,0]
	ds_read_b128 v[52:55], v174 offset:2848
	v_add_f32_e32 v122, v132, v133
	v_add_f32_e32 v123, v144, v145
	v_add_f32_e32 v152, v122, v123
	v_cmp_eq_u32_e32 vcc, 12, v33
	s_waitcnt lgkmcnt(2)
	v_pk_fma_f32 v[34:35], v[124:125], v[44:45], v[34:35] neg_lo:[1,0,0] neg_hi:[1,0,0]
	v_pk_fma_f32 v[38:39], v[126:127], v[46:47], v[38:39] neg_lo:[1,0,0] neg_hi:[1,0,0]
	ds_read_b128 v[44:47], v174 offset:3072
	v_cndmask_b32_e64 v132, 0, 1.0, vcc
	v_mov_b32_e32 v133, 0
	v_mov_b64_e32 v[144:145], 0
	s_waitcnt lgkmcnt(2)
	v_pk_fma_f32 v[34:35], v[128:129], v[48:49], v[34:35] neg_lo:[1,0,0] neg_hi:[1,0,0]
	v_pk_fma_f32 v[38:39], v[130:131], v[50:51], v[38:39] neg_lo:[1,0,0] neg_hi:[1,0,0]
	ds_read_b128 v[48:51], v174 offset:3088
	s_waitcnt lgkmcnt(2)
	v_pk_fma_f32 v[34:35], v[150:151], v[52:53], v[34:35] neg_lo:[1,0,0] neg_hi:[1,0,0]
	v_pk_fma_f32 v[38:39], v[152:153], v[54:55], v[38:39] neg_lo:[1,0,0] neg_hi:[1,0,0]
	ds_read_b128 v[52:55], v174 offset:3104
	v_add_f32_e32 v122, v34, v35
	v_add_f32_e32 v123, v38, v39
	v_add_f32_e32 v153, v122, v123
	ds_read_b128 v[56:59], v174 offset:3376
	v_cmp_eq_u32_e32 vcc, 13, v33
	s_waitcnt lgkmcnt(3)
	v_pk_fma_f32 v[132:133], v[124:125], v[44:45], v[132:133] neg_lo:[1,0,0] neg_hi:[1,0,0]
	v_pk_fma_f32 v[144:145], v[126:127], v[46:47], v[144:145] neg_lo:[1,0,0] neg_hi:[1,0,0]
	ds_read_b128 v[44:47], v174 offset:3328
	v_cndmask_b32_e64 v34, 0, 1.0, vcc
	v_mov_b32_e32 v35, 0
	v_mov_b64_e32 v[38:39], 0
	s_waitcnt lgkmcnt(3)
	v_pk_fma_f32 v[132:133], v[128:129], v[48:49], v[132:133] neg_lo:[1,0,0] neg_hi:[1,0,0]
	v_pk_fma_f32 v[144:145], v[130:131], v[50:51], v[144:145] neg_lo:[1,0,0] neg_hi:[1,0,0]
	ds_read_b128 v[48:51], v174 offset:3344
	s_waitcnt lgkmcnt(3)
	v_pk_fma_f32 v[132:133], v[150:151], v[52:53], v[132:133] neg_lo:[1,0,0] neg_hi:[1,0,0]
	v_pk_fma_f32 v[144:145], v[152:153], v[54:55], v[144:145] neg_lo:[1,0,0] neg_hi:[1,0,0]
	ds_read_b128 v[52:55], v174 offset:3360
	v_add_f32_e32 v122, v132, v133
	v_add_f32_e32 v123, v144, v145
	v_add_f32_e32 v206, v122, v123
	v_cmp_eq_u32_e32 vcc, 14, v33
	s_waitcnt lgkmcnt(2)
	v_pk_fma_f32 v[34:35], v[124:125], v[44:45], v[34:35] neg_lo:[1,0,0] neg_hi:[1,0,0]
	v_pk_fma_f32 v[38:39], v[126:127], v[46:47], v[38:39] neg_lo:[1,0,0] neg_hi:[1,0,0]
	ds_read_b128 v[44:47], v174 offset:3584
	v_cndmask_b32_e64 v132, 0, 1.0, vcc
	v_mov_b32_e32 v133, 0
	v_mov_b64_e32 v[144:145], 0
	s_waitcnt lgkmcnt(2)
	v_pk_fma_f32 v[34:35], v[128:129], v[48:49], v[34:35] neg_lo:[1,0,0] neg_hi:[1,0,0]
	v_pk_fma_f32 v[38:39], v[130:131], v[50:51], v[38:39] neg_lo:[1,0,0] neg_hi:[1,0,0]
	ds_read_b128 v[48:51], v174 offset:3600
	s_waitcnt lgkmcnt(2)
	v_pk_fma_f32 v[34:35], v[150:151], v[52:53], v[34:35] neg_lo:[1,0,0] neg_hi:[1,0,0]
	v_pk_fma_f32 v[38:39], v[152:153], v[54:55], v[38:39] neg_lo:[1,0,0] neg_hi:[1,0,0]
	ds_read_b128 v[52:55], v174 offset:3616
	s_waitcnt lgkmcnt(6)
	v_pk_fma_f32 v[34:35], v[206:207], v[56:57], v[34:35] neg_lo:[1,0,0] neg_hi:[1,0,0]
	v_pk_fma_f32 v[38:39], v[208:209], v[58:59], v[38:39] neg_lo:[1,0,0] neg_hi:[1,0,0]
	ds_read_b128 v[56:59], v174 offset:3632
	v_add_f32_e32 v122, v34, v35
	v_add_f32_e32 v123, v38, v39
	v_add_f32_e32 v207, v122, v123
	v_cmp_eq_u32_e32 vcc, 15, v33
	s_waitcnt lgkmcnt(3)
; #define LAS __attribute__((address_space(3)))
; DI void gdn_unit(const Params& P, bf16_t* proj, const float* gb, int b, int h, LAS unsigned char* lds) {
;     ...
;             const LAS float* Lblk = Lm + blk * (32 * 64 + 32);
;             float Tc[32];
; #pragma unroll
;             for (int i = 0; i < 32; ++i) {
;                 float s0 = (cl == i) ? 1.0f : 0.0f, s1 = 0.f, s2 = 0.f, s3 = 0.f;
;                 f32x4 lr[8];
; #pragma unroll
;                 for (int j4 = 0; j4 < (i + 3) / 4; ++j4) lr[j4] = *(const LAS f32x4*)(Lblk + i * 64 + j4 * 4);
;                 __builtin_amdgcn_sched_barrier(0);
; #pragma unroll
;                 for (int j4 = 0; j4 < (i + 3) / 4; ++j4) {
;                     const f32x4 l4 = lr[j4];
;                     if (j4 * 4 + 0 < i) s0 -= l4[0] * Tc[j4 * 4 + 0];
;                     if (j4 * 4 + 1 < i) s1 -= l4[1] * Tc[j4 * 4 + 1];
;                     if (j4 * 4 + 2 < i) s2 -= l4[2] * Tc[j4 * 4 + 2];
;                     if (j4 * 4 + 3 < i) s3 -= l4[3] * Tc[j4 * 4 + 3];
;                 }
;                 Tc[i] = (s0 + s1) + (s2 + s3);
;             }
	v_pk_fma_f32 v[132:133], v[124:125], v[44:45], v[132:133] neg_lo:[1,0,0] neg_hi:[1,0,0]
	v_pk_fma_f32 v[144:145], v[126:127], v[46:47], v[144:145] neg_lo:[1,0,0] neg_hi:[1,0,0]
	ds_read_b128 v[44:47], v174 offset:3840
	v_cndmask_b32_e64 v34, 0, 1.0, vcc
	v_mov_b32_e32 v35, 0
	v_mov_b64_e32 v[38:39], 0
	s_waitcnt lgkmcnt(3)
	v_pk_fma_f32 v[132:133], v[128:129], v[48:49], v[132:133] neg_lo:[1,0,0] neg_hi:[1,0,0]
	v_pk_fma_f32 v[144:145], v[130:131], v[50:51], v[144:145] neg_lo:[1,0,0] neg_hi:[1,0,0]
	ds_read_b128 v[48:51], v174 offset:3856
	s_waitcnt lgkmcnt(3)
	v_pk_fma_f32 v[132:133], v[150:151], v[52:53], v[132:133] neg_lo:[1,0,0] neg_hi:[1,0,0]
	v_pk_fma_f32 v[144:145], v[152:153], v[54:55], v[144:145] neg_lo:[1,0,0] neg_hi:[1,0,0]
	ds_read_b128 v[52:55], v174 offset:3872
	s_waitcnt lgkmcnt(3)
	v_pk_fma_f32 v[132:133], v[206:207], v[56:57], v[132:133] neg_lo:[1,0,0] neg_hi:[1,0,0]
	v_pk_fma_f32 v[144:145], v[208:209], v[58:59], v[144:145] neg_lo:[1,0,0] neg_hi:[1,0,0]
	ds_read_b128 v[56:59], v174 offset:3888
	v_add_f32_e32 v122, v132, v133
	v_add_f32_e32 v123, v144, v145
	v_add_f32_e32 v208, v122, v123
	v_cmp_eq_u32_e32 vcc, 16, v33
	s_waitcnt lgkmcnt(3)
	v_pk_fma_f32 v[34:35], v[124:125], v[44:45], v[34:35] neg_lo:[1,0,0] neg_hi:[1,0,0]
	v_pk_fma_f32 v[38:39], v[126:127], v[46:47], v[38:39] neg_lo:[1,0,0] neg_hi:[1,0,0]
	ds_read_b128 v[44:47], v174 offset:4096
	v_cndmask_b32_e64 v132, 0, 1.0, vcc
	v_mov_b32_e32 v133, 0
	v_mov_b64_e32 v[144:145], 0
	s_waitcnt lgkmcnt(3)
	v_pk_fma_f32 v[34:35], v[128:129], v[48:49], v[34:35] neg_lo:[1,0,0] neg_hi:[1,0,0]
	v_pk_fma_f32 v[38:39], v[130:131], v[50:51], v[38:39] neg_lo:[1,0,0] neg_hi:[1,0,0]
	ds_read_b128 v[48:51], v174 offset:4112
	s_waitcnt lgkmcnt(3)
	v_pk_fma_f32 v[34:35], v[150:151], v[52:53], v[34:35] neg_lo:[1,0,0] neg_hi:[1,0,0]
	v_pk_fma_f32 v[38:39], v[152:153], v[54:55], v[38:39] neg_lo:[1,0,0] neg_hi:[1,0,0]
	ds_read_b128 v[52:55], v174 offset:4128
	s_waitcnt lgkmcnt(3)
	v_pk_fma_f32 v[34:35], v[206:207], v[56:57], v[34:35] neg_lo:[1,0,0] neg_hi:[1,0,0]
	v_pk_fma_f32 v[38:39], v[208:209], v[58:59], v[38:39] neg_lo:[1,0,0] neg_hi:[1,0,0]
	ds_read_b128 v[56:59], v174 offset:4144
	v_add_f32_e32 v122, v34, v35
	v_add_f32_e32 v123, v38, v39
	v_add_f32_e32 v209, v122, v123
	ds_read_b128 v[62:65], v174 offset:4416
	v_cmp_eq_u32_e32 vcc, 17, v33
	s_waitcnt lgkmcnt(4)
	v_pk_fma_f32 v[132:133], v[124:125], v[44:45], v[132:133] neg_lo:[1,0,0] neg_hi:[1,0,0]
	v_pk_fma_f32 v[144:145], v[126:127], v[46:47], v[144:145] neg_lo:[1,0,0] neg_hi:[1,0,0]
	ds_read_b128 v[44:47], v174 offset:4352
	v_cndmask_b32_e64 v34, 0, 1.0, vcc
	v_mov_b32_e32 v35, 0
	v_mov_b64_e32 v[38:39], 0
	s_waitcnt lgkmcnt(4)
	v_pk_fma_f32 v[132:133], v[128:129], v[48:49], v[132:133] neg_lo:[1,0,0] neg_hi:[1,0,0]
	v_pk_fma_f32 v[144:145], v[130:131], v[50:51], v[144:145] neg_lo:[1,0,0] neg_hi:[1,0,0]
	ds_read_b128 v[48:51], v174 offset:4368
	s_waitcnt lgkmcnt(4)
	v_pk_fma_f32 v[132:133], v[150:151], v[52:53], v[132:133] neg_lo:[1,0,0] neg_hi:[1,0,0]
	v_pk_fma_f32 v[144:145], v[152:153], v[54:55], v[144:145] neg_lo:[1,0,0] neg_hi:[1,0,0]
	ds_read_b128 v[52:55], v174 offset:4384
	s_waitcnt lgkmcnt(4)
	v_pk_fma_f32 v[132:133], v[206:207], v[56:57], v[132:133] neg_lo:[1,0,0] neg_hi:[1,0,0]
	v_pk_fma_f32 v[144:145], v[208:209], v[58:59], v[144:145] neg_lo:[1,0,0] neg_hi:[1,0,0]
	ds_read_b128 v[56:59], v174 offset:4400
	v_add_f32_e32 v122, v132, v133
	v_add_f32_e32 v123, v144, v145
	v_add_f32_e32 v210, v122, v123
	v_cmp_eq_u32_e32 vcc, 18, v33
	s_waitcnt lgkmcnt(3)
	v_pk_fma_f32 v[34:35], v[124:125], v[44:45], v[34:35] neg_lo:[1,0,0] neg_hi:[1,0,0]
	v_pk_fma_f32 v[38:39], v[126:127], v[46:47], v[38:39] neg_lo:[1,0,0] neg_hi:[1,0,0]
	ds_read_b128 v[44:47], v174 offset:4608
	v_cndmask_b32_e64 v132, 0, 1.0, vcc
	v_mov_b32_e32 v133, 0
	v_mov_b64_e32 v[144:145], 0
	s_waitcnt lgkmcnt(3)
	v_pk_fma_f32 v[34:35], v[128:129], v[48:49], v[34:35] neg_lo:[1,0,0] neg_hi:[1,0,0]
	v_pk_fma_f32 v[38:39], v[130:131], v[50:51], v[38:39] neg_lo:[1,0,0] neg_hi:[1,0,0]
	ds_read_b128 v[48:51], v174 offset:4624
	s_waitcnt lgkmcnt(3)
	v_pk_fma_f32 v[34:35], v[150:151], v[52:53], v[34:35] neg_lo:[1,0,0] neg_hi:[1,0,0]
	v_pk_fma_f32 v[38:39], v[152:153], v[54:55], v[38:39] neg_lo:[1,0,0] neg_hi:[1,0,0]
	ds_read_b128 v[52:55], v174 offset:4640
	s_waitcnt lgkmcnt(3)
	v_pk_fma_f32 v[34:35], v[206:207], v[56:57], v[34:35] neg_lo:[1,0,0] neg_hi:[1,0,0]
	v_pk_fma_f32 v[38:39], v[208:209], v[58:59], v[38:39] neg_lo:[1,0,0] neg_hi:[1,0,0]
	ds_read_b128 v[56:59], v174 offset:4656
	s_waitcnt lgkmcnt(8)
	v_pk_fma_f32 v[34:35], v[210:211], v[62:63], v[34:35] neg_lo:[1,0,0] neg_hi:[1,0,0]
	v_pk_fma_f32 v[38:39], v[212:213], v[64:65], v[38:39] neg_lo:[1,0,0] neg_hi:[1,0,0]
	ds_read_b128 v[62:65], v174 offset:4672
	v_add_f32_e32 v122, v34, v35
	v_add_f32_e32 v123, v38, v39
	v_add_f32_e32 v211, v122, v123
	v_cmp_eq_u32_e32 vcc, 19, v33
	s_waitcnt lgkmcnt(4)
	v_pk_fma_f32 v[132:133], v[124:125], v[44:45], v[132:133] neg_lo:[1,0,0] neg_hi:[1,0,0]
	v_pk_fma_f32 v[144:145], v[126:127], v[46:47], v[144:145] neg_lo:[1,0,0] neg_hi:[1,0,0]
	ds_read_b128 v[44:47], v174 offset:4864
	v_cndmask_b32_e64 v34, 0, 1.0, vcc
	v_mov_b32_e32 v35, 0
	v_mov_b64_e32 v[38:39], 0
	s_waitcnt lgkmcnt(4)
	v_pk_fma_f32 v[132:133], v[128:129], v[48:49], v[132:133] neg_lo:[1,0,0] neg_hi:[1,0,0]
	v_pk_fma_f32 v[144:145], v[130:131], v[50:51], v[144:145] neg_lo:[1,0,0] neg_hi:[1,0,0]
	ds_read_b128 v[48:51], v174 offset:4880
	s_waitcnt lgkmcnt(4)
	v_pk_fma_f32 v[132:133], v[150:151], v[52:53], v[132:133] neg_lo:[1,0,0] neg_hi:[1,0,0]
	v_pk_fma_f32 v[144:145], v[152:153], v[54:55], v[144:145] neg_lo:[1,0,0] neg_hi:[1,0,0]
	ds_read_b128 v[52:55], v174 offset:4896
	s_waitcnt lgkmcnt(4)
; #define LAS __attribute__((address_space(3)))
; DI void gdn_unit(const Params& P, bf16_t* proj, const float* gb, int b, int h, LAS unsigned char* lds) {
;     ...
;             const LAS float* Lblk = Lm + blk * (32 * 64 + 32);
;             float Tc[32];
; #pragma unroll
;             for (int i = 0; i < 32; ++i) {
;                 float s0 = (cl == i) ? 1.0f : 0.0f, s1 = 0.f, s2 = 0.f, s3 = 0.f;
;                 f32x4 lr[8];
; #pragma unroll
;                 for (int j4 = 0; j4 < (i + 3) / 4; ++j4) lr[j4] = *(const LAS f32x4*)(Lblk + i * 64 + j4 * 4);
;                 __builtin_amdgcn_sched_barrier(0);
; #pragma unroll
;                 for (int j4 = 0; j4 < (i + 3) / 4; ++j4) {
;                     const f32x4 l4 = lr[j4];
;                     if (j4 * 4 + 0 < i) s0 -= l4[0] * Tc[j4 * 4 + 0];
;                     if (j4 * 4 + 1 < i) s1 -= l4[1] * Tc[j4 * 4 + 1];
;                     if (j4 * 4 + 2 < i) s2 -= l4[2] * Tc[j4 * 4 + 2];
;                     if (j4 * 4 + 3 < i) s3 -= l4[3] * Tc[j4 * 4 + 3];
;                 }
;                 Tc[i] = (s0 + s1) + (s2 + s3);
;             }
	v_pk_fma_f32 v[132:133], v[206:207], v[56:57], v[132:133] neg_lo:[1,0,0] neg_hi:[1,0,0]
	v_pk_fma_f32 v[144:145], v[208:209], v[58:59], v[144:145] neg_lo:[1,0,0] neg_hi:[1,0,0]
	ds_read_b128 v[56:59], v174 offset:4912
	s_waitcnt lgkmcnt(4)
	v_pk_fma_f32 v[132:133], v[210:211], v[62:63], v[132:133] neg_lo:[1,0,0] neg_hi:[1,0,0]
	v_pk_fma_f32 v[144:145], v[212:213], v[64:65], v[144:145] neg_lo:[1,0,0] neg_hi:[1,0,0]
	ds_read_b128 v[62:65], v174 offset:4928
	v_add_f32_e32 v122, v132, v133
	v_add_f32_e32 v123, v144, v145
	v_add_f32_e32 v212, v122, v123
	v_cmp_eq_u32_e32 vcc, 20, v33
	s_waitcnt lgkmcnt(4)
	v_pk_fma_f32 v[34:35], v[124:125], v[44:45], v[34:35] neg_lo:[1,0,0] neg_hi:[1,0,0]
	v_pk_fma_f32 v[38:39], v[126:127], v[46:47], v[38:39] neg_lo:[1,0,0] neg_hi:[1,0,0]
	ds_read_b128 v[44:47], v174 offset:5120
	v_cndmask_b32_e64 v132, 0, 1.0, vcc
	v_mov_b32_e32 v133, 0
	v_mov_b64_e32 v[144:145], 0
	s_waitcnt lgkmcnt(4)
	v_pk_fma_f32 v[34:35], v[128:129], v[48:49], v[34:35] neg_lo:[1,0,0] neg_hi:[1,0,0]
	v_pk_fma_f32 v[38:39], v[130:131], v[50:51], v[38:39] neg_lo:[1,0,0] neg_hi:[1,0,0]
	ds_read_b128 v[48:51], v174 offset:5136
	s_waitcnt lgkmcnt(4)
	v_pk_fma_f32 v[34:35], v[150:151], v[52:53], v[34:35] neg_lo:[1,0,0] neg_hi:[1,0,0]
	v_pk_fma_f32 v[38:39], v[152:153], v[54:55], v[38:39] neg_lo:[1,0,0] neg_hi:[1,0,0]
	ds_read_b128 v[52:55], v174 offset:5152
	s_waitcnt lgkmcnt(4)
	v_pk_fma_f32 v[34:35], v[206:207], v[56:57], v[34:35] neg_lo:[1,0,0] neg_hi:[1,0,0]
	v_pk_fma_f32 v[38:39], v[208:209], v[58:59], v[38:39] neg_lo:[1,0,0] neg_hi:[1,0,0]
	ds_read_b128 v[56:59], v174 offset:5168
	s_waitcnt lgkmcnt(4)
	v_pk_fma_f32 v[34:35], v[210:211], v[62:63], v[34:35] neg_lo:[1,0,0] neg_hi:[1,0,0]
	v_pk_fma_f32 v[38:39], v[212:213], v[64:65], v[38:39] neg_lo:[1,0,0] neg_hi:[1,0,0]
	ds_read_b128 v[62:65], v174 offset:5184
	v_add_f32_e32 v122, v34, v35
	v_add_f32_e32 v123, v38, v39
	v_add_f32_e32 v213, v122, v123
	ds_read_b128 v[114:117], v174 offset:5456
	v_cmp_eq_u32_e32 vcc, 21, v33
	s_waitcnt lgkmcnt(5)
	v_pk_fma_f32 v[132:133], v[124:125], v[44:45], v[132:133] neg_lo:[1,0,0] neg_hi:[1,0,0]
	v_pk_fma_f32 v[144:145], v[126:127], v[46:47], v[144:145] neg_lo:[1,0,0] neg_hi:[1,0,0]
	ds_read_b128 v[44:47], v174 offset:5376
	v_cndmask_b32_e64 v34, 0, 1.0, vcc
	v_mov_b32_e32 v35, 0
	v_mov_b64_e32 v[38:39], 0
	s_waitcnt lgkmcnt(5)
	v_pk_fma_f32 v[132:133], v[128:129], v[48:49], v[132:133] neg_lo:[1,0,0] neg_hi:[1,0,0]
	v_pk_fma_f32 v[144:145], v[130:131], v[50:51], v[144:145] neg_lo:[1,0,0] neg_hi:[1,0,0]
	ds_read_b128 v[48:51], v174 offset:5392
	s_waitcnt lgkmcnt(5)
	v_pk_fma_f32 v[132:133], v[150:151], v[52:53], v[132:133] neg_lo:[1,0,0] neg_hi:[1,0,0]
	v_pk_fma_f32 v[144:145], v[152:153], v[54:55], v[144:145] neg_lo:[1,0,0] neg_hi:[1,0,0]
	ds_read_b128 v[52:55], v174 offset:5408
	s_waitcnt lgkmcnt(5)
	v_pk_fma_f32 v[132:133], v[206:207], v[56:57], v[132:133] neg_lo:[1,0,0] neg_hi:[1,0,0]
	v_pk_fma_f32 v[144:145], v[208:209], v[58:59], v[144:145] neg_lo:[1,0,0] neg_hi:[1,0,0]
	ds_read_b128 v[56:59], v174 offset:5424
	s_waitcnt lgkmcnt(5)
	v_pk_fma_f32 v[132:133], v[210:211], v[62:63], v[132:133] neg_lo:[1,0,0] neg_hi:[1,0,0]
	v_pk_fma_f32 v[144:145], v[212:213], v[64:65], v[144:145] neg_lo:[1,0,0] neg_hi:[1,0,0]
	ds_read_b128 v[62:65], v174 offset:5440
	v_add_f32_e32 v122, v132, v133
	v_add_f32_e32 v123, v144, v145
	v_add_f32_e32 v214, v122, v123
	v_cmp_eq_u32_e32 vcc, 22, v33
	s_waitcnt lgkmcnt(4)
	v_pk_fma_f32 v[34:35], v[124:125], v[44:45], v[34:35] neg_lo:[1,0,0] neg_hi:[1,0,0]
	v_pk_fma_f32 v[38:39], v[126:127], v[46:47], v[38:39] neg_lo:[1,0,0] neg_hi:[1,0,0]
	ds_read_b128 v[44:47], v174 offset:5632
	v_cndmask_b32_e64 v132, 0, 1.0, vcc
	v_mov_b32_e32 v133, 0
	v_mov_b64_e32 v[144:145], 0
	s_waitcnt lgkmcnt(4)
	v_pk_fma_f32 v[34:35], v[128:129], v[48:49], v[34:35] neg_lo:[1,0,0] neg_hi:[1,0,0]
	v_pk_fma_f32 v[38:39], v[130:131], v[50:51], v[38:39] neg_lo:[1,0,0] neg_hi:[1,0,0]
	ds_read_b128 v[48:51], v174 offset:5648
	s_waitcnt lgkmcnt(4)
	v_pk_fma_f32 v[34:35], v[150:151], v[52:53], v[34:35] neg_lo:[1,0,0] neg_hi:[1,0,0]
	v_pk_fma_f32 v[38:39], v[152:153], v[54:55], v[38:39] neg_lo:[1,0,0] neg_hi:[1,0,0]
	ds_read_b128 v[52:55], v174 offset:5664
	s_waitcnt lgkmcnt(4)
	v_pk_fma_f32 v[34:35], v[206:207], v[56:57], v[34:35] neg_lo:[1,0,0] neg_hi:[1,0,0]
	v_pk_fma_f32 v[38:39], v[208:209], v[58:59], v[38:39] neg_lo:[1,0,0] neg_hi:[1,0,0]
	ds_read_b128 v[56:59], v174 offset:5680
	s_waitcnt lgkmcnt(4)
	v_pk_fma_f32 v[34:35], v[210:211], v[62:63], v[34:35] neg_lo:[1,0,0] neg_hi:[1,0,0]
	v_pk_fma_f32 v[38:39], v[212:213], v[64:65], v[38:39] neg_lo:[1,0,0] neg_hi:[1,0,0]
	ds_read_b128 v[62:65], v174 offset:5696
	s_waitcnt lgkmcnt(10)
	v_pk_fma_f32 v[34:35], v[214:215], v[114:115], v[34:35] neg_lo:[1,0,0] neg_hi:[1,0,0]
	v_pk_fma_f32 v[38:39], v[216:217], v[116:117], v[38:39] neg_lo:[1,0,0] neg_hi:[1,0,0]
	ds_read_b128 v[114:117], v174 offset:5712
	v_add_f32_e32 v122, v34, v35
	v_add_f32_e32 v123, v38, v39
	v_add_f32_e32 v215, v122, v123
	v_cmp_eq_u32_e32 vcc, 23, v33
	s_waitcnt lgkmcnt(5)
	v_pk_fma_f32 v[132:133], v[124:125], v[44:45], v[132:133] neg_lo:[1,0,0] neg_hi:[1,0,0]
	v_pk_fma_f32 v[144:145], v[126:127], v[46:47], v[144:145] neg_lo:[1,0,0] neg_hi:[1,0,0]
	ds_read_b128 v[44:47], v174 offset:5888
	v_cndmask_b32_e64 v34, 0, 1.0, vcc
	v_mov_b32_e32 v35, 0
	v_mov_b64_e32 v[38:39], 0
	s_waitcnt lgkmcnt(5)
	v_pk_fma_f32 v[132:133], v[128:129], v[48:49], v[132:133] neg_lo:[1,0,0] neg_hi:[1,0,0]
	v_pk_fma_f32 v[144:145], v[130:131], v[50:51], v[144:145] neg_lo:[1,0,0] neg_hi:[1,0,0]
	ds_read_b128 v[48:51], v174 offset:5904
	s_waitcnt lgkmcnt(5)
; #define LAS __attribute__((address_space(3)))
; DI void gdn_unit(const Params& P, bf16_t* proj, const float* gb, int b, int h, LAS unsigned char* lds) {
;     ...
;             const LAS float* Lblk = Lm + blk * (32 * 64 + 32);
;             float Tc[32];
; #pragma unroll
;             for (int i = 0; i < 32; ++i) {
;                 float s0 = (cl == i) ? 1.0f : 0.0f, s1 = 0.f, s2 = 0.f, s3 = 0.f;
;                 f32x4 lr[8];
; #pragma unroll
;                 for (int j4 = 0; j4 < (i + 3) / 4; ++j4) lr[j4] = *(const LAS f32x4*)(Lblk + i * 64 + j4 * 4);
;                 __builtin_amdgcn_sched_barrier(0);
; #pragma unroll
;                 for (int j4 = 0; j4 < (i + 3) / 4; ++j4) {
;                     const f32x4 l4 = lr[j4];
;                     if (j4 * 4 + 0 < i) s0 -= l4[0] * Tc[j4 * 4 + 0];
;                     if (j4 * 4 + 1 < i) s1 -= l4[1] * Tc[j4 * 4 + 1];
;                     if (j4 * 4 + 2 < i) s2 -= l4[2] * Tc[j4 * 4 + 2];
;                     if (j4 * 4 + 3 < i) s3 -= l4[3] * Tc[j4 * 4 + 3];
;                 }
;                 Tc[i] = (s0 + s1) + (s2 + s3);
;             }
	v_pk_fma_f32 v[132:133], v[150:151], v[52:53], v[132:133] neg_lo:[1,0,0] neg_hi:[1,0,0]
	v_pk_fma_f32 v[144:145], v[152:153], v[54:55], v[144:145] neg_lo:[1,0,0] neg_hi:[1,0,0]
	ds_read_b128 v[52:55], v174 offset:5920
	s_waitcnt lgkmcnt(5)
	v_pk_fma_f32 v[132:133], v[206:207], v[56:57], v[132:133] neg_lo:[1,0,0] neg_hi:[1,0,0]
	v_pk_fma_f32 v[144:145], v[208:209], v[58:59], v[144:145] neg_lo:[1,0,0] neg_hi:[1,0,0]
	ds_read_b128 v[56:59], v174 offset:5936
	s_waitcnt lgkmcnt(5)
	v_pk_fma_f32 v[132:133], v[210:211], v[62:63], v[132:133] neg_lo:[1,0,0] neg_hi:[1,0,0]
	v_pk_fma_f32 v[144:145], v[212:213], v[64:65], v[144:145] neg_lo:[1,0,0] neg_hi:[1,0,0]
	ds_read_b128 v[62:65], v174 offset:5952
	s_waitcnt lgkmcnt(5)
	v_pk_fma_f32 v[132:133], v[214:215], v[114:115], v[132:133] neg_lo:[1,0,0] neg_hi:[1,0,0]
	v_pk_fma_f32 v[144:145], v[216:217], v[116:117], v[144:145] neg_lo:[1,0,0] neg_hi:[1,0,0]
	ds_read_b128 v[114:117], v174 offset:5968
	v_add_f32_e32 v122, v132, v133
	v_add_f32_e32 v123, v144, v145
	v_add_f32_e32 v216, v122, v123
	v_cmp_eq_u32_e32 vcc, 24, v33
	s_waitcnt lgkmcnt(5)
	v_pk_fma_f32 v[34:35], v[124:125], v[44:45], v[34:35] neg_lo:[1,0,0] neg_hi:[1,0,0]
	v_pk_fma_f32 v[38:39], v[126:127], v[46:47], v[38:39] neg_lo:[1,0,0] neg_hi:[1,0,0]
	ds_read_b128 v[44:47], v174 offset:6144
	v_cndmask_b32_e64 v132, 0, 1.0, vcc
	v_mov_b32_e32 v133, 0
	v_mov_b64_e32 v[144:145], 0
	s_waitcnt lgkmcnt(5)
	v_pk_fma_f32 v[34:35], v[128:129], v[48:49], v[34:35] neg_lo:[1,0,0] neg_hi:[1,0,0]
	v_pk_fma_f32 v[38:39], v[130:131], v[50:51], v[38:39] neg_lo:[1,0,0] neg_hi:[1,0,0]
	ds_read_b128 v[48:51], v174 offset:6160
	s_waitcnt lgkmcnt(5)
	v_pk_fma_f32 v[34:35], v[150:151], v[52:53], v[34:35] neg_lo:[1,0,0] neg_hi:[1,0,0]
	v_pk_fma_f32 v[38:39], v[152:153], v[54:55], v[38:39] neg_lo:[1,0,0] neg_hi:[1,0,0]
	ds_read_b128 v[52:55], v174 offset:6176
	s_waitcnt lgkmcnt(5)
	v_pk_fma_f32 v[34:35], v[206:207], v[56:57], v[34:35] neg_lo:[1,0,0] neg_hi:[1,0,0]
	v_pk_fma_f32 v[38:39], v[208:209], v[58:59], v[38:39] neg_lo:[1,0,0] neg_hi:[1,0,0]
	ds_read_b128 v[56:59], v174 offset:6192
	s_waitcnt lgkmcnt(5)
	v_pk_fma_f32 v[34:35], v[210:211], v[62:63], v[34:35] neg_lo:[1,0,0] neg_hi:[1,0,0]
	v_pk_fma_f32 v[38:39], v[212:213], v[64:65], v[38:39] neg_lo:[1,0,0] neg_hi:[1,0,0]
	ds_read_b128 v[62:65], v174 offset:6208
	s_waitcnt lgkmcnt(5)
	v_pk_fma_f32 v[34:35], v[214:215], v[114:115], v[34:35] neg_lo:[1,0,0] neg_hi:[1,0,0]
	v_pk_fma_f32 v[38:39], v[216:217], v[116:117], v[38:39] neg_lo:[1,0,0] neg_hi:[1,0,0]
	ds_read_b128 v[114:117], v174 offset:6224
	v_add_f32_e32 v122, v34, v35
	v_add_f32_e32 v123, v38, v39
	v_add_f32_e32 v217, v122, v123
	ds_read_b128 v[118:121], v174 offset:6496
	v_cmp_eq_u32_e32 vcc, 25, v33
	s_waitcnt lgkmcnt(6)
	v_pk_fma_f32 v[132:133], v[124:125], v[44:45], v[132:133] neg_lo:[1,0,0] neg_hi:[1,0,0]
	v_pk_fma_f32 v[144:145], v[126:127], v[46:47], v[144:145] neg_lo:[1,0,0] neg_hi:[1,0,0]
	ds_read_b128 v[44:47], v174 offset:6400
	v_cndmask_b32_e64 v34, 0, 1.0, vcc
	v_mov_b32_e32 v35, 0
	v_mov_b64_e32 v[38:39], 0
	s_waitcnt lgkmcnt(6)
	v_pk_fma_f32 v[132:133], v[128:129], v[48:49], v[132:133] neg_lo:[1,0,0] neg_hi:[1,0,0]
	v_pk_fma_f32 v[144:145], v[130:131], v[50:51], v[144:145] neg_lo:[1,0,0] neg_hi:[1,0,0]
	ds_read_b128 v[48:51], v174 offset:6416
	s_waitcnt lgkmcnt(6)
	v_pk_fma_f32 v[132:133], v[150:151], v[52:53], v[132:133] neg_lo:[1,0,0] neg_hi:[1,0,0]
	v_pk_fma_f32 v[144:145], v[152:153], v[54:55], v[144:145] neg_lo:[1,0,0] neg_hi:[1,0,0]
	ds_read_b128 v[52:55], v174 offset:6432
	s_waitcnt lgkmcnt(6)
	v_pk_fma_f32 v[132:133], v[206:207], v[56:57], v[132:133] neg_lo:[1,0,0] neg_hi:[1,0,0]
	v_pk_fma_f32 v[144:145], v[208:209], v[58:59], v[144:145] neg_lo:[1,0,0] neg_hi:[1,0,0]
	ds_read_b128 v[56:59], v174 offset:6448
	s_waitcnt lgkmcnt(6)
	v_pk_fma_f32 v[132:133], v[210:211], v[62:63], v[132:133] neg_lo:[1,0,0] neg_hi:[1,0,0]
	v_pk_fma_f32 v[144:145], v[212:213], v[64:65], v[144:145] neg_lo:[1,0,0] neg_hi:[1,0,0]
	ds_read_b128 v[62:65], v174 offset:6464
	s_waitcnt lgkmcnt(6)
	v_pk_fma_f32 v[132:133], v[214:215], v[114:115], v[132:133] neg_lo:[1,0,0] neg_hi:[1,0,0]
	v_pk_fma_f32 v[144:145], v[216:217], v[116:117], v[144:145] neg_lo:[1,0,0] neg_hi:[1,0,0]
	ds_read_b128 v[114:117], v174 offset:6480
	v_add_f32_e32 v122, v132, v133
	v_add_f32_e32 v123, v144, v145
	v_add_f32_e32 v218, v122, v123
	v_cmp_eq_u32_e32 vcc, 26, v33
	s_waitcnt lgkmcnt(5)
	v_pk_fma_f32 v[34:35], v[124:125], v[44:45], v[34:35] neg_lo:[1,0,0] neg_hi:[1,0,0]
	v_pk_fma_f32 v[38:39], v[126:127], v[46:47], v[38:39] neg_lo:[1,0,0] neg_hi:[1,0,0]
	ds_read_b128 v[44:47], v174 offset:6656
	v_cndmask_b32_e64 v132, 0, 1.0, vcc
	v_mov_b32_e32 v133, 0
	v_mov_b64_e32 v[144:145], 0
	s_waitcnt lgkmcnt(5)
	v_pk_fma_f32 v[34:35], v[128:129], v[48:49], v[34:35] neg_lo:[1,0,0] neg_hi:[1,0,0]
	v_pk_fma_f32 v[38:39], v[130:131], v[50:51], v[38:39] neg_lo:[1,0,0] neg_hi:[1,0,0]
	ds_read_b128 v[48:51], v174 offset:6672
	s_waitcnt lgkmcnt(5)
	v_pk_fma_f32 v[34:35], v[150:151], v[52:53], v[34:35] neg_lo:[1,0,0] neg_hi:[1,0,0]
	v_pk_fma_f32 v[38:39], v[152:153], v[54:55], v[38:39] neg_lo:[1,0,0] neg_hi:[1,0,0]
	ds_read_b128 v[52:55], v174 offset:6688
	s_waitcnt lgkmcnt(5)
	v_pk_fma_f32 v[34:35], v[206:207], v[56:57], v[34:35] neg_lo:[1,0,0] neg_hi:[1,0,0]
	v_pk_fma_f32 v[38:39], v[208:209], v[58:59], v[38:39] neg_lo:[1,0,0] neg_hi:[1,0,0]
	ds_read_b128 v[56:59], v174 offset:6704
	s_waitcnt lgkmcnt(5)
	v_pk_fma_f32 v[34:35], v[210:211], v[62:63], v[34:35] neg_lo:[1,0,0] neg_hi:[1,0,0]
	v_pk_fma_f32 v[38:39], v[212:213], v[64:65], v[38:39] neg_lo:[1,0,0] neg_hi:[1,0,0]
	ds_read_b128 v[62:65], v174 offset:6720
	s_waitcnt lgkmcnt(5)
; #define LAS __attribute__((address_space(3)))
; DI void gdn_unit(const Params& P, bf16_t* proj, const float* gb, int b, int h, LAS unsigned char* lds) {
;     ...
;             const LAS float* Lblk = Lm + blk * (32 * 64 + 32);
;             float Tc[32];
; #pragma unroll
;             for (int i = 0; i < 32; ++i) {
;                 float s0 = (cl == i) ? 1.0f : 0.0f, s1 = 0.f, s2 = 0.f, s3 = 0.f;
;                 f32x4 lr[8];
; #pragma unroll
;                 for (int j4 = 0; j4 < (i + 3) / 4; ++j4) lr[j4] = *(const LAS f32x4*)(Lblk + i * 64 + j4 * 4);
;                 __builtin_amdgcn_sched_barrier(0);
; #pragma unroll
;                 for (int j4 = 0; j4 < (i + 3) / 4; ++j4) {
;                     const f32x4 l4 = lr[j4];
;                     if (j4 * 4 + 0 < i) s0 -= l4[0] * Tc[j4 * 4 + 0];
;                     if (j4 * 4 + 1 < i) s1 -= l4[1] * Tc[j4 * 4 + 1];
;                     if (j4 * 4 + 2 < i) s2 -= l4[2] * Tc[j4 * 4 + 2];
;                     if (j4 * 4 + 3 < i) s3 -= l4[3] * Tc[j4 * 4 + 3];
;                 }
;                 Tc[i] = (s0 + s1) + (s2 + s3);
;             }
	v_pk_fma_f32 v[34:35], v[214:215], v[114:115], v[34:35] neg_lo:[1,0,0] neg_hi:[1,0,0]
	v_pk_fma_f32 v[38:39], v[216:217], v[116:117], v[38:39] neg_lo:[1,0,0] neg_hi:[1,0,0]
	ds_read_b128 v[114:117], v174 offset:6736
	s_waitcnt lgkmcnt(12)
	v_pk_fma_f32 v[34:35], v[218:219], v[118:119], v[34:35] neg_lo:[1,0,0] neg_hi:[1,0,0]
	v_pk_fma_f32 v[38:39], v[220:221], v[120:121], v[38:39] neg_lo:[1,0,0] neg_hi:[1,0,0]
	ds_read_b128 v[118:121], v174 offset:6752
	v_add_f32_e32 v122, v34, v35
	v_add_f32_e32 v123, v38, v39
	v_add_f32_e32 v219, v122, v123
	v_cmp_eq_u32_e32 vcc, 27, v33
	s_waitcnt lgkmcnt(6)
	v_pk_fma_f32 v[132:133], v[124:125], v[44:45], v[132:133] neg_lo:[1,0,0] neg_hi:[1,0,0]
	v_pk_fma_f32 v[144:145], v[126:127], v[46:47], v[144:145] neg_lo:[1,0,0] neg_hi:[1,0,0]
	ds_read_b128 v[44:47], v174 offset:6912
	v_cndmask_b32_e64 v34, 0, 1.0, vcc
	v_mov_b32_e32 v35, 0
	v_mov_b64_e32 v[38:39], 0
	s_waitcnt lgkmcnt(6)
	v_pk_fma_f32 v[132:133], v[128:129], v[48:49], v[132:133] neg_lo:[1,0,0] neg_hi:[1,0,0]
	v_pk_fma_f32 v[144:145], v[130:131], v[50:51], v[144:145] neg_lo:[1,0,0] neg_hi:[1,0,0]
	ds_read_b128 v[48:51], v174 offset:6928
	s_waitcnt lgkmcnt(6)
	v_pk_fma_f32 v[132:133], v[150:151], v[52:53], v[132:133] neg_lo:[1,0,0] neg_hi:[1,0,0]
	v_pk_fma_f32 v[144:145], v[152:153], v[54:55], v[144:145] neg_lo:[1,0,0] neg_hi:[1,0,0]
	ds_read_b128 v[52:55], v174 offset:6944
	s_waitcnt lgkmcnt(6)
	v_pk_fma_f32 v[132:133], v[206:207], v[56:57], v[132:133] neg_lo:[1,0,0] neg_hi:[1,0,0]
	v_pk_fma_f32 v[144:145], v[208:209], v[58:59], v[144:145] neg_lo:[1,0,0] neg_hi:[1,0,0]
	ds_read_b128 v[56:59], v174 offset:6960
	s_waitcnt lgkmcnt(6)
	v_pk_fma_f32 v[132:133], v[210:211], v[62:63], v[132:133] neg_lo:[1,0,0] neg_hi:[1,0,0]
	v_pk_fma_f32 v[144:145], v[212:213], v[64:65], v[144:145] neg_lo:[1,0,0] neg_hi:[1,0,0]
	ds_read_b128 v[62:65], v174 offset:6976
	s_waitcnt lgkmcnt(6)
	v_pk_fma_f32 v[132:133], v[214:215], v[114:115], v[132:133] neg_lo:[1,0,0] neg_hi:[1,0,0]
	v_pk_fma_f32 v[144:145], v[216:217], v[116:117], v[144:145] neg_lo:[1,0,0] neg_hi:[1,0,0]
	ds_read_b128 v[114:117], v174 offset:6992
	s_waitcnt lgkmcnt(6)
	v_pk_fma_f32 v[132:133], v[218:219], v[118:119], v[132:133] neg_lo:[1,0,0] neg_hi:[1,0,0]
	v_pk_fma_f32 v[144:145], v[220:221], v[120:121], v[144:145] neg_lo:[1,0,0] neg_hi:[1,0,0]
	ds_read_b128 v[118:121], v174 offset:7008
	v_add_f32_e32 v122, v132, v133
	v_add_f32_e32 v123, v144, v145
	v_add_f32_e32 v220, v122, v123
	v_cmp_eq_u32_e32 vcc, 28, v33
	s_waitcnt lgkmcnt(6)
	v_pk_fma_f32 v[34:35], v[124:125], v[44:45], v[34:35] neg_lo:[1,0,0] neg_hi:[1,0,0]
	v_pk_fma_f32 v[38:39], v[126:127], v[46:47], v[38:39] neg_lo:[1,0,0] neg_hi:[1,0,0]
	ds_read_b128 v[44:47], v174 offset:7168
	v_cndmask_b32_e64 v132, 0, 1.0, vcc
	v_mov_b32_e32 v133, 0
	v_mov_b64_e32 v[144:145], 0
	s_waitcnt lgkmcnt(6)
	v_pk_fma_f32 v[34:35], v[128:129], v[48:49], v[34:35] neg_lo:[1,0,0] neg_hi:[1,0,0]
	v_pk_fma_f32 v[38:39], v[130:131], v[50:51], v[38:39] neg_lo:[1,0,0] neg_hi:[1,0,0]
	ds_read_b128 v[48:51], v174 offset:7184
	s_waitcnt lgkmcnt(6)
	v_pk_fma_f32 v[34:35], v[150:151], v[52:53], v[34:35] neg_lo:[1,0,0] neg_hi:[1,0,0]
	v_pk_fma_f32 v[38:39], v[152:153], v[54:55], v[38:39] neg_lo:[1,0,0] neg_hi:[1,0,0]
	ds_read_b128 v[52:55], v174 offset:7200
	s_waitcnt lgkmcnt(6)
	v_pk_fma_f32 v[34:35], v[206:207], v[56:57], v[34:35] neg_lo:[1,0,0] neg_hi:[1,0,0]
	v_pk_fma_f32 v[38:39], v[208:209], v[58:59], v[38:39] neg_lo:[1,0,0] neg_hi:[1,0,0]
	ds_read_b128 v[56:59], v174 offset:7216
	s_waitcnt lgkmcnt(6)
	v_pk_fma_f32 v[34:35], v[210:211], v[62:63], v[34:35] neg_lo:[1,0,0] neg_hi:[1,0,0]
	v_pk_fma_f32 v[38:39], v[212:213], v[64:65], v[38:39] neg_lo:[1,0,0] neg_hi:[1,0,0]
	ds_read_b128 v[62:65], v174 offset:7232
	s_waitcnt lgkmcnt(6)
	v_pk_fma_f32 v[34:35], v[214:215], v[114:115], v[34:35] neg_lo:[1,0,0] neg_hi:[1,0,0]
	v_pk_fma_f32 v[38:39], v[216:217], v[116:117], v[38:39] neg_lo:[1,0,0] neg_hi:[1,0,0]
	ds_read_b128 v[114:117], v174 offset:7248
	s_waitcnt lgkmcnt(6)
	v_pk_fma_f32 v[34:35], v[218:219], v[118:119], v[34:35] neg_lo:[1,0,0] neg_hi:[1,0,0]
	v_pk_fma_f32 v[38:39], v[220:221], v[120:121], v[38:39] neg_lo:[1,0,0] neg_hi:[1,0,0]
	ds_read_b128 v[118:121], v174 offset:7264
	v_add_f32_e32 v122, v34, v35
	v_add_f32_e32 v123, v38, v39
	v_add_f32_e32 v221, v122, v123
	ds_read_b128 v[138:141], v174 offset:7536
	v_cmp_eq_u32_e32 vcc, 29, v33
	s_waitcnt lgkmcnt(7)
	v_pk_fma_f32 v[132:133], v[124:125], v[44:45], v[132:133] neg_lo:[1,0,0] neg_hi:[1,0,0]
	v_pk_fma_f32 v[144:145], v[126:127], v[46:47], v[144:145] neg_lo:[1,0,0] neg_hi:[1,0,0]
	ds_read_b128 v[44:47], v174 offset:7424
	v_cndmask_b32_e64 v34, 0, 1.0, vcc
	v_mov_b32_e32 v35, 0
	v_mov_b64_e32 v[38:39], 0
	s_waitcnt lgkmcnt(7)
	v_pk_fma_f32 v[132:133], v[128:129], v[48:49], v[132:133] neg_lo:[1,0,0] neg_hi:[1,0,0]
	v_pk_fma_f32 v[144:145], v[130:131], v[50:51], v[144:145] neg_lo:[1,0,0] neg_hi:[1,0,0]
	ds_read_b128 v[48:51], v174 offset:7440
	s_waitcnt lgkmcnt(7)
	v_pk_fma_f32 v[132:133], v[150:151], v[52:53], v[132:133] neg_lo:[1,0,0] neg_hi:[1,0,0]
	v_pk_fma_f32 v[144:145], v[152:153], v[54:55], v[144:145] neg_lo:[1,0,0] neg_hi:[1,0,0]
	ds_read_b128 v[52:55], v174 offset:7456
	s_waitcnt lgkmcnt(7)
	v_pk_fma_f32 v[132:133], v[206:207], v[56:57], v[132:133] neg_lo:[1,0,0] neg_hi:[1,0,0]
	v_pk_fma_f32 v[144:145], v[208:209], v[58:59], v[144:145] neg_lo:[1,0,0] neg_hi:[1,0,0]
	ds_read_b128 v[56:59], v174 offset:7472
	s_waitcnt lgkmcnt(7)
	v_pk_fma_f32 v[132:133], v[210:211], v[62:63], v[132:133] neg_lo:[1,0,0] neg_hi:[1,0,0]
	v_pk_fma_f32 v[144:145], v[212:213], v[64:65], v[144:145] neg_lo:[1,0,0] neg_hi:[1,0,0]
	ds_read_b128 v[62:65], v174 offset:7488
	s_waitcnt lgkmcnt(7)
; #define LAS __attribute__((address_space(3)))
; DI void gdn_unit(const Params& P, bf16_t* proj, const float* gb, int b, int h, LAS unsigned char* lds) {
;     ...
;             const LAS float* Lblk = Lm + blk * (32 * 64 + 32);
;             float Tc[32];
; #pragma unroll
;             for (int i = 0; i < 32; ++i) {
;                 float s0 = (cl == i) ? 1.0f : 0.0f, s1 = 0.f, s2 = 0.f, s3 = 0.f;
;                 f32x4 lr[8];
; #pragma unroll
;                 for (int j4 = 0; j4 < (i + 3) / 4; ++j4) lr[j4] = *(const LAS f32x4*)(Lblk + i * 64 + j4 * 4);
;                 __builtin_amdgcn_sched_barrier(0);
; #pragma unroll
;                 for (int j4 = 0; j4 < (i + 3) / 4; ++j4) {
;                     const f32x4 l4 = lr[j4];
;                     if (j4 * 4 + 0 < i) s0 -= l4[0] * Tc[j4 * 4 + 0];
;                     if (j4 * 4 + 1 < i) s1 -= l4[1] * Tc[j4 * 4 + 1];
;                     if (j4 * 4 + 2 < i) s2 -= l4[2] * Tc[j4 * 4 + 2];
;                     if (j4 * 4 + 3 < i) s3 -= l4[3] * Tc[j4 * 4 + 3];
;                 }
;                 Tc[i] = (s0 + s1) + (s2 + s3);
;             }
	v_pk_fma_f32 v[132:133], v[214:215], v[114:115], v[132:133] neg_lo:[1,0,0] neg_hi:[1,0,0]
	v_pk_fma_f32 v[144:145], v[216:217], v[116:117], v[144:145] neg_lo:[1,0,0] neg_hi:[1,0,0]
	ds_read_b128 v[114:117], v174 offset:7504
	s_waitcnt lgkmcnt(7)
	v_pk_fma_f32 v[132:133], v[218:219], v[118:119], v[132:133] neg_lo:[1,0,0] neg_hi:[1,0,0]
	v_pk_fma_f32 v[144:145], v[220:221], v[120:121], v[144:145] neg_lo:[1,0,0] neg_hi:[1,0,0]
	ds_read_b128 v[118:121], v174 offset:7520
	v_add_f32_e32 v122, v132, v133
	v_add_f32_e32 v123, v144, v145
	v_add_f32_e32 v146, v122, v123
	v_cmp_eq_u32_e32 vcc, 30, v33
	s_waitcnt lgkmcnt(6)
	v_pk_fma_f32 v[34:35], v[124:125], v[44:45], v[34:35] neg_lo:[1,0,0] neg_hi:[1,0,0]
	v_pk_fma_f32 v[38:39], v[126:127], v[46:47], v[38:39] neg_lo:[1,0,0] neg_hi:[1,0,0]
	ds_read_b128 v[44:47], v174 offset:7680
	v_cndmask_b32_e64 v132, 0, 1.0, vcc
	v_mov_b32_e32 v133, 0
	v_mov_b64_e32 v[144:145], 0
	s_waitcnt lgkmcnt(6)
	v_pk_fma_f32 v[34:35], v[128:129], v[48:49], v[34:35] neg_lo:[1,0,0] neg_hi:[1,0,0]
	v_pk_fma_f32 v[38:39], v[130:131], v[50:51], v[38:39] neg_lo:[1,0,0] neg_hi:[1,0,0]
	ds_read_b128 v[48:51], v174 offset:7696
	s_waitcnt lgkmcnt(6)
	v_pk_fma_f32 v[34:35], v[150:151], v[52:53], v[34:35] neg_lo:[1,0,0] neg_hi:[1,0,0]
	v_pk_fma_f32 v[38:39], v[152:153], v[54:55], v[38:39] neg_lo:[1,0,0] neg_hi:[1,0,0]
	ds_read_b128 v[52:55], v174 offset:7712
	s_waitcnt lgkmcnt(6)
	v_pk_fma_f32 v[34:35], v[206:207], v[56:57], v[34:35] neg_lo:[1,0,0] neg_hi:[1,0,0]
	v_pk_fma_f32 v[38:39], v[208:209], v[58:59], v[38:39] neg_lo:[1,0,0] neg_hi:[1,0,0]
	ds_read_b128 v[56:59], v174 offset:7728
	s_waitcnt lgkmcnt(6)
	v_pk_fma_f32 v[34:35], v[210:211], v[62:63], v[34:35] neg_lo:[1,0,0] neg_hi:[1,0,0]
	v_pk_fma_f32 v[38:39], v[212:213], v[64:65], v[38:39] neg_lo:[1,0,0] neg_hi:[1,0,0]
	ds_read_b128 v[62:65], v174 offset:7744
	s_waitcnt lgkmcnt(6)
	v_pk_fma_f32 v[34:35], v[214:215], v[114:115], v[34:35] neg_lo:[1,0,0] neg_hi:[1,0,0]
	v_pk_fma_f32 v[38:39], v[216:217], v[116:117], v[38:39] neg_lo:[1,0,0] neg_hi:[1,0,0]
	ds_read_b128 v[114:117], v174 offset:7760
	s_waitcnt lgkmcnt(6)
	v_pk_fma_f32 v[34:35], v[218:219], v[118:119], v[34:35] neg_lo:[1,0,0] neg_hi:[1,0,0]
	v_pk_fma_f32 v[38:39], v[220:221], v[120:121], v[38:39] neg_lo:[1,0,0] neg_hi:[1,0,0]
	ds_read_b128 v[118:121], v174 offset:7776
	s_waitcnt lgkmcnt(14)
	v_pk_fma_f32 v[34:35], v[146:147], v[138:139], v[34:35] neg_lo:[1,0,0] neg_hi:[1,0,0]
	v_pk_fma_f32 v[38:39], v[172:173], v[140:141], v[38:39] neg_lo:[1,0,0] neg_hi:[1,0,0]
	ds_read_b128 v[138:141], v174 offset:7792
	v_add_f32_e32 v122, v34, v35
	v_add_f32_e32 v123, v38, v39
	v_add_f32_e32 v147, v122, v123
	v_cmp_eq_u32_e32 vcc, 31, v33
	s_waitcnt lgkmcnt(7)
	v_pk_fma_f32 v[132:133], v[124:125], v[44:45], v[132:133] neg_lo:[1,0,0] neg_hi:[1,0,0]
	v_pk_fma_f32 v[144:145], v[126:127], v[46:47], v[144:145] neg_lo:[1,0,0] neg_hi:[1,0,0]
	ds_read_b128 v[44:47], v174 offset:7936
	v_cndmask_b32_e64 v34, 0, 1.0, vcc
	v_mov_b32_e32 v35, 0
	v_mov_b64_e32 v[38:39], 0
	s_waitcnt lgkmcnt(7)
	v_pk_fma_f32 v[132:133], v[128:129], v[48:49], v[132:133] neg_lo:[1,0,0] neg_hi:[1,0,0]
	v_pk_fma_f32 v[144:145], v[130:131], v[50:51], v[144:145] neg_lo:[1,0,0] neg_hi:[1,0,0]
	ds_read_b128 v[48:51], v174 offset:7952
	s_waitcnt lgkmcnt(7)
	v_pk_fma_f32 v[132:133], v[150:151], v[52:53], v[132:133] neg_lo:[1,0,0] neg_hi:[1,0,0]
	v_pk_fma_f32 v[144:145], v[152:153], v[54:55], v[144:145] neg_lo:[1,0,0] neg_hi:[1,0,0]
	ds_read_b128 v[52:55], v174 offset:7968
	s_waitcnt lgkmcnt(7)
	v_pk_fma_f32 v[132:133], v[206:207], v[56:57], v[132:133] neg_lo:[1,0,0] neg_hi:[1,0,0]
	v_pk_fma_f32 v[144:145], v[208:209], v[58:59], v[144:145] neg_lo:[1,0,0] neg_hi:[1,0,0]
	ds_read_b128 v[56:59], v174 offset:7984
	s_waitcnt lgkmcnt(7)
	v_pk_fma_f32 v[132:133], v[210:211], v[62:63], v[132:133] neg_lo:[1,0,0] neg_hi:[1,0,0]
	v_pk_fma_f32 v[144:145], v[212:213], v[64:65], v[144:145] neg_lo:[1,0,0] neg_hi:[1,0,0]
	ds_read_b128 v[62:65], v174 offset:8000
	s_waitcnt lgkmcnt(7)
	v_pk_fma_f32 v[132:133], v[214:215], v[114:115], v[132:133] neg_lo:[1,0,0] neg_hi:[1,0,0]
	v_pk_fma_f32 v[144:145], v[216:217], v[116:117], v[144:145] neg_lo:[1,0,0] neg_hi:[1,0,0]
	ds_read_b128 v[114:117], v174 offset:8016
	s_waitcnt lgkmcnt(7)
	v_pk_fma_f32 v[132:133], v[218:219], v[118:119], v[132:133] neg_lo:[1,0,0] neg_hi:[1,0,0]
	v_pk_fma_f32 v[144:145], v[220:221], v[120:121], v[144:145] neg_lo:[1,0,0] neg_hi:[1,0,0]
	ds_read_b128 v[118:121], v174 offset:8032
	s_waitcnt lgkmcnt(7)
	v_pk_fma_f32 v[132:133], v[146:147], v[138:139], v[132:133] neg_lo:[1,0,0] neg_hi:[1,0,0]
	v_pk_fma_f32 v[144:145], v[172:173], v[140:141], v[144:145] neg_lo:[1,0,0] neg_hi:[1,0,0]
	ds_read_b128 v[138:141], v174 offset:8048
	v_add_f32_e32 v122, v132, v133
	v_add_f32_e32 v123, v144, v145
	v_add_f32_e32 v172, v122, v123
	s_waitcnt lgkmcnt(7)
	v_pk_fma_f32 v[34:35], v[124:125], v[44:45], v[34:35] neg_lo:[1,0,0] neg_hi:[1,0,0]
	v_pk_fma_f32 v[38:39], v[126:127], v[46:47], v[38:39] neg_lo:[1,0,0] neg_hi:[1,0,0]
	s_waitcnt lgkmcnt(6)
	v_pk_fma_f32 v[34:35], v[128:129], v[48:49], v[34:35] neg_lo:[1,0,0] neg_hi:[1,0,0]
	v_pk_fma_f32 v[38:39], v[130:131], v[50:51], v[38:39] neg_lo:[1,0,0] neg_hi:[1,0,0]
	s_waitcnt lgkmcnt(5)
	v_pk_fma_f32 v[34:35], v[150:151], v[52:53], v[34:35] neg_lo:[1,0,0] neg_hi:[1,0,0]
	v_pk_fma_f32 v[38:39], v[152:153], v[54:55], v[38:39] neg_lo:[1,0,0] neg_hi:[1,0,0]
	s_waitcnt lgkmcnt(4)
	v_pk_fma_f32 v[34:35], v[206:207], v[56:57], v[34:35] neg_lo:[1,0,0] neg_hi:[1,0,0]
	v_pk_fma_f32 v[38:39], v[208:209], v[58:59], v[38:39] neg_lo:[1,0,0] neg_hi:[1,0,0]
	s_waitcnt lgkmcnt(3)
; #define LAS __attribute__((address_space(3)))
; DI unsigned f2bf(float f) { unsigned u = __float_as_uint(f); u += 0x7FFFu + ((u >> 16) & 1u); return u >> 16; }
; DI void gdn_unit(const Params& P, bf16_t* proj, const float* gb, int b, int h, LAS unsigned char* lds) {
;     ...
;                 Tc[i] = (s0 + s1) + (s2 + s3);
;             }
;             const float sc1 = beta * egc, sc2 = beta;
; #pragma unroll
;             for (int i = 0; i < 32; ++i) {
;                 const int row = blk * 32 + i;
;                 *(LAS bf16_t*)(lds + TP_OFF + row * 144 + lane * 2) = (bf16_t)f2bf(Tc[i] * sc1);
;                 *(LAS bf16_t*)(lds + TPP_OFF + row * 144 + lane * 2) = (bf16_t)f2bf(Tc[i] * sc2);
;             }
	v_pk_fma_f32 v[34:35], v[210:211], v[62:63], v[34:35] neg_lo:[1,0,0] neg_hi:[1,0,0]
	v_pk_fma_f32 v[38:39], v[212:213], v[64:65], v[38:39] neg_lo:[1,0,0] neg_hi:[1,0,0]
	s_waitcnt lgkmcnt(2)
	v_pk_fma_f32 v[34:35], v[214:215], v[114:115], v[34:35] neg_lo:[1,0,0] neg_hi:[1,0,0]
	v_pk_fma_f32 v[38:39], v[216:217], v[116:117], v[38:39] neg_lo:[1,0,0] neg_hi:[1,0,0]
	s_waitcnt lgkmcnt(1)
	v_pk_fma_f32 v[34:35], v[218:219], v[118:119], v[34:35] neg_lo:[1,0,0] neg_hi:[1,0,0]
	v_pk_fma_f32 v[38:39], v[220:221], v[120:121], v[38:39] neg_lo:[1,0,0] neg_hi:[1,0,0]
	s_waitcnt lgkmcnt(0)
	v_pk_fma_f32 v[34:35], v[146:147], v[138:139], v[34:35] neg_lo:[1,0,0] neg_hi:[1,0,0]
	v_pk_fma_f32 v[38:39], v[172:173], v[140:141], v[38:39] neg_lo:[1,0,0] neg_hi:[1,0,0]
	v_add_f32_e32 v122, v34, v35
	v_add_f32_e32 v123, v38, v39
	v_add_f32_e32 v173, v122, v123
	v_mov_b32_e32 v37, v124
	v_mov_b32_e32 v32, v125
	v_mov_b32_e32 v34, v126
	v_mov_b32_e32 v35, v127
	v_mov_b32_e32 v39, v128
	v_mov_b32_e32 v38, v129
	v_mov_b32_e32 v43, v130
	v_mov_b32_e32 v44, v131
	v_mov_b32_e32 v45, v150
	v_mov_b32_e32 v47, v151
	v_mov_b32_e32 v46, v152
	v_mov_b32_e32 v48, v153
	v_mov_b32_e32 v50, v206
	v_mov_b32_e32 v52, v207
	v_mov_b32_e32 v51, v208
	v_mov_b32_e32 v53, v209
	v_mov_b32_e32 v54, v210
	v_mov_b32_e32 v56, v211
	v_mov_b32_e32 v55, v212
	v_mov_b32_e32 v57, v213
	v_mov_b32_e32 v58, v214
	v_mov_b32_e32 v62, v215
	v_mov_b32_e32 v59, v216
	v_mov_b32_e32 v63, v217
	v_mov_b32_e32 v64, v218
	v_mov_b32_e32 v114, v219
	v_mov_b32_e32 v65, v220
	v_mov_b32_e32 v115, v221
	v_mov_b32_e32 v49, v146
	v_mov_b32_e32 v117, v147
	v_mov_b32_e32 v116, v172
	v_mov_b32_e32 v118, v173
	v_mul_f32_e32 v119, v108, v109
	v_and_b32_e32 v120, 0xfffffe0, v67
	v_readlane_b32 s0, v255, 9
	v_mul_f32_e32 v121, v37, v119
	s_nop 0
	v_add_u32_e32 v109, s0, v60
	v_mul_lo_u32 v120, v120, s37
	v_cvt_pk_bf16_f32 v121, v121, v121
	v_add_u32_e32 v122, v109, v120
	v_readlane_b32 s0, v255, 10
	ds_write_b16_d16_hi v122, v121
	v_mul_f32_e32 v121, v108, v37
	v_add_u32_e32 v60, s0, v60
	s_nop 0
	v_cvt_pk_bf16_f32 v121, v121, v121
	v_add_u32_e32 v120, v60, v120
	ds_write_b16_d16_hi v120, v121
	v_mul_f32_e32 v121, v119, v32
	v_mul_f32_e32 v123, v108, v32
	v_cvt_pk_bf16_f32 v121, v121, v123
	ds_write_b16 v122, v121 offset:144
	ds_write_b16_d16_hi v120, v121 offset:144
	v_mul_f32_e32 v172, v119, v34
	v_mul_f32_e32 v173, v108, v34
	v_cvt_pk_bf16_f32 v172, v172, v173
	ds_write_b16 v122, v172 offset:288
	ds_write_b16_d16_hi v120, v172 offset:288
	v_mul_f32_e32 v121, v119, v35
	v_mul_f32_e32 v123, v108, v35
	v_cvt_pk_bf16_f32 v121, v121, v123
	ds_write_b16 v122, v121 offset:432
	ds_write_b16_d16_hi v120, v121 offset:432
	v_mul_f32_e32 v172, v119, v39
	v_mul_f32_e32 v173, v108, v39
	v_cvt_pk_bf16_f32 v172, v172, v173
	ds_write_b16 v122, v172 offset:576
	ds_write_b16_d16_hi v120, v172 offset:576
	v_mul_f32_e32 v121, v119, v38
	v_mul_f32_e32 v123, v108, v38
	v_cvt_pk_bf16_f32 v121, v121, v123
	ds_write_b16 v122, v121 offset:720
	ds_write_b16_d16_hi v120, v121 offset:720
	v_mul_f32_e32 v172, v119, v43
	v_mul_f32_e32 v173, v108, v43
	v_cvt_pk_bf16_f32 v172, v172, v173
	ds_write_b16 v122, v172 offset:864
	ds_write_b16_d16_hi v120, v172 offset:864
	v_mul_f32_e32 v121, v119, v44
	v_mul_f32_e32 v123, v108, v44
	v_cvt_pk_bf16_f32 v121, v121, v123
	ds_write_b16 v122, v121 offset:1008
	ds_write_b16_d16_hi v120, v121 offset:1008
	v_mul_f32_e32 v172, v119, v45
	v_mul_f32_e32 v173, v108, v45
	v_cvt_pk_bf16_f32 v172, v172, v173
	ds_write_b16 v122, v172 offset:1152
	ds_write_b16_d16_hi v120, v172 offset:1152
	v_mul_f32_e32 v121, v119, v47
	v_mul_f32_e32 v123, v108, v47
	v_cvt_pk_bf16_f32 v121, v121, v123
	ds_write_b16 v122, v121 offset:1296
	ds_write_b16_d16_hi v120, v121 offset:1296
	v_mul_f32_e32 v172, v119, v46
	v_mul_f32_e32 v173, v108, v46
	v_cvt_pk_bf16_f32 v172, v172, v173
	ds_write_b16 v122, v172 offset:1440
	ds_write_b16_d16_hi v120, v172 offset:1440
	v_mul_f32_e32 v121, v119, v48
	v_mul_f32_e32 v123, v108, v48
	v_cvt_pk_bf16_f32 v121, v121, v123
	ds_write_b16 v122, v121 offset:1584
	ds_write_b16_d16_hi v120, v121 offset:1584
	v_mul_f32_e32 v172, v119, v50
	v_mul_f32_e32 v173, v108, v50
	v_cvt_pk_bf16_f32 v172, v172, v173
	ds_write_b16 v122, v172 offset:1728
	ds_write_b16_d16_hi v120, v172 offset:1728
	v_mul_f32_e32 v121, v119, v52
	v_mul_f32_e32 v123, v108, v52
; #define LAS __attribute__((address_space(3)))
; DI unsigned f2bf(float f) { unsigned u = __float_as_uint(f); u += 0x7FFFu + ((u >> 16) & 1u); return u >> 16; }
; DI void gdn_unit(const Params& P, bf16_t* proj, const float* gb, int b, int h, LAS unsigned char* lds) {
;     ...
;             for (int i = 0; i < 32; ++i) {
;                 const int row = blk * 32 + i;
;                 *(LAS bf16_t*)(lds + TP_OFF + row * 144 + lane * 2) = (bf16_t)f2bf(Tc[i] * sc1);
;                 *(LAS bf16_t*)(lds + TPP_OFF + row * 144 + lane * 2) = (bf16_t)f2bf(Tc[i] * sc2);
;             }
;             if (blk == 1) {
; #pragma unroll
;                 for (int i = 0; i < 32; ++i) { *(LAS bf16_t*)(lds + TP_OFF + i * 144 + lane * 2) = (bf16_t)0; *(LAS bf16_t*)(lds + TPP_OFF + i * 144 + lane * 2) = (bf16_t)0; }
;             }
	v_cvt_pk_bf16_f32 v121, v121, v123
	ds_write_b16 v122, v121 offset:1872
	ds_write_b16_d16_hi v120, v121 offset:1872
	v_mul_f32_e32 v172, v119, v51
	v_mul_f32_e32 v173, v108, v51
	v_cvt_pk_bf16_f32 v172, v172, v173
	ds_write_b16 v122, v172 offset:2016
	ds_write_b16_d16_hi v120, v172 offset:2016
	v_mul_f32_e32 v121, v119, v53
	v_mul_f32_e32 v123, v108, v53
	v_cvt_pk_bf16_f32 v121, v121, v123
	ds_write_b16 v122, v121 offset:2160
	ds_write_b16_d16_hi v120, v121 offset:2160
	v_mul_f32_e32 v172, v119, v54
	v_mul_f32_e32 v173, v108, v54
	v_cvt_pk_bf16_f32 v172, v172, v173
	ds_write_b16 v122, v172 offset:2304
	ds_write_b16_d16_hi v120, v172 offset:2304
	v_mul_f32_e32 v121, v119, v56
	v_mul_f32_e32 v123, v108, v56
	v_cvt_pk_bf16_f32 v121, v121, v123
	ds_write_b16 v122, v121 offset:2448
	ds_write_b16_d16_hi v120, v121 offset:2448
	v_mul_f32_e32 v172, v119, v55
	v_mul_f32_e32 v173, v108, v55
	v_cvt_pk_bf16_f32 v172, v172, v173
	ds_write_b16 v122, v172 offset:2592
	ds_write_b16_d16_hi v120, v172 offset:2592
	v_mul_f32_e32 v121, v119, v57
	v_mul_f32_e32 v123, v108, v57
	v_cvt_pk_bf16_f32 v121, v121, v123
	ds_write_b16 v122, v121 offset:2736
	ds_write_b16_d16_hi v120, v121 offset:2736
	v_mul_f32_e32 v172, v119, v58
	v_mul_f32_e32 v173, v108, v58
	v_cvt_pk_bf16_f32 v172, v172, v173
	ds_write_b16 v122, v172 offset:2880
	ds_write_b16_d16_hi v120, v172 offset:2880
	v_mul_f32_e32 v121, v119, v62
	v_mul_f32_e32 v123, v108, v62
	v_cvt_pk_bf16_f32 v121, v121, v123
	ds_write_b16 v122, v121 offset:3024
	ds_write_b16_d16_hi v120, v121 offset:3024
	v_mul_f32_e32 v172, v119, v59
	v_mul_f32_e32 v173, v108, v59
	v_cvt_pk_bf16_f32 v172, v172, v173
	ds_write_b16 v122, v172 offset:3168
	ds_write_b16_d16_hi v120, v172 offset:3168
	v_mul_f32_e32 v121, v119, v63
	v_mul_f32_e32 v123, v108, v63
	v_cvt_pk_bf16_f32 v121, v121, v123
	ds_write_b16 v122, v121 offset:3312
	ds_write_b16_d16_hi v120, v121 offset:3312
	v_mul_f32_e32 v172, v119, v64
	v_mul_f32_e32 v173, v108, v64
	v_cvt_pk_bf16_f32 v172, v172, v173
	ds_write_b16 v122, v172 offset:3456
	ds_write_b16_d16_hi v120, v172 offset:3456
	v_mul_f32_e32 v121, v119, v114
	v_mul_f32_e32 v123, v108, v114
	v_cvt_pk_bf16_f32 v121, v121, v123
	ds_write_b16 v122, v121 offset:3600
	ds_write_b16_d16_hi v120, v121 offset:3600
	v_mul_f32_e32 v172, v119, v65
	v_mul_f32_e32 v173, v108, v65
	v_cvt_pk_bf16_f32 v172, v172, v173
	ds_write_b16 v122, v172 offset:3744
	ds_write_b16_d16_hi v120, v172 offset:3744
	v_mul_f32_e32 v121, v119, v115
	v_mul_f32_e32 v123, v108, v115
	v_cvt_pk_bf16_f32 v121, v121, v123
	ds_write_b16 v122, v121 offset:3888
	ds_write_b16_d16_hi v120, v121 offset:3888
	v_mul_f32_e32 v172, v119, v49
	v_mul_f32_e32 v173, v108, v49
	v_cvt_pk_bf16_f32 v172, v172, v173
	ds_write_b16 v122, v172 offset:4032
	ds_write_b16_d16_hi v120, v172 offset:4032
	v_mul_f32_e32 v121, v119, v117
	v_mul_f32_e32 v123, v108, v117
	v_cvt_pk_bf16_f32 v121, v121, v123
	ds_write_b16 v122, v121 offset:4176
	ds_write_b16_d16_hi v120, v121 offset:4176
	v_mul_f32_e32 v121, v119, v116
	v_bfe_u32 v123, v121, 16, 1
	v_add3_u32 v121, v121, v123, s68
	ds_write_b16_d16_hi v122, v121 offset:4320
	v_mul_f32_e32 v121, v108, v116
	v_bfe_u32 v122, v121, 16, 1
	v_add3_u32 v121, v121, v122, s68
	ds_write_b16_d16_hi v120, v121 offset:4320
	v_or_b32_e32 v120, 31, v67
	v_mul_f32_e32 v119, v119, v118
	v_mul_lo_u32 v120, v120, s37
	v_cvt_pk_bf16_f32 v119, v119, v119
	v_add_u32_e32 v121, v109, v120
	v_mul_f32_e32 v108, v108, v118
	ds_write_b16_d16_hi v121, v119
	v_bfe_u32 v119, v108, 16, 1
	v_add3_u32 v108, v108, v119, s68
	v_add_u32_e32 v119, v60, v120
	v_cmp_eq_u32_e32 vcc, 1, v36
	ds_write_b16_d16_hi v119, v108
	s_and_saveexec_b64 s[0:1], vcc
	s_cbranch_execz .LBB0_494
	v_lshlrev_b32_e32 v121, 1, v33
	v_lshrrev_b32_e32 v123, 2, v33
	v_mul_u32_u24_e32 v123, 0x90, v123
	v_sub_u32_e32 v123, v123, v121
	v_and_b32_e32 v121, 3, v33
	v_lshl_add_u32 v123, v121, 4, v123
	v_add_u32_e32 v121, v109, v123
	v_add_u32_e32 v123, v60, v123
	v_mov_b64_e32 v[172:173], 0
	v_mov_b64_e32 v[174:175], 0
	ds_write_b128 v121, v[172:175]
	ds_write_b128 v123, v[172:175]
	ds_write_b128 v121, v[172:175] offset:1152
	ds_write_b128 v123, v[172:175] offset:1152
	ds_write_b128 v121, v[172:175] offset:2304
	ds_write_b128 v123, v[172:175] offset:2304
	ds_write_b128 v121, v[172:175] offset:3456
	ds_write_b128 v123, v[172:175] offset:3456

; #define LAS __attribute__((address_space(3)))
; DI unsigned pk2(float lo, float hi) { return f2bf(lo) | (f2bf(hi) << 16); }
; DI void gdn_unit(const Params& P, bf16_t* proj, const float* gb, int b, int h, LAS unsigned char* lds) {
;     ...
;             LAS unsigned char* T11t = Lbytes, *T22n = Lbytes + 2048, *Xt = Lbytes + 4096;
;             if (blk == 0) {
; #pragma unroll
;                 for (int q = 0; q < 4; ++q) {
;                     u32x4 w; w.x = pk2(Tc[q * 8 + 0], Tc[q * 8 + 1]); w.y = pk2(Tc[q * 8 + 2], Tc[q * 8 + 3]); w.z = pk2(Tc[q * 8 + 4], Tc[q * 8 + 5]); w.w = pk2(Tc[q * 8 + 6], Tc[q * 8 + 7]);
;                     *(LAS u32x4*)(T11t + cl * 64 + q * 16) = w;
;                 }
;             } else {
; #pragma unroll
;                 for (int i = 0; i < 32; ++i) *(LAS bf16_t*)(T22n + i * 64 + cl * 2) = (bf16_t)f2bf(Tc[i]);
;             }
;             f32x4 xacc[2][2];
; #pragma unroll
;             for (int ti = 0; ti < 2; ++ti)
; #pragma unroll
;                 for (int tj = 0; tj < 2; ++tj)
;                     xacc[ti][tj] = MFMA16(ldsfrag(L21b + (ti * 16 + fr) * 64 + fq * 16), ldsfrag(T11t + (tj * 16 + fr) * 64 + fq * 16), ((f32x4){0.f, 0.f, 0.f, 0.f}));
; #pragma unroll
;             for (int ti = 0; ti < 2; ++ti)
; #pragma unroll
;                 for (int tj = 0; tj < 2; ++tj) {
;                     u32x2 w; w.x = pk2(xacc[ti][tj][0], xacc[ti][tj][1]); w.y = pk2(xacc[ti][tj][2], xacc[ti][tj][3]);
;                     *(LAS u32x2*)(Xt + (tj * 16 + fr) * 64 + (ti * 16 + fq * 4) * 2) = w;
;                 }
; #pragma unroll
;             for (int tj = 0; tj < 2; ++tj) {
;                 const int col = tj * 16 + fr;
;                 const float c1 = -betas[col] * egcs[col], c2 = -betas[col];
; #pragma unroll
;                 for (int ti = 0; ti < 2; ++ti) {
;                     const f32x4 t = MFMA16(ldsfrag(T22n + (ti * 16 + fr) * 64 + fq * 16), ldsfrag(Xt + (tj * 16 + fr) * 64 + fq * 16), ((f32x4){0.f, 0.f, 0.f, 0.f}));
; #pragma unroll
;                     for (int jj = 0; jj < 4; ++jj) {
;                         const int row = 32 + ti * 16 + fq * 4 + jj;
;                         *(LAS bf16_t*)(lds + TP_OFF + row * 144 + col * 2) = (bf16_t)f2bf(t[jj] * c1);
;                         *(LAS bf16_t*)(lds + TPP_OFF + row * 144 + col * 2) = (bf16_t)f2bf(t[jj] * c2);
;                     }
;                 }
;             }
.LBB0_496:
	s_andn2_saveexec_b64 s[0:1], s[0:1]
	s_cbranch_execz .LBB0_498
	v_lshl_add_u32 v33, v67, 6, 0
	v_add_u32_e32 v37, 0x20c00, v33
	v_cvt_pk_bf16_f32 v33, v34, v34
	v_cvt_pk_bf16_f32 v34, v43, v43
	v_cvt_pk_bf16_f32 v39, v39, v39
	v_bfe_u32 v60, v44, 16, 1
	v_bfe_u32 v67, v38, 16, 1
	v_bfe_u32 v108, v32, 16, 1
	v_lshrrev_b32_e32 v36, 16, v36
	v_lshrrev_b32_e32 v33, 16, v33
	v_lshrrev_b32_e32 v39, 16, v39
	v_lshrrev_b32_e32 v34, 16, v34
	v_add3_u32 v32, v32, v108, s68
	v_add3_u32 v38, v38, v67, s68
	v_add3_u32 v44, v44, v60, s68
	v_cvt_pk_bf16_f32 v35, v35, v35
	v_and_or_b32 v33, v35, s39, v33
	v_and_or_b32 v35, v44, s39, v34
	v_and_or_b32 v34, v38, s39, v39
	v_and_or_b32 v32, v32, s39, v36
	ds_write_b128 v37, v[32:35]
	s_nop 0
	s_nop 0
	v_cvt_pk_bf16_f32 v36, v47, v47
	v_cvt_pk_bf16_f32 v38, v48, v48
	v_bfe_u32 v34, v45, 16, 1
	v_bfe_u32 v35, v46, 16, 1
	v_add3_u32 v35, v46, v35, s68
	v_add3_u32 v34, v45, v34, s68
	v_lshrrev_b32_e32 v44, 16, v34
	v_lshrrev_b32_e32 v45, 16, v35
	v_cvt_pk_bf16_f32 v35, v51, v53
	v_cvt_pk_bf16_f32 v34, v50, v52
	v_and_or_b32 v33, v38, s39, v45
	v_and_or_b32 v32, v36, s39, v44
	ds_write_b128 v37, v[32:35] offset:16
	s_nop 0
	s_nop 0
	v_cvt_pk_bf16_f32 v36, v56, v56
	v_cvt_pk_bf16_f32 v38, v57, v57
	v_bfe_u32 v34, v54, 16, 1
	v_bfe_u32 v35, v55, 16, 1
	v_add3_u32 v35, v55, v35, s68
	v_add3_u32 v34, v54, v34, s68
	v_lshrrev_b32_e32 v44, 16, v34
	v_lshrrev_b32_e32 v45, 16, v35
	v_cvt_pk_bf16_f32 v35, v59, v63
	v_cvt_pk_bf16_f32 v34, v58, v62
	v_and_or_b32 v33, v38, s39, v45
	v_and_or_b32 v32, v36, s39, v44
	ds_write_b128 v37, v[32:35] offset:32
	s_nop 0
	s_nop 0
	v_cvt_pk_bf16_f32 v36, v114, v114
	v_cvt_pk_bf16_f32 v38, v115, v115
	v_cvt_pk_bf16_f32 v43, v116, v116
	v_cvt_pk_bf16_f32 v39, v49, v49
	v_cvt_pk_bf16_f32 v35, v65, v65
	v_cvt_pk_bf16_f32 v34, v64, v64
	v_cvt_pk_bf16_f32 v33, v117, v117
	v_cvt_pk_bf16_f32 v32, v118, v118
	v_lshrrev_b32_e32 v44, 16, v34
	v_lshrrev_b32_e32 v45, 16, v35
	v_lshrrev_b32_e32 v34, 16, v39
	v_lshrrev_b32_e32 v35, 16, v43
	v_and_or_b32 v35, v32, s39, v35
	v_and_or_b32 v34, v33, s39, v34
	v_and_or_b32 v33, v38, s39, v45
	v_and_or_b32 v32, v36, s39, v44
	ds_write_b128 v37, v[32:35] offset:48
.LBB0_498:
	s_or_b64 exec, exec, s[0:1]
	v_lshlrev_b32_e32 v56, 6, v148
	v_add3_u32 v43, s2, v56, v134
	ds_read_b128 v[32:35], v43
	v_readlane_b32 s0, v255, 7
	v_readlane_b32 s2, v255, 11
	s_add_i32 s1, 0, 0x24d00
	v_add3_u32 v44, s0, v56, v134
	ds_read_b128 v[36:39], v44
	ds_read_b128 v[44:47], v44 offset:1024
	ds_read_b128 v[48:51], v43 offset:1024
	v_add3_u32 v43, s2, v56, v42
	s_add_i32 s0, 0, 0x21400
	v_readlane_b32 s3, v255, 10
	s_waitcnt lgkmcnt(2)
	v_mfma_f32_16x16x32_bf16 v[52:55], v[32:35], v[36:39], 0
	v_lshlrev_b32_e32 v57, 6, v113
	v_mov_b32_e32 v207, v42
	s_waitcnt lgkmcnt(1)
	v_mfma_f32_16x16x32_bf16 v[32:35], v[32:35], v[44:47], 0
	s_waitcnt lgkmcnt(0)
	v_mfma_f32_16x16x32_bf16 v[36:39], v[48:51], v[36:39], 0
	v_mfma_f32_16x16x32_bf16 v[44:47], v[48:51], v[44:47], 0
	s_nop 0
	s_nop 0
	s_nop 0
	s_nop 0
	s_nop 0
	s_nop 0
	s_nop 0
	v_cvt_pk_bf16_f32 v48, v52, v53
	s_nop 0
	s_nop 0
	s_nop 0
	s_nop 0
	v_cvt_pk_bf16_f32 v49, v54, v55
	v_cvt_pk_bf16_f32 v32, v32, v33
	v_cvt_pk_bf16_f32 v33, v34, v35
	v_cvt_pk_bf16_f32 v34, v36, v37
	v_cvt_pk_bf16_f32 v35, v38, v39
	ds_write2_b64 v43, v[48:49], v[34:35] offset1:4
	v_cvt_pk_bf16_f32 v34, v44, v45
	v_cvt_pk_bf16_f32 v35, v46, v47
	v_add_u32_e32 v45, s0, v134
	s_add_i32 s0, 0, 0x24e00
	ds_write2_b64 v43, v[32:33], v[34:35] offset0:128 offset1:132
	v_add_u32_e32 v32, s1, v111
	v_add_u32_e32 v33, s0, v111
	v_add_u32_e32 v43, v45, v56
	ds_read_b32 v46, v32
	ds_read_b32 v47, v33
	ds_read_b128 v[32:35], v43
	v_add_u32_e32 v44, s2, v134
	v_add_u32_e32 v48, v44, v56
	ds_read_b128 v[36:39], v48
	s_waitcnt lgkmcnt(0)
	v_mfma_f32_16x16x32_bf16 v[32:35], v[32:35], v[36:39], 0
	v_mul_f32_e64 v47, v47, -v46
	v_readlane_b32 s2, v255, 9
	v_mul_lo_u32 v52, v205, s37
	s_nop 4
	v_mul_f32_e32 v36, v47, v32
	v_add_u32_e32 v49, s2, v112
	s_nop 0
	v_add_u32_e32 v53, 0x1200, v52
	v_cvt_pk_bf16_f32 v36, v36, v36
	v_add_u32_e32 v37, v49, v53
	v_mul_f32_e64 v32, v32, -v46
	v_add_u32_e32 v50, s3, v112
	ds_write_b16_d16_hi v37, v36
	v_cvt_pk_bf16_f32 v32, v32, v32
	v_add_u32_e32 v36, v50, v53
	v_add_u32_e32 v51, s1, v110
	ds_write_b16_d16_hi v36, v32
	v_mul_f32_e32 v32, v47, v33
	s_movk_i32 s1, 0x240
	v_bfe_u32 v36, v32, 16, 1
	v_mul_lo_u32 v54, v61, s1
	v_add3_u32 v32, v32, v36, s68
	v_add_u32_e32 v55, v49, v54
	ds_write_b16_d16_hi v55, v32 offset:4752
	v_mul_f32_e64 v32, v33, -v46
	v_bfe_u32 v33, v32, 16, 1
	v_add3_u32 v32, v32, v33, s68
	v_add_u32_e32 v56, v50, v54
	ds_write_b16_d16_hi v56, v32 offset:4752
	v_mul_f32_e32 v32, v47, v34
	v_bfe_u32 v33, v32, 16, 1
	v_add3_u32 v32, v32, v33, s68
	ds_write_b16_d16_hi v55, v32 offset:4896
	v_mul_f32_e64 v32, v34, -v46
	v_bfe_u32 v33, v32, 16, 1
	v_add3_u32 v32, v32, v33, s68
	ds_write_b16_d16_hi v56, v32 offset:4896
	v_mul_f32_e32 v32, v47, v35
	v_bfe_u32 v33, v32, 16, 1
	v_add3_u32 v32, v32, v33, s68
	ds_write_b16_d16_hi v55, v32 offset:5040
	v_mul_f32_e64 v32, v35, -v46
	v_bfe_u32 v33, v32, 16, 1
	v_add3_u32 v32, v32, v33, s68
	ds_write_b16_d16_hi v56, v32 offset:5040
	v_add_u32_e32 v45, v45, v57
	ds_read_b32 v51, v51
	ds_read_b128 v[32:35], v45
	ds_read_b128 v[36:39], v48
	s_waitcnt lgkmcnt(0)
; #define LAS __attribute__((address_space(3)))
; DI unsigned f2bf(float f) { unsigned u = __float_as_uint(f); u += 0x7FFFu + ((u >> 16) & 1u); return u >> 16; }
; DI void lds_barrier() { asm volatile("s_waitcnt lgkmcnt(0)" ::: "memory"); __builtin_amdgcn_s_barrier(); asm volatile("" ::: "memory"); }
; #define MFMA16(a, b, c) __builtin_amdgcn_mfma_f32_16x16x32_bf16((a), (b), (c), 0, 0, 0)
; DI void gdn_unit(const Params& P, bf16_t* proj, const float* gb, int b, int h, LAS unsigned char* lds) {
;     ...
;                 for (int ti = 0; ti < 2; ++ti) {
;                     const f32x4 t = MFMA16(ldsfrag(T22n + (ti * 16 + fr) * 64 + fq * 16), ldsfrag(Xt + (tj * 16 + fr) * 64 + fq * 16), ((f32x4){0.f, 0.f, 0.f, 0.f}));
; #pragma unroll
;                     for (int jj = 0; jj < 4; ++jj) {
;                         const int row = 32 + ti * 16 + fq * 4 + jj;
;                         *(LAS bf16_t*)(lds + TP_OFF + row * 144 + col * 2) = (bf16_t)f2bf(t[jj] * c1);
;                         *(LAS bf16_t*)(lds + TPP_OFF + row * 144 + col * 2) = (bf16_t)f2bf(t[jj] * c2);
;                     }
;                 }
;             }
;         }
;         lds_barrier();
;         f32x4 uacc[4];
;         {
;             bf16x8 vb[2], kb[2];
; #pragma unroll
;             for (int ks = 0; ks < 2; ++ks) { vb[ks] = ldsfrag(lds + VT_OFF + (16 * wave + fr) * 144 + (ks * 32 + fq * 8) * 2); kb[ks] = ldsfrag(lds + KT_OFF + (16 * wave + fr) * 144 + (ks * 32 + fq * 8) * 2); }
; #pragma unroll
;             for (int tt = 0; tt < 4; ++tt) {
;                 f32x4 au = (f32x4){0.f, 0.f, 0.f, 0.f}, aw = (f32x4){0.f, 0.f, 0.f, 0.f};
; #pragma unroll
;                 for (int ks = 0; ks < 2; ++ks) {
;                     au = MFMA16(ldsfrag(lds + TPP_OFF + (tt * 16 + fr) * 144 + (ks * 32 + fq * 8) * 2), vb[ks], au);
;                     aw = MFMA16(ldsfrag(lds + TP_OFF + (tt * 16 + fr) * 144 + (ks * 32 + fq * 8) * 2), kb[ks], aw);
;                 }
;                 uacc[tt] = au;
; #pragma unroll
;                 for (int jj = 0; jj < 4; ++jj) *(LAS bf16_t*)(lds + K_OFF + (tt * 16 + fq * 4 + jj) * 272 + (16 * wave + fr) * 2) = (bf16_t)f2bf(aw[jj]);
;             }
	v_mfma_f32_16x16x32_bf16 v[32:35], v[32:35], v[36:39], 0
	v_add_u32_e32 v48, 0x1b00, v52
	v_add_u32_e32 v44, v44, v57
	s_nop 5
	v_mul_f32_e32 v36, v47, v32
	s_nop 0
	v_cvt_pk_bf16_f32 v36, v36, v36
	v_add_u32_e32 v37, v49, v48
	v_mul_f32_e64 v32, v32, -v46
	ds_write_b16_d16_hi v37, v36
	s_nop 0
	v_cvt_pk_bf16_f32 v32, v32, v32
	v_add_u32_e32 v36, v50, v48
	ds_write_b16_d16_hi v36, v32
	v_mul_f32_e32 v32, v47, v33
	v_bfe_u32 v36, v32, 16, 1
	v_add3_u32 v32, v32, v36, s68
	ds_write_b16_d16_hi v55, v32 offset:7056
	v_mul_f32_e64 v32, v33, -v46
	v_bfe_u32 v33, v32, 16, 1
	v_add3_u32 v32, v32, v33, s68
	ds_write_b16_d16_hi v56, v32 offset:7056
	v_mul_f32_e32 v32, v47, v34
	v_bfe_u32 v33, v32, 16, 1
	v_add3_u32 v32, v32, v33, s68
	ds_write_b16_d16_hi v55, v32 offset:7200
	v_mul_f32_e64 v32, v34, -v46
	v_bfe_u32 v33, v32, 16, 1
	v_add3_u32 v32, v32, v33, s68
	ds_write_b16_d16_hi v56, v32 offset:7200
	v_mul_f32_e32 v32, v47, v35
	v_bfe_u32 v33, v32, 16, 1
	v_add3_u32 v32, v32, v33, s68
	ds_write_b16_d16_hi v55, v32 offset:7344
	v_mul_f32_e64 v32, v35, -v46
	v_bfe_u32 v33, v32, 16, 1
	v_add3_u32 v32, v32, v33, s68
	ds_write_b16_d16_hi v56, v32 offset:7344
	v_add_u32_e32 v36, s0, v110
	ds_read_b128 v[32:35], v43
	ds_read_b32 v43, v36
	ds_read_b128 v[36:39], v44
	s_waitcnt lgkmcnt(0)
	v_mfma_f32_16x16x32_bf16 v[32:35], v[32:35], v[36:39], 0
	v_mul_f32_e64 v43, v43, -v51
	v_add_u32_e32 v46, s2, v66
	v_add_u32_e32 v47, s3, v66
	s_nop 4
	v_mul_f32_e32 v36, v43, v32
	s_nop 0
	v_cvt_pk_bf16_f32 v36, v36, v36
	v_add_u32_e32 v37, v46, v53
	v_mul_f32_e64 v32, v32, -v51
	ds_write_b16_d16_hi v37, v36
	s_nop 0
	v_cvt_pk_bf16_f32 v32, v32, v32
	v_add_u32_e32 v36, v47, v53
	ds_write_b16_d16_hi v36, v32
	v_mul_f32_e32 v32, v43, v33
	v_bfe_u32 v36, v32, 16, 1
	v_add3_u32 v32, v32, v36, s68
	v_add_u32_e32 v49, v46, v54
	ds_write_b16_d16_hi v49, v32 offset:4752
	v_mul_f32_e64 v32, v33, -v51
	v_bfe_u32 v33, v32, 16, 1
	v_add3_u32 v32, v32, v33, s68
	v_add_u32_e32 v50, v47, v54
	ds_write_b16_d16_hi v50, v32 offset:4752
	v_mul_f32_e32 v32, v43, v34
	v_bfe_u32 v33, v32, 16, 1
	v_add3_u32 v32, v32, v33, s68
	ds_write_b16_d16_hi v49, v32 offset:4896
	v_mul_f32_e64 v32, v34, -v51
	v_bfe_u32 v33, v32, 16, 1
	v_add3_u32 v32, v32, v33, s68
	ds_write_b16_d16_hi v50, v32 offset:4896
	v_mul_f32_e32 v32, v43, v35
	v_bfe_u32 v33, v32, 16, 1
	v_add3_u32 v32, v32, v33, s68
	ds_write_b16_d16_hi v49, v32 offset:5040
	v_mul_f32_e64 v32, v35, -v51
	v_bfe_u32 v33, v32, 16, 1
	v_add3_u32 v32, v32, v33, s68
	ds_write_b16_d16_hi v50, v32 offset:5040
	ds_read_b128 v[32:35], v45
	ds_read_b128 v[36:39], v44
	s_waitcnt lgkmcnt(0)
	v_mfma_f32_16x16x32_bf16 v[32:35], v[32:35], v[36:39], 0
	s_nop 7
	v_mul_f32_e32 v36, v43, v32
	s_nop 0
	v_cvt_pk_bf16_f32 v36, v36, v36
	v_add_u32_e32 v37, v46, v48
	v_mul_f32_e64 v32, v32, -v51
	ds_write_b16_d16_hi v37, v36
	s_nop 0
	v_cvt_pk_bf16_f32 v32, v32, v32
	v_add_u32_e32 v36, v47, v48
	ds_write_b16_d16_hi v36, v32
	v_mul_f32_e32 v32, v43, v33
	v_bfe_u32 v36, v32, 16, 1
	v_add3_u32 v32, v32, v36, s68
	ds_write_b16_d16_hi v49, v32 offset:7056
	v_mul_f32_e64 v32, v33, -v51
	v_bfe_u32 v33, v32, 16, 1
	v_add3_u32 v32, v32, v33, s68
	ds_write_b16_d16_hi v50, v32 offset:7056
	v_mul_f32_e32 v32, v43, v34
	v_bfe_u32 v33, v32, 16, 1
	v_add3_u32 v32, v32, v33, s68
	ds_write_b16_d16_hi v49, v32 offset:7200
	v_mul_f32_e64 v32, v34, -v51
	v_bfe_u32 v33, v32, 16, 1
	v_add3_u32 v32, v32, v33, s68
	ds_write_b16_d16_hi v50, v32 offset:7200
	v_mul_f32_e32 v32, v43, v35
	v_bfe_u32 v33, v32, 16, 1
	v_add3_u32 v32, v32, v33, s68
	ds_write_b16_d16_hi v49, v32 offset:7344
	v_mul_f32_e64 v32, v35, -v51
	v_bfe_u32 v33, v32, 16, 1
	v_add3_u32 v32, v32, v33, s68
	ds_write_b16_d16_hi v50, v32 offset:7344
	v_mov_b32_e32 v50, v40
	v_mov_b32_e32 v49, v41
.LBB0_499:
	v_mul_u32_u24_e32 v150, 0x90, v148
	v_readlane_b32 s16, v255, 10
	s_waitcnt lgkmcnt(0)
	s_barrier
	v_or_b32_e32 v51, s4, v148
	v_add3_u32 v44, s16, v150, v134
	ds_read_b128 v[32:35], v44
	v_mul_lo_u32 v60, v51, s37
	v_add_u32_e32 v48, 0, v60
	v_readlane_b32 s3, v255, 9
	v_add_u32_e32 v64, v48, v134
	ds_read_b128 v[40:43], v64 offset:53248
	v_add3_u32 v62, s3, v150, v134
	ds_read_b128 v[36:39], v62
	ds_read_b128 v[52:55], v64 offset:34816
	ds_read_b128 v[44:47], v44 offset:64
	ds_read_b128 v[56:59], v64 offset:53312
	ds_read_b128 v[108:111], v62 offset:64
	ds_read_b128 v[112:115], v64 offset:34880
	s_waitcnt lgkmcnt(6)
	v_mfma_f32_16x16x32_bf16 v[32:35], v[32:35], v[40:43], 0
	s_movk_i32 s0, 0xff72
	v_mad_u64_u32 v[62:63], s[0:1], v51, s0, v[48:49]
	s_waitcnt lgkmcnt(4)
	v_mfma_f32_16x16x32_bf16 v[36:39], v[36:39], v[52:55], 0
	s_movk_i32 s0, 0x440
	v_mad_u64_u32 v[66:67], s[0:1], v61, s0, v[62:63]
	s_waitcnt lgkmcnt(2)
	v_mfma_f32_16x16x32_bf16 v[44:47], v[44:47], v[56:59], v[32:35]
	v_mad_u32_u24 v224, v148, s37, v252
	v_add3_u32 v65, s3, v224, v134
	v_add3_u32 v63, s16, v224, v134
	s_waitcnt lgkmcnt(0)
	v_mfma_f32_16x16x32_bf16 v[32:35], v[108:111], v[112:115], v[36:39]
	s_movk_i32 s2, 0x110
	v_mad_u32_u24 v153, v148, s37, v164
	v_mad_u32_u24 v152, v148, s37, v167
	v_mul_lo_u32 v51, v51, s2
	v_lshlrev_b32_e32 v225, 2, v205
	s_nop 2
	v_bfe_u32 v36, v32, 16, 1
	v_add3_u32 v32, v32, v36, s68
	ds_write_b16_d16_hi v66, v32 offset:17408
	v_bfe_u32 v32, v33, 16, 1
	v_add3_u32 v32, v33, v32, s68
	ds_write_b16_d16_hi v66, v32 offset:17680
	v_bfe_u32 v32, v34, 16, 1
	v_add3_u32 v32, v34, v32, s68
	ds_write_b16_d16_hi v66, v32 offset:17952
	v_bfe_u32 v32, v35, 16, 1
	v_add3_u32 v32, v35, v32, s68
	ds_write_b16_d16_hi v66, v32 offset:18224
	ds_read_b128 v[36:39], v65
	ds_read_b128 v[32:35], v63
	s_waitcnt lgkmcnt(1)
; #define LAS __attribute__((address_space(3)))
; DI unsigned f2bf(float f) { unsigned u = __float_as_uint(f); u += 0x7FFFu + ((u >> 16) & 1u); return u >> 16; }
; DI unsigned pk2(float lo, float hi) { return f2bf(lo) | (f2bf(hi) << 16); }
; DI void lds_barrier() { asm volatile("s_waitcnt lgkmcnt(0)" ::: "memory"); __builtin_amdgcn_s_barrier(); asm volatile("" ::: "memory"); }
; DI void gdn_unit(const Params& P, bf16_t* proj, const float* gb, int b, int h, LAS unsigned char* lds) {
;     ...
;             for (int tt = 0; tt < 4; ++tt) {
;                 f32x4 au = (f32x4){0.f, 0.f, 0.f, 0.f}, aw = (f32x4){0.f, 0.f, 0.f, 0.f};
; #pragma unroll
;                 for (int ks = 0; ks < 2; ++ks) {
;                     au = MFMA16(ldsfrag(lds + TPP_OFF + (tt * 16 + fr) * 144 + (ks * 32 + fq * 8) * 2), vb[ks], au);
;                     aw = MFMA16(ldsfrag(lds + TP_OFF + (tt * 16 + fr) * 144 + (ks * 32 + fq * 8) * 2), kb[ks], aw);
;                 }
;                 uacc[tt] = au;
; #pragma unroll
;                 for (int jj = 0; jj < 4; ++jj) *(LAS bf16_t*)(lds + K_OFF + (tt * 16 + fq * 4 + jj) * 272 + (16 * wave + fr) * 2) = (bf16_t)f2bf(aw[jj]);
;             }
;         }
;         lds_barrier();
;         {
;             bf16x8 sb[4];
; #pragma unroll
;             for (int ks = 0; ks < 4; ++ks) sb[ks] = ldsfrag(lds + ST_OFF + (16 * wave + fr) * 272 + (ks * 32 + fq * 8) * 2);
; #pragma unroll
;             for (int tt = 0; tt < 4; ++tt) {
;                 f32x4 a = (f32x4){0.f, 0.f, 0.f, 0.f};
;                 bf16x8 wf[4];
; #pragma unroll
;                 for (int ks = 0; ks < 4; ++ks) wf[ks] = ldsfrag(lds + K_OFF + (tt * 16 + fr) * 272 + (ks * 32 + fq * 8) * 2);
;                 const f32x4 d4 = *(const LAS f32x4*)(djs + tt * 16 + fq * 4);
; #pragma unroll
;                 for (int ks = 0; ks < 4; ++ks) a = MFMA16(wf[ks], sb[ks], a);
;                 const f32x4 vn = uacc[tt] - a;
;                 u32x2 p0, p1;
;                 p0.x = pk2(vn[0], vn[1]); p0.y = pk2(vn[2], vn[3]);
;                 p1.x = pk2(vn[0] * d4[0], vn[1] * d4[1]); p1.y = pk2(vn[2] * d4[2], vn[3] * d4[3]);
;                 *(LAS u32x2*)(lds + VN_OFF + (16 * wave + fr) * 144 + (tt * 16 + fq * 4) * 2) = p0;
;                 *(LAS u32x2*)(lds + VNS_OFF + (16 * wave + fr) * 144 + (tt * 16 + fq * 4) * 2) = p1;
;             }
	v_mfma_f32_16x16x32_bf16 v[108:111], v[36:39], v[52:55], 0
	ds_read_b128 v[36:39], v63 offset:64
	v_add_u32_e32 v151, s3, v60
	s_waitcnt lgkmcnt(1)
	v_mfma_f32_16x16x32_bf16 v[32:35], v[32:35], v[40:43], 0
	s_waitcnt lgkmcnt(0)
	v_mfma_f32_16x16x32_bf16 v[36:39], v[36:39], v[56:59], v[32:35]
	s_nop 5
	ds_read_b128 v[32:35], v65 offset:64
	s_waitcnt lgkmcnt(0)
	v_mfma_f32_16x16x32_bf16 v[32:35], v[32:35], v[112:115], v[108:111]
	v_add3_u32 v65, s3, v153, v134
	s_nop 6
	v_bfe_u32 v63, v32, 16, 1
	v_add3_u32 v32, v32, v63, s68
	v_mad_u64_u32 v[108:109], s[0:1], v205, s2, v[62:63]
	ds_write_b16_d16_hi v108, v32 offset:21760
	v_bfe_u32 v32, v33, 16, 1
	v_add3_u32 v32, v33, v32, s68
	ds_write_b16_d16_hi v66, v32 offset:22032
	v_bfe_u32 v32, v34, 16, 1
	v_add3_u32 v32, v34, v32, s68
	ds_write_b16_d16_hi v66, v32 offset:22304
	v_bfe_u32 v32, v35, 16, 1
	v_add3_u32 v32, v35, v32, s68
	ds_write_b16_d16_hi v66, v32 offset:22576
	v_add3_u32 v63, s16, v153, v134
	ds_read_b128 v[32:35], v63
	ds_read_b128 v[116:119], v63 offset:64
	s_waitcnt lgkmcnt(1)
	v_mfma_f32_16x16x32_bf16 v[32:35], v[32:35], v[40:43], 0
	ds_read_b128 v[108:111], v65
	s_waitcnt lgkmcnt(1)
	v_mfma_f32_16x16x32_bf16 v[32:35], v[116:119], v[56:59], v[32:35]
	ds_read_b128 v[116:119], v65 offset:64
	v_add3_u32 v65, s3, v152, v134
	s_mov_b32 s3, 0x18001000
	s_waitcnt lgkmcnt(1)
	v_mfma_f32_16x16x32_bf16 v[108:111], v[108:111], v[52:55], 0
	s_waitcnt lgkmcnt(0)
	v_mfma_f32_16x16x32_bf16 v[108:111], v[116:119], v[112:115], v[108:111]
	s_nop 7
	v_bfe_u32 v63, v108, 16, 1
	v_add3_u32 v63, v108, v63, s68
	v_mad_u64_u32 v[66:67], s[0:1], v50, s2, v[62:63]
	ds_write_b16_d16_hi v66, v63 offset:17408
	v_bfe_u32 v63, v109, 16, 1
	v_add3_u32 v63, v109, v63, s68
	ds_write_b16_d16_hi v66, v63 offset:17680
	v_bfe_u32 v63, v110, 16, 1
	v_add3_u32 v63, v110, v63, s68
	ds_write_b16_d16_hi v66, v63 offset:17952
	v_bfe_u32 v63, v111, 16, 1
	v_add3_u32 v63, v111, v63, s68
	ds_write_b16_d16_hi v66, v63 offset:18224
	v_add3_u32 v63, s16, v152, v134
	ds_read_b128 v[108:111], v63
	s_waitcnt lgkmcnt(0)
	v_mfma_f32_16x16x32_bf16 v[40:43], v[108:111], v[40:43], 0
	ds_read_b128 v[108:111], v65
	s_waitcnt lgkmcnt(0)
	v_mfma_f32_16x16x32_bf16 v[52:55], v[108:111], v[52:55], 0
	ds_read_b128 v[108:111], v65 offset:64
	ds_read_b128 v[116:119], v63 offset:64
	v_add_u32_e32 v65, 0, v225
	v_add_u32_e32 v227, 0x24e00, v65
	s_waitcnt lgkmcnt(1)
	v_mfma_f32_16x16x32_bf16 v[52:55], v[108:111], v[112:115], v[52:55]
	s_waitcnt lgkmcnt(0)
	v_mfma_f32_16x16x32_bf16 v[40:43], v[116:119], v[56:59], v[40:43]
	s_nop 5
	v_bfe_u32 v63, v52, 16, 1
	v_add3_u32 v52, v52, v63, s68
	v_mad_u64_u32 v[62:63], s[0:1], v49, s2, v[62:63]
	ds_write_b16_d16_hi v62, v52 offset:17408
	v_bfe_u32 v52, v53, 16, 1
	v_add3_u32 v52, v53, v52, s68
	ds_write_b16_d16_hi v62, v52 offset:17680
	v_bfe_u32 v52, v54, 16, 1
	v_add3_u32 v52, v54, v52, s68
	ds_write_b16_d16_hi v62, v52 offset:17952
	v_bfe_u32 v52, v55, 16, 1
	v_add3_u32 v52, v55, v52, s68
	ds_write_b16_d16_hi v62, v52 offset:18224
	s_waitcnt lgkmcnt(0)
	s_barrier
	ds_read_b128 v[108:111], v149 offset:17408
	s_add_i32 s0, 0, 0x16000
	v_add_u32_e32 v219, s0, v51
	v_add_u32_e32 v52, v219, v134
	ds_read_b128 v[112:115], v52
	ds_read_b128 v[54:57], v149 offset:17472
	ds_read_b128 v[116:119], v52 offset:64
	s_waitcnt lgkmcnt(2)
	v_mfma_f32_16x16x32_bf16 v[108:111], v[108:111], v[112:115], 0
	ds_read_b128 v[120:123], v149 offset:17536
	ds_read_b128 v[124:127], v52 offset:128
	ds_read_b128 v[128:131], v149 offset:17600
	v_add_u32_e32 v51, 0x24f00, v65
	s_add_u32 s0, s5, s14
	s_waitcnt lgkmcnt(3)
	v_mfma_f32_16x16x32_bf16 v[54:57], v[54:57], v[116:119], v[108:111]
	s_addc_u32 s1, s69, s15
	s_mov_b32 s2, 0x18003000
	s_nop 0
	ds_read_b128 v[108:111], v52 offset:192
	s_waitcnt lgkmcnt(2)
	v_mfma_f32_16x16x32_bf16 v[54:57], v[120:123], v[124:127], v[54:57]
	ds_read_b128 v[120:123], v51
	s_waitcnt lgkmcnt(1)
	v_mfma_f32_16x16x32_bf16 v[54:57], v[128:131], v[108:111], v[54:57]
	s_nop 7
	v_sub_f32_e32 v47, v47, v57
	v_sub_f32_e32 v45, v45, v55
	v_sub_f32_e32 v46, v46, v56
	s_nop 0
	v_sub_f32_e32 v44, v44, v54
	v_and_b32_sdwa v53, v46, v166 dst_sel:DWORD dst_unused:UNUSED_PAD src0_sel:WORD_1 src1_sel:DWORD
	s_nop 0
	v_cvt_pk_bf16_f32 v55, v47, v47
	v_and_b32_sdwa v54, v44, v166 dst_sel:DWORD dst_unused:UNUSED_PAD src0_sel:WORD_1 src1_sel:DWORD
	v_add3_u32 v53, v46, v53, s68
	v_cvt_pk_bf16_f32 v56, v45, v45
	v_and_b32_e32 v55, 0xffff0000, v55
	s_waitcnt lgkmcnt(0)
	v_pk_mul_f32 v[46:47], v[122:123], v[46:47]
	v_add3_u32 v54, v44, v54, s68
	v_and_b32_e32 v56, 0xffff0000, v56
	v_or_b32_sdwa v55, v55, v53 dst_sel:DWORD dst_unused:UNUSED_PAD src0_sel:DWORD src1_sel:WORD_1
	v_pk_mul_f32 v[44:45], v[120:121], v[44:45]
	v_and_b32_sdwa v53, v46, v166 dst_sel:DWORD dst_unused:UNUSED_PAD src0_sel:WORD_1 src1_sel:DWORD
	v_or_b32_sdwa v54, v56, v54 dst_sel:DWORD dst_unused:UNUSED_PAD src0_sel:DWORD src1_sel:WORD_1
	v_and_b32_sdwa v56, v44, v166 dst_sel:DWORD dst_unused:UNUSED_PAD src0_sel:WORD_1 src1_sel:DWORD
	v_add3_u32 v46, v46, v53, s68
	v_add3_u32 v44, v44, v56, s68
	v_cvt_pk_bf16_f32 v47, v47, v47
	v_cvt_pk_bf16_f32 v45, v45, v45
	v_and_b32_e32 v47, 0xffff0000, v47
	v_and_b32_e32 v53, 0xffff0000, v45
	v_or_b32_sdwa v45, v47, v46 dst_sel:DWORD dst_unused:UNUSED_PAD src0_sel:DWORD src1_sel:WORD_1
	v_add_u32_e32 v46, v48, v207
	v_or_b32_sdwa v44, v53, v44 dst_sel:DWORD dst_unused:UNUSED_PAD src0_sel:DWORD src1_sel:WORD_1
	ds_write_b64 v46, v[54:55] offset:53248
	v_add_u32_e32 v46, v151, v207
	ds_write_b64 v46, v[44:45]
	ds_read_b128 v[44:47], v149 offset:21760
	ds_read_b128 v[54:57], v149 offset:21824
	s_waitcnt lgkmcnt(1)
; #define LAS __attribute__((address_space(3)))
; DI unsigned pk2(float lo, float hi) { return f2bf(lo) | (f2bf(hi) << 16); }
; DI void lds_barrier() { asm volatile("s_waitcnt lgkmcnt(0)" ::: "memory"); __builtin_amdgcn_s_barrier(); asm volatile("" ::: "memory"); }
; #define MFMA16(a, b, c) __builtin_amdgcn_mfma_f32_16x16x32_bf16((a), (b), (c), 0, 0, 0)
; DI void gdn_unit(const Params& P, bf16_t* proj, const float* gb, int b, int h, LAS unsigned char* lds) {
;     ...
;             for (int tt = 0; tt < 4; ++tt) {
;                 f32x4 a = (f32x4){0.f, 0.f, 0.f, 0.f};
;                 bf16x8 wf[4];
; #pragma unroll
;                 for (int ks = 0; ks < 4; ++ks) wf[ks] = ldsfrag(lds + K_OFF + (tt * 16 + fr) * 272 + (ks * 32 + fq * 8) * 2);
;                 const f32x4 d4 = *(const LAS f32x4*)(djs + tt * 16 + fq * 4);
; #pragma unroll
;                 for (int ks = 0; ks < 4; ++ks) a = MFMA16(wf[ks], sb[ks], a);
;                 const f32x4 vn = uacc[tt] - a;
;                 u32x2 p0, p1;
;                 p0.x = pk2(vn[0], vn[1]); p0.y = pk2(vn[2], vn[3]);
;                 p1.x = pk2(vn[0] * d4[0], vn[1] * d4[1]); p1.y = pk2(vn[2] * d4[2], vn[3] * d4[3]);
;                 *(LAS u32x2*)(lds + VN_OFF + (16 * wave + fr) * 144 + (tt * 16 + fq * 4) * 2) = p0;
;                 *(LAS u32x2*)(lds + VNS_OFF + (16 * wave + fr) * 144 + (tt * 16 + fq * 4) * 2) = p1;
;             }
;         }
;         lds_barrier();
;         f32x4 oacc[4];
;         unsigned zr[4][4];
;         const bf16_t* zbase = proj + (size_t)t0 * PJ1 + 3072 + h * 128 + 16 * wave;
;         const int zoffl = fq * 4 * PJ1 + fr;
;         {
; #pragma unroll
;             for (int tt = 0; tt < 4; ++tt)
; #pragma unroll
;                 for (int jj = 0; jj < 4; ++jj) zr[tt][jj] = zbase[(tt * 16 + jj) * PJ1 + zoffl];
	v_mfma_f32_16x16x32_bf16 v[44:47], v[44:47], v[112:115], 0
	s_waitcnt lgkmcnt(0)
	v_mfma_f32_16x16x32_bf16 v[44:47], v[54:57], v[116:119], v[44:47]
	ds_read_b128 v[54:57], v149 offset:21888
	s_waitcnt lgkmcnt(0)
	v_mfma_f32_16x16x32_bf16 v[44:47], v[54:57], v[124:127], v[44:47]
	ds_read_b128 v[54:57], v149 offset:21952
	ds_read_b128 v[120:123], v51 offset:64
	s_waitcnt lgkmcnt(1)
	v_mfma_f32_16x16x32_bf16 v[44:47], v[54:57], v[108:111], v[44:47]
	s_nop 7
	v_sub_f32_e32 v36, v36, v44
	v_sub_f32_e32 v37, v37, v45
	v_sub_f32_e32 v39, v39, v47
	v_and_b32_sdwa v45, v36, v166 dst_sel:DWORD dst_unused:UNUSED_PAD src0_sel:WORD_1 src1_sel:DWORD
	v_sub_f32_e32 v38, v38, v46
	v_add3_u32 v46, v36, v45, s68
	s_nop 0
	s_nop 0
	v_and_b32_sdwa v44, v38, v166 dst_sel:DWORD dst_unused:UNUSED_PAD src0_sel:WORD_1 src1_sel:DWORD
	v_cvt_pk_bf16_f32 v45, v39, v39
	v_cvt_pk_bf16_f32 v47, v37, v37
	v_add3_u32 v44, v38, v44, s68
	v_and_b32_e32 v45, 0xffff0000, v45
	v_and_b32_e32 v47, 0xffff0000, v47
	s_waitcnt lgkmcnt(0)
	v_pk_mul_f32 v[38:39], v[122:123], v[38:39]
	v_or_b32_sdwa v45, v45, v44 dst_sel:DWORD dst_unused:UNUSED_PAD src0_sel:DWORD src1_sel:WORD_1
	v_or_b32_sdwa v44, v47, v46 dst_sel:DWORD dst_unused:UNUSED_PAD src0_sel:DWORD src1_sel:WORD_1
	v_pk_mul_f32 v[36:37], v[120:121], v[36:37]
	v_and_b32_sdwa v46, v38, v166 dst_sel:DWORD dst_unused:UNUSED_PAD src0_sel:WORD_1 src1_sel:DWORD
	v_and_b32_sdwa v47, v36, v166 dst_sel:DWORD dst_unused:UNUSED_PAD src0_sel:WORD_1 src1_sel:DWORD
	v_add3_u32 v38, v38, v46, s68
	v_add3_u32 v36, v36, v47, s68
	v_cvt_pk_bf16_f32 v39, v39, v39
	v_cvt_pk_bf16_f32 v37, v37, v37
	v_and_b32_e32 v39, 0xffff0000, v39
	v_and_b32_e32 v46, 0xffff0000, v37
	v_or_b32_sdwa v37, v39, v38 dst_sel:DWORD dst_unused:UNUSED_PAD src0_sel:DWORD src1_sel:WORD_1
	v_lshl_add_u32 v38, v205, 1, 32
	v_or_b32_sdwa v36, v46, v36 dst_sel:DWORD dst_unused:UNUSED_PAD src0_sel:DWORD src1_sel:WORD_1
	v_add_u32_e32 v39, v48, v38
	v_add_u32_e32 v38, v151, v38
	ds_write_b64 v39, v[44:45] offset:53248
	ds_write_b64 v38, v[36:37]
	ds_read_b128 v[36:39], v149 offset:26112
	ds_read_b128 v[44:47], v149 offset:26176
	s_waitcnt lgkmcnt(1)
	v_mfma_f32_16x16x32_bf16 v[36:39], v[36:39], v[112:115], 0
	s_waitcnt lgkmcnt(0)
	v_mfma_f32_16x16x32_bf16 v[36:39], v[44:47], v[116:119], v[36:39]
	ds_read_b128 v[44:47], v149 offset:26240
	s_waitcnt lgkmcnt(0)
	v_mfma_f32_16x16x32_bf16 v[36:39], v[44:47], v[124:127], v[36:39]
	ds_read_b128 v[44:47], v149 offset:26304
	ds_read_b128 v[54:57], v51 offset:128
	s_waitcnt lgkmcnt(1)
	v_mfma_f32_16x16x32_bf16 v[36:39], v[44:47], v[108:111], v[36:39]
	s_nop 7
	v_sub_f32_e32 v32, v32, v36
	v_sub_f32_e32 v33, v33, v37
	v_sub_f32_e32 v35, v35, v39
	v_and_b32_sdwa v37, v32, v166 dst_sel:DWORD dst_unused:UNUSED_PAD src0_sel:WORD_1 src1_sel:DWORD
	v_sub_f32_e32 v34, v34, v38
	v_add3_u32 v38, v32, v37, s68
	s_nop 0
	s_nop 0
	v_and_b32_sdwa v36, v34, v166 dst_sel:DWORD dst_unused:UNUSED_PAD src0_sel:WORD_1 src1_sel:DWORD
	v_cvt_pk_bf16_f32 v37, v35, v35
	v_cvt_pk_bf16_f32 v39, v33, v33
	v_add3_u32 v36, v34, v36, s68
	v_and_b32_e32 v37, 0xffff0000, v37
	v_and_b32_e32 v39, 0xffff0000, v39
	s_waitcnt lgkmcnt(0)
	v_pk_mul_f32 v[34:35], v[56:57], v[34:35]
	v_or_b32_sdwa v37, v37, v36 dst_sel:DWORD dst_unused:UNUSED_PAD src0_sel:DWORD src1_sel:WORD_1
	v_or_b32_sdwa v36, v39, v38 dst_sel:DWORD dst_unused:UNUSED_PAD src0_sel:DWORD src1_sel:WORD_1
	v_pk_mul_f32 v[32:33], v[54:55], v[32:33]
	v_and_b32_sdwa v38, v34, v166 dst_sel:DWORD dst_unused:UNUSED_PAD src0_sel:WORD_1 src1_sel:DWORD
	v_and_b32_sdwa v39, v32, v166 dst_sel:DWORD dst_unused:UNUSED_PAD src0_sel:WORD_1 src1_sel:DWORD
	v_add3_u32 v34, v34, v38, s68
	v_add3_u32 v32, v32, v39, s68
	v_cvt_pk_bf16_f32 v35, v35, v35
	v_cvt_pk_bf16_f32 v33, v33, v33
	v_and_b32_e32 v35, 0xffff0000, v35
	v_and_b32_e32 v38, 0xffff0000, v33
	v_or_b32_sdwa v33, v35, v34 dst_sel:DWORD dst_unused:UNUSED_PAD src0_sel:DWORD src1_sel:WORD_1
	v_lshlrev_b32_e32 v34, 1, v50
	v_or_b32_sdwa v32, v38, v32 dst_sel:DWORD dst_unused:UNUSED_PAD src0_sel:DWORD src1_sel:WORD_1
	v_add_u32_e32 v35, v48, v34
	v_add_u32_e32 v34, v151, v34
	ds_write_b64 v35, v[36:37] offset:53248
	ds_write_b64 v34, v[32:33]
	ds_read_b128 v[32:35], v149 offset:30464
	ds_read_b128 v[36:39], v149 offset:30528
	s_waitcnt lgkmcnt(1)
	v_mfma_f32_16x16x32_bf16 v[32:35], v[32:35], v[112:115], 0
	s_waitcnt lgkmcnt(0)
	v_mfma_f32_16x16x32_bf16 v[32:35], v[36:39], v[116:119], v[32:35]
	ds_read_b128 v[36:39], v149 offset:30592
	s_waitcnt lgkmcnt(0)
	v_mfma_f32_16x16x32_bf16 v[32:35], v[36:39], v[124:127], v[32:35]
	ds_read_b128 v[36:39], v149 offset:30656
	ds_read_b128 v[44:47], v51 offset:192
	s_waitcnt lgkmcnt(1)
	v_mfma_f32_16x16x32_bf16 v[32:35], v[36:39], v[108:111], v[32:35]
	s_nop 7
	v_sub_f32_e32 v32, v40, v32
	v_sub_f32_e32 v33, v41, v33
	v_sub_f32_e32 v35, v43, v35
	v_and_b32_sdwa v37, v32, v166 dst_sel:DWORD dst_unused:UNUSED_PAD src0_sel:WORD_1 src1_sel:DWORD
	v_sub_f32_e32 v34, v42, v34
	v_add3_u32 v38, v32, v37, s68
	s_nop 0
	s_nop 0
	v_and_b32_sdwa v36, v34, v166 dst_sel:DWORD dst_unused:UNUSED_PAD src0_sel:WORD_1 src1_sel:DWORD
	v_cvt_pk_bf16_f32 v37, v35, v35
	v_cvt_pk_bf16_f32 v39, v33, v33
	v_add3_u32 v36, v34, v36, s68
	v_and_b32_e32 v37, 0xffff0000, v37
	v_and_b32_e32 v39, 0xffff0000, v39
	s_waitcnt lgkmcnt(0)
	v_pk_mul_f32 v[34:35], v[46:47], v[34:35]
	v_or_b32_sdwa v37, v37, v36 dst_sel:DWORD dst_unused:UNUSED_PAD src0_sel:DWORD src1_sel:WORD_1
	v_or_b32_sdwa v36, v39, v38 dst_sel:DWORD dst_unused:UNUSED_PAD src0_sel:DWORD src1_sel:WORD_1
	v_pk_mul_f32 v[32:33], v[44:45], v[32:33]
	v_and_b32_sdwa v38, v34, v166 dst_sel:DWORD dst_unused:UNUSED_PAD src0_sel:WORD_1 src1_sel:DWORD
	v_and_b32_sdwa v39, v32, v166 dst_sel:DWORD dst_unused:UNUSED_PAD src0_sel:WORD_1 src1_sel:DWORD
	v_add3_u32 v34, v34, v38, s68
	v_add3_u32 v32, v32, v39, s68
	v_cvt_pk_bf16_f32 v35, v35, v35
	v_cvt_pk_bf16_f32 v33, v33, v33
	v_and_b32_e32 v35, 0xffff0000, v35
	v_and_b32_e32 v38, 0xffff0000, v33
	v_or_b32_sdwa v33, v35, v34 dst_sel:DWORD dst_unused:UNUSED_PAD src0_sel:DWORD src1_sel:WORD_1
	v_lshlrev_b32_e32 v34, 1, v49
	v_or_b32_sdwa v32, v38, v32 dst_sel:DWORD dst_unused:UNUSED_PAD src0_sel:DWORD src1_sel:WORD_1
	v_add_u32_e32 v35, v48, v34
	v_add_u32_e32 v34, v151, v34
	ds_write_b64 v34, v[32:33]
	v_lshl_or_b32 v32, v61, 14, v148
	v_ashrrev_i32_e32 v33, 31, v32
	v_lshl_add_u64 v[118:119], v[32:33], 1, s[0:1]
	ds_write_b64 v35, v[36:37] offset:53248
	v_add_co_u32_e32 v34, vcc, s3, v118
	s_waitcnt lgkmcnt(0)
	s_barrier
; #define LAS __attribute__((address_space(3)))
; #define MFMA16(a, b, c) __builtin_amdgcn_mfma_f32_16x16x32_bf16((a), (b), (c), 0, 0, 0)
; DI void gdn_unit(const Params& P, bf16_t* proj, const float* gb, int b, int h, LAS unsigned char* lds) {
;     ...
;         f32x4 oacc[4];
;         unsigned zr[4][4];
;         const bf16_t* zbase = proj + (size_t)t0 * PJ1 + 3072 + h * 128 + 16 * wave;
;         const int zoffl = fq * 4 * PJ1 + fr;
;         {
; #pragma unroll
;             for (int tt = 0; tt < 4; ++tt)
; #pragma unroll
;                 for (int jj = 0; jj < 4; ++jj) zr[tt][jj] = zbase[(tt * 16 + jj) * PJ1 + zoffl];
;             bf16x8 sb[4], vnb[2];
; #pragma unroll
;             for (int ks = 0; ks < 4; ++ks) sb[ks] = ldsfrag(lds + ST_OFF + (16 * wave + fr) * 272 + (ks * 32 + fq * 8) * 2);
; #pragma unroll
;             for (int ks = 0; ks < 2; ++ks) vnb[ks] = ldsfrag(lds + VN_OFF + (16 * wave + fr) * 144 + (ks * 32 + fq * 8) * 2);
; #pragma unroll
;             for (int tt = 0; tt < 4; ++tt) {
;                 f32x4 a = (f32x4){0.f, 0.f, 0.f, 0.f};
;                 bf16x8 qf[4], atf[2];
; #pragma unroll
;                 for (int ks = 0; ks < 4; ++ks) qf[ks] = ldsfrag(lds + Q_OFF + (tt * 16 + fr) * 272 + (ks * 32 + fq * 8) * 2);
; #pragma unroll
;                 for (int ks = 0; ks < 2; ++ks) atf[ks] = ldsfrag(lds + ATT_OFF + (tt * 16 + fr) * 144 + (ks * 32 + fq * 8) * 2);
;                 const f32x4 e4 = *(const LAS f32x4*)(egcs + tt * 16 + fq * 4);
; #pragma unroll
;                 for (int ks = 0; ks < 4; ++ks) a = MFMA16(qf[ks], sb[ks], a);
;                 a = a * e4;
; #pragma unroll
;                 for (int ks = 0; ks < 2; ++ks) a = MFMA16(atf[ks], vnb[ks], a);
	s_nop 0
	v_addc_co_u32_e32 v35, vcc, 0, v119, vcc
	global_load_ushort v223, v[34:35], off offset:2048
	v_add_co_u32_e32 v34, vcc, s2, v118
	s_mov_b32 s2, 0x18005000
	s_nop 0
	v_addc_co_u32_e32 v35, vcc, 0, v119, vcc
	global_load_ushort v222, v[34:35], off offset:2048
	v_add_co_u32_e32 v34, vcc, s2, v118
	s_mov_b32 s2, 0x18007000
	s_nop 0
	v_addc_co_u32_e32 v35, vcc, 0, v119, vcc
	global_load_ushort v221, v[34:35], off offset:2048
	v_add_co_u32_e32 v34, vcc, s2, v118
	s_nop 1
	v_addc_co_u32_e32 v35, vcc, 0, v119, vcc
	global_load_ushort v220, v[34:35], off offset:2048
	v_add_u32_e32 v34, 0x10000, v32
	v_ashrrev_i32_e32 v35, 31, v34
	v_lshl_add_u64 v[120:121], v[34:35], 1, s[0:1]
	v_add_co_u32_e32 v34, vcc, s3, v120
	s_nop 1
	v_addc_co_u32_e32 v35, vcc, 0, v121, vcc
	global_load_ushort v218, v[34:35], off offset:2048
	v_add_u32_e32 v34, 0x11000, v32
	v_ashrrev_i32_e32 v35, 31, v34
	v_lshl_add_u64 v[124:125], v[34:35], 1, s[0:1]
	v_add_co_u32_e32 v34, vcc, s3, v124
	s_nop 1
	v_addc_co_u32_e32 v35, vcc, 0, v125, vcc
	global_load_ushort v217, v[34:35], off offset:2048
	v_add_u32_e32 v34, 0x12000, v32
	v_ashrrev_i32_e32 v35, 31, v34
	v_lshl_add_u64 v[116:117], v[34:35], 1, s[0:1]
	v_add_co_u32_e32 v34, vcc, s3, v116
	s_nop 1
	v_addc_co_u32_e32 v35, vcc, 0, v117, vcc
	global_load_ushort v216, v[34:35], off offset:2048
	v_add_u32_e32 v34, 0x13000, v32
	v_ashrrev_i32_e32 v35, 31, v34
	v_lshl_add_u64 v[122:123], v[34:35], 1, s[0:1]
	v_add_co_u32_e32 v34, vcc, s3, v122
	s_nop 1
	v_addc_co_u32_e32 v35, vcc, 0, v123, vcc
	global_load_ushort v215, v[34:35], off offset:2048
	v_add_u32_e32 v34, 0x20000, v32
	v_ashrrev_i32_e32 v35, 31, v34
	v_lshl_add_u64 v[128:129], v[34:35], 1, s[0:1]
	v_add_co_u32_e32 v34, vcc, s3, v128
	s_nop 1
	v_addc_co_u32_e32 v35, vcc, 0, v129, vcc
	global_load_ushort v214, v[34:35], off offset:2048
	v_add_u32_e32 v34, 0x21000, v32
	v_ashrrev_i32_e32 v35, 31, v34
	v_lshl_add_u64 v[126:127], v[34:35], 1, s[0:1]
	v_add_co_u32_e32 v34, vcc, s3, v126
	s_nop 1
	v_addc_co_u32_e32 v35, vcc, 0, v127, vcc
	global_load_ushort v213, v[34:35], off offset:2048
	v_add_u32_e32 v34, 0x22000, v32
	v_ashrrev_i32_e32 v35, 31, v34
	v_lshl_add_u64 v[130:131], v[34:35], 1, s[0:1]
	v_add_co_u32_e32 v34, vcc, s3, v130
	s_nop 1
	v_addc_co_u32_e32 v35, vcc, 0, v131, vcc
	global_load_ushort v212, v[34:35], off offset:2048
	v_add_u32_e32 v34, 0x23000, v32
	v_ashrrev_i32_e32 v35, 31, v34
	v_lshl_add_u64 v[132:133], v[34:35], 1, s[0:1]
	v_add_co_u32_e32 v34, vcc, s3, v132
	s_nop 1
	v_addc_co_u32_e32 v35, vcc, 0, v133, vcc
	global_load_ushort v211, v[34:35], off offset:2048
	v_add_u32_e32 v34, 0x30000, v32
	v_ashrrev_i32_e32 v35, 31, v34
	v_lshl_add_u64 v[108:109], v[34:35], 1, s[0:1]
	v_add_co_u32_e32 v34, vcc, s3, v108
	s_nop 1
	v_addc_co_u32_e32 v35, vcc, 0, v109, vcc
	global_load_ushort v210, v[34:35], off offset:2048
	v_add_u32_e32 v34, 0x31000, v32
	v_ashrrev_i32_e32 v35, 31, v34
	v_lshl_add_u64 v[110:111], v[34:35], 1, s[0:1]
	v_add_co_u32_e32 v34, vcc, s3, v110
	s_nop 1
	v_addc_co_u32_e32 v35, vcc, 0, v111, vcc
	global_load_ushort v209, v[34:35], off offset:2048
	v_add_u32_e32 v34, 0x32000, v32
	v_ashrrev_i32_e32 v35, 31, v34
	v_lshl_add_u64 v[112:113], v[34:35], 1, s[0:1]
	v_add_u32_e32 v32, 0x33000, v32
	v_add_co_u32_e32 v34, vcc, s3, v112
	v_ashrrev_i32_e32 v33, 31, v32
	s_nop 0
	v_addc_co_u32_e32 v35, vcc, 0, v113, vcc
	v_lshl_add_u64 v[114:115], v[32:33], 1, s[0:1]
	v_add_co_u32_e32 v32, vcc, s3, v114
	global_load_ushort v208, v[34:35], off offset:2048
	s_nop 0
	v_addc_co_u32_e32 v33, vcc, 0, v115, vcc
	global_load_ushort v206, v[32:33], off offset:2048
	ds_read_b128 v[32:35], v149
	ds_read_b128 v[56:59], v52
	ds_read_b128 v[36:39], v149 offset:64
	ds_read_b128 v[48:51], v52 offset:64
	ds_read_b128 v[40:43], v149 offset:128
	s_waitcnt lgkmcnt(3)
	v_mfma_f32_16x16x32_bf16 v[32:35], v[32:35], v[56:59], 0
	ds_read_b128 v[60:63], v52 offset:128
	ds_read_b128 v[52:55], v52 offset:192
	ds_read_b128 v[44:47], v149 offset:192
	v_readlane_b32 s0, v255, 8
	ds_read_b128 v[228:231], v227
	s_waitcnt lgkmcnt(5)
	v_mfma_f32_16x16x32_bf16 v[36:39], v[36:39], v[48:51], v[32:35]
	v_add_u32_e32 v226, s0, v134
	v_mad_u32_u24 v66, v148, s37, v226
	v_cmp_eq_u32_e32 vcc, 0, v148
	ds_read_b128 v[32:35], v64 offset:53248
	s_waitcnt lgkmcnt(4)
	v_mfma_f32_16x16x32_bf16 v[36:39], v[40:43], v[60:63], v[36:39]
	ds_read_b128 v[40:43], v66
	v_add_u32_e32 v148, s49, v225
	s_waitcnt lgkmcnt(3)
	v_mfma_f32_16x16x32_bf16 v[36:39], v[44:47], v[52:55], v[36:39]
	ds_read_b128 v[44:47], v66 offset:64
	ds_read_b128 v[64:67], v64 offset:53312
	s_waitcnt lgkmcnt(4)
	s_nop 4
	v_pk_mul_f32 v[38:39], v[230:231], v[38:39]
	v_pk_mul_f32 v[36:37], v[228:229], v[36:37]
	s_waitcnt lgkmcnt(2)
	s_nop 0
	v_mfma_f32_16x16x32_bf16 v[36:39], v[40:43], v[32:35], v[36:39]
	s_waitcnt lgkmcnt(0)
; #define LAS __attribute__((address_space(3)))
; #define MFMA16(a, b, c) __builtin_amdgcn_mfma_f32_16x16x32_bf16((a), (b), (c), 0, 0, 0)
; DI float row16_sum(float v) { v += dppf<0xB1>(v); v += dppf<0x4E>(v); v += dppf<0x141>(v); v += dppf<0x140>(v); return v; }
; DI void gdn_unit(const Params& P, bf16_t* proj, const float* gb, int b, int h, LAS unsigned char* lds) {
;     ...
;             for (int tt = 0; tt < 4; ++tt) {
;                 f32x4 a = (f32x4){0.f, 0.f, 0.f, 0.f};
;                 bf16x8 qf[4], atf[2];
; #pragma unroll
;                 for (int ks = 0; ks < 4; ++ks) qf[ks] = ldsfrag(lds + Q_OFF + (tt * 16 + fr) * 272 + (ks * 32 + fq * 8) * 2);
; #pragma unroll
;                 for (int ks = 0; ks < 2; ++ks) atf[ks] = ldsfrag(lds + ATT_OFF + (tt * 16 + fr) * 144 + (ks * 32 + fq * 8) * 2);
;                 const f32x4 e4 = *(const LAS f32x4*)(egcs + tt * 16 + fq * 4);
; #pragma unroll
;                 for (int ks = 0; ks < 4; ++ks) a = MFMA16(qf[ks], sb[ks], a);
;                 a = a * e4;
; #pragma unroll
;                 for (int ks = 0; ks < 2; ++ks) a = MFMA16(atf[ks], vnb[ks], a);
;                 oacc[tt] = a;
; #pragma unroll
;                 for (int jj = 0; jj < 4; ++jj) {
;                     const float s = row16_sum(a[jj] * a[jj]);
;                     if (fr == 0) part[wave * 64 + tt * 16 + fq * 4 + jj] = s;
;                 }
;             }
	v_mfma_f32_16x16x32_bf16 v[44:47], v[44:47], v[64:67], v[36:39]
	s_nop 7
	v_mul_f32_e32 v36, v44, v44
	s_nop 1
	v_mov_b32_dpp v36, v36 quad_perm:[1,0,3,2] row_mask:0xf bank_mask:0xf bound_ctrl:1
	v_fmac_f32_e32 v36, v44, v44
	s_nop 1
	v_add_f32_dpp v36, v36, v36 quad_perm:[2,3,0,1] row_mask:0xf bank_mask:0xf bound_ctrl:1
	s_nop 1
	v_add_f32_dpp v36, v36, v36 row_half_mirror row_mask:0xf bank_mask:0xf bound_ctrl:1
	s_nop 1
	v_mov_b32_dpp v37, v36 row_mirror row_mask:0xf bank_mask:0xf bound_ctrl:1
	s_and_saveexec_b64 s[0:1], vcc
	v_add_f32_e32 v36, v36, v37
	ds_write_b32 v148, v36
	s_or_b64 exec, exec, s[0:1]
	v_mul_f32_e32 v36, v45, v45
	s_nop 1
	v_mov_b32_dpp v36, v36 quad_perm:[1,0,3,2] row_mask:0xf bank_mask:0xf bound_ctrl:1
	v_fmac_f32_e32 v36, v45, v45
	s_nop 1
	v_add_f32_dpp v36, v36, v36 quad_perm:[2,3,0,1] row_mask:0xf bank_mask:0xf bound_ctrl:1
	s_nop 1
	v_add_f32_dpp v36, v36, v36 row_half_mirror row_mask:0xf bank_mask:0xf bound_ctrl:1
	s_nop 1
	v_mov_b32_dpp v37, v36 row_mirror row_mask:0xf bank_mask:0xf bound_ctrl:1
	s_and_saveexec_b64 s[0:1], vcc
	v_add_f32_e32 v36, v36, v37
	ds_write_b32 v148, v36 offset:4
	s_or_b64 exec, exec, s[0:1]
	v_mul_f32_e32 v36, v46, v46
	s_nop 1
	v_mov_b32_dpp v36, v36 quad_perm:[1,0,3,2] row_mask:0xf bank_mask:0xf bound_ctrl:1
	v_fmac_f32_e32 v36, v46, v46
	s_nop 1
	v_add_f32_dpp v36, v36, v36 quad_perm:[2,3,0,1] row_mask:0xf bank_mask:0xf bound_ctrl:1
	s_nop 1
	v_add_f32_dpp v36, v36, v36 row_half_mirror row_mask:0xf bank_mask:0xf bound_ctrl:1
	s_nop 1
	v_mov_b32_dpp v37, v36 row_mirror row_mask:0xf bank_mask:0xf bound_ctrl:1
	s_and_saveexec_b64 s[0:1], vcc
	v_add_f32_e32 v36, v36, v37
	ds_write_b32 v148, v36 offset:8
	s_or_b64 exec, exec, s[0:1]
	v_mul_f32_e32 v36, v47, v47
	s_nop 1
	v_mov_b32_dpp v36, v36 quad_perm:[1,0,3,2] row_mask:0xf bank_mask:0xf bound_ctrl:1
	v_fmac_f32_e32 v36, v47, v47
	s_nop 1
	v_add_f32_dpp v36, v36, v36 quad_perm:[2,3,0,1] row_mask:0xf bank_mask:0xf bound_ctrl:1
	s_nop 1
	v_add_f32_dpp v36, v36, v36 row_half_mirror row_mask:0xf bank_mask:0xf bound_ctrl:1
	s_nop 1
	v_mov_b32_dpp v37, v36 row_mirror row_mask:0xf bank_mask:0xf bound_ctrl:1
	s_and_saveexec_b64 s[0:1], vcc
	v_add_f32_e32 v36, v36, v37
	ds_write_b32 v148, v36 offset:12
	s_or_b64 exec, exec, s[0:1]
	ds_read_b128 v[36:39], v149 offset:4352
	ds_read_b128 v[40:43], v149 offset:4416
	v_add_u32_e32 v138, v226, v224
	ds_read_b128 v[228:231], v138
	s_waitcnt lgkmcnt(2)
	v_mfma_f32_16x16x32_bf16 v[36:39], v[36:39], v[56:59], 0
	s_waitcnt lgkmcnt(1)
	v_mfma_f32_16x16x32_bf16 v[36:39], v[40:43], v[48:51], v[36:39]
	ds_read_b128 v[40:43], v149 offset:4480
	s_waitcnt lgkmcnt(0)
	v_mfma_f32_16x16x32_bf16 v[36:39], v[40:43], v[60:63], v[36:39]
	ds_read_b128 v[40:43], v149 offset:4544
	s_waitcnt lgkmcnt(0)
	v_mfma_f32_16x16x32_bf16 v[36:39], v[40:43], v[52:55], v[36:39]
	ds_read_b128 v[40:43], v227 offset:64
	s_waitcnt lgkmcnt(0)
	s_nop 5
	v_pk_mul_f32 v[38:39], v[42:43], v[38:39]
	v_pk_mul_f32 v[36:37], v[40:41], v[36:37]
	ds_read_b128 v[40:43], v138 offset:64
	s_nop 0
	v_mfma_f32_16x16x32_bf16 v[36:39], v[228:231], v[32:35], v[36:39]
	s_waitcnt lgkmcnt(0)
	v_mfma_f32_16x16x32_bf16 v[40:43], v[40:43], v[64:67], v[36:39]
	s_nop 7
	v_mul_f32_e32 v36, v40, v40
	s_nop 1
	v_mov_b32_dpp v36, v36 quad_perm:[1,0,3,2] row_mask:0xf bank_mask:0xf bound_ctrl:1
	v_fmac_f32_e32 v36, v40, v40
	s_nop 1
	v_add_f32_dpp v36, v36, v36 quad_perm:[2,3,0,1] row_mask:0xf bank_mask:0xf bound_ctrl:1
	s_nop 1
	v_add_f32_dpp v36, v36, v36 row_half_mirror row_mask:0xf bank_mask:0xf bound_ctrl:1
	s_nop 1
	v_mov_b32_dpp v37, v36 row_mirror row_mask:0xf bank_mask:0xf bound_ctrl:1
	s_and_saveexec_b64 s[0:1], vcc
	v_add_f32_e32 v36, v36, v37
	ds_write_b32 v148, v36 offset:64
	s_or_b64 exec, exec, s[0:1]
	v_mul_f32_e32 v36, v41, v41
	s_nop 1
	v_mov_b32_dpp v36, v36 quad_perm:[1,0,3,2] row_mask:0xf bank_mask:0xf bound_ctrl:1
	v_fmac_f32_e32 v36, v41, v41
	s_nop 1
	v_add_f32_dpp v36, v36, v36 quad_perm:[2,3,0,1] row_mask:0xf bank_mask:0xf bound_ctrl:1
	s_nop 1
	v_add_f32_dpp v36, v36, v36 row_half_mirror row_mask:0xf bank_mask:0xf bound_ctrl:1
	s_nop 1
	v_mov_b32_dpp v37, v36 row_mirror row_mask:0xf bank_mask:0xf bound_ctrl:1
	s_and_saveexec_b64 s[0:1], vcc
	v_add_f32_e32 v36, v36, v37
	ds_write_b32 v148, v36 offset:68
	s_or_b64 exec, exec, s[0:1]
	v_mul_f32_e32 v36, v42, v42
	s_nop 1
	v_mov_b32_dpp v36, v36 quad_perm:[1,0,3,2] row_mask:0xf bank_mask:0xf bound_ctrl:1
	v_fmac_f32_e32 v36, v42, v42
	s_nop 1
	v_add_f32_dpp v36, v36, v36 quad_perm:[2,3,0,1] row_mask:0xf bank_mask:0xf bound_ctrl:1
	s_nop 1
	v_add_f32_dpp v36, v36, v36 row_half_mirror row_mask:0xf bank_mask:0xf bound_ctrl:1
	s_nop 1
	v_mov_b32_dpp v37, v36 row_mirror row_mask:0xf bank_mask:0xf bound_ctrl:1
	s_and_saveexec_b64 s[0:1], vcc
	v_add_f32_e32 v36, v36, v37
	ds_write_b32 v148, v36 offset:72
	s_or_b64 exec, exec, s[0:1]
	v_mul_f32_e32 v36, v43, v43
	s_nop 1
	v_mov_b32_dpp v36, v36 quad_perm:[1,0,3,2] row_mask:0xf bank_mask:0xf bound_ctrl:1
	v_fmac_f32_e32 v36, v43, v43
	s_nop 1
	v_add_f32_dpp v36, v36, v36 quad_perm:[2,3,0,1] row_mask:0xf bank_mask:0xf bound_ctrl:1
	s_nop 1
	v_add_f32_dpp v36, v36, v36 row_half_mirror row_mask:0xf bank_mask:0xf bound_ctrl:1
	s_nop 1
	v_mov_b32_dpp v37, v36 row_mirror row_mask:0xf bank_mask:0xf bound_ctrl:1
	s_and_saveexec_b64 s[0:1], vcc
	v_add_f32_e32 v36, v36, v37
	ds_write_b32 v148, v36 offset:76
	s_or_b64 exec, exec, s[0:1]
	ds_read_b128 v[36:39], v149 offset:8704
	ds_read_b128 v[228:231], v149 offset:8768
	v_add_u32_e32 v138, v226, v153
	ds_read_b128 v[232:235], v138
	s_waitcnt lgkmcnt(2)
	v_mfma_f32_16x16x32_bf16 v[36:39], v[36:39], v[56:59], 0
	s_waitcnt lgkmcnt(1)
; #define LAS __attribute__((address_space(3)))
; #define MFMA16(a, b, c) __builtin_amdgcn_mfma_f32_16x16x32_bf16((a), (b), (c), 0, 0, 0)
; DI float row16_sum(float v) { v += dppf<0xB1>(v); v += dppf<0x4E>(v); v += dppf<0x141>(v); v += dppf<0x140>(v); return v; }
; DI void gdn_unit(const Params& P, bf16_t* proj, const float* gb, int b, int h, LAS unsigned char* lds) {
;     ...
;             for (int tt = 0; tt < 4; ++tt) {
;                 f32x4 a = (f32x4){0.f, 0.f, 0.f, 0.f};
;                 bf16x8 qf[4], atf[2];
; #pragma unroll
;                 for (int ks = 0; ks < 4; ++ks) qf[ks] = ldsfrag(lds + Q_OFF + (tt * 16 + fr) * 272 + (ks * 32 + fq * 8) * 2);
; #pragma unroll
;                 for (int ks = 0; ks < 2; ++ks) atf[ks] = ldsfrag(lds + ATT_OFF + (tt * 16 + fr) * 144 + (ks * 32 + fq * 8) * 2);
;                 const f32x4 e4 = *(const LAS f32x4*)(egcs + tt * 16 + fq * 4);
; #pragma unroll
;                 for (int ks = 0; ks < 4; ++ks) a = MFMA16(qf[ks], sb[ks], a);
;                 a = a * e4;
; #pragma unroll
;                 for (int ks = 0; ks < 2; ++ks) a = MFMA16(atf[ks], vnb[ks], a);
;                 oacc[tt] = a;
; #pragma unroll
;                 for (int jj = 0; jj < 4; ++jj) {
;                     const float s = row16_sum(a[jj] * a[jj]);
;                     if (fr == 0) part[wave * 64 + tt * 16 + fq * 4 + jj] = s;
;                 }
;             }
	v_mfma_f32_16x16x32_bf16 v[36:39], v[228:231], v[48:51], v[36:39]
	ds_read_b128 v[228:231], v149 offset:8832
	s_waitcnt lgkmcnt(0)
	v_mfma_f32_16x16x32_bf16 v[36:39], v[228:231], v[60:63], v[36:39]
	ds_read_b128 v[228:231], v149 offset:8896
	s_waitcnt lgkmcnt(0)
	v_mfma_f32_16x16x32_bf16 v[36:39], v[228:231], v[52:55], v[36:39]
	ds_read_b128 v[228:231], v227 offset:128
	s_waitcnt lgkmcnt(0)
	s_nop 5
	v_pk_mul_f32 v[38:39], v[230:231], v[38:39]
	v_pk_mul_f32 v[36:37], v[228:229], v[36:37]
	ds_read_b128 v[228:231], v138 offset:64
	s_nop 0
	v_mfma_f32_16x16x32_bf16 v[36:39], v[232:235], v[32:35], v[36:39]
	s_waitcnt lgkmcnt(0)
	v_mfma_f32_16x16x32_bf16 v[36:39], v[228:231], v[64:67], v[36:39]
	s_nop 7
	v_mul_f32_e32 v138, v36, v36
	s_nop 1
	v_mov_b32_dpp v138, v138 quad_perm:[1,0,3,2] row_mask:0xf bank_mask:0xf bound_ctrl:1
	v_fmac_f32_e32 v138, v36, v36
	s_nop 1
	v_add_f32_dpp v138, v138, v138 quad_perm:[2,3,0,1] row_mask:0xf bank_mask:0xf bound_ctrl:1
	s_nop 1
	v_add_f32_dpp v153, v138, v138 row_half_mirror row_mask:0xf bank_mask:0xf bound_ctrl:1
	s_nop 1
	v_mov_b32_dpp v224, v153 row_mirror row_mask:0xf bank_mask:0xf bound_ctrl:1
	s_and_saveexec_b64 s[0:1], vcc
	v_add_f32_e32 v138, v153, v224
	ds_write_b32 v148, v138 offset:128
	s_or_b64 exec, exec, s[0:1]
	v_mul_f32_e32 v138, v37, v37
	s_nop 1
	v_mov_b32_dpp v138, v138 quad_perm:[1,0,3,2] row_mask:0xf bank_mask:0xf bound_ctrl:1
	v_fmac_f32_e32 v138, v37, v37
	s_nop 1
	v_add_f32_dpp v138, v138, v138 quad_perm:[2,3,0,1] row_mask:0xf bank_mask:0xf bound_ctrl:1
	s_nop 1
	v_add_f32_dpp v153, v138, v138 row_half_mirror row_mask:0xf bank_mask:0xf bound_ctrl:1
	s_nop 1
	v_mov_b32_dpp v224, v153 row_mirror row_mask:0xf bank_mask:0xf bound_ctrl:1
	s_and_saveexec_b64 s[0:1], vcc
	v_add_f32_e32 v138, v153, v224
	ds_write_b32 v148, v138 offset:132
	s_or_b64 exec, exec, s[0:1]
	v_mul_f32_e32 v138, v38, v38
	s_nop 1
	v_mov_b32_dpp v138, v138 quad_perm:[1,0,3,2] row_mask:0xf bank_mask:0xf bound_ctrl:1
	v_fmac_f32_e32 v138, v38, v38
	s_nop 1
	v_add_f32_dpp v138, v138, v138 quad_perm:[2,3,0,1] row_mask:0xf bank_mask:0xf bound_ctrl:1
	s_nop 1
	v_add_f32_dpp v153, v138, v138 row_half_mirror row_mask:0xf bank_mask:0xf bound_ctrl:1
	s_nop 1
	v_mov_b32_dpp v224, v153 row_mirror row_mask:0xf bank_mask:0xf bound_ctrl:1
	s_and_saveexec_b64 s[0:1], vcc
	v_add_f32_e32 v138, v153, v224
	ds_write_b32 v148, v138 offset:136
	s_or_b64 exec, exec, s[0:1]
	v_mul_f32_e32 v138, v39, v39
	s_nop 1
	v_mov_b32_dpp v138, v138 quad_perm:[1,0,3,2] row_mask:0xf bank_mask:0xf bound_ctrl:1
	v_fmac_f32_e32 v138, v39, v39
	s_nop 1
	v_add_f32_dpp v138, v138, v138 quad_perm:[2,3,0,1] row_mask:0xf bank_mask:0xf bound_ctrl:1
	s_nop 1
	v_add_f32_dpp v153, v138, v138 row_half_mirror row_mask:0xf bank_mask:0xf bound_ctrl:1
	s_nop 1
	v_mov_b32_dpp v224, v153 row_mirror row_mask:0xf bank_mask:0xf bound_ctrl:1
	s_and_saveexec_b64 s[0:1], vcc
	v_add_f32_e32 v138, v153, v224
	ds_write_b32 v148, v138 offset:140
	s_or_b64 exec, exec, s[0:1]
	ds_read_b128 v[228:231], v149 offset:13056
	v_add_u32_e32 v138, v226, v152
	s_waitcnt lgkmcnt(0)
	v_mfma_f32_16x16x32_bf16 v[56:59], v[228:231], v[56:59], 0
	ds_read_b128 v[228:231], v149 offset:13120
	s_waitcnt lgkmcnt(0)
	v_mfma_f32_16x16x32_bf16 v[48:51], v[228:231], v[48:51], v[56:59]
	s_nop 4
	ds_read_b128 v[56:59], v149 offset:13184
	s_waitcnt lgkmcnt(0)
	v_mfma_f32_16x16x32_bf16 v[48:51], v[56:59], v[60:63], v[48:51]
	ds_read_b128 v[56:59], v149 offset:13248
	ds_read_b128 v[60:63], v138
	s_waitcnt lgkmcnt(1)
	v_mfma_f32_16x16x32_bf16 v[48:51], v[56:59], v[52:55], v[48:51]
	ds_read_b128 v[52:55], v227 offset:192
	s_waitcnt lgkmcnt(0)
	s_nop 5
	v_pk_mul_f32 v[50:51], v[54:55], v[50:51]
	v_pk_mul_f32 v[48:49], v[52:53], v[48:49]
	s_nop 1
	v_mfma_f32_16x16x32_bf16 v[32:35], v[60:63], v[32:35], v[48:51]
	s_nop 2
	ds_read_b128 v[48:51], v138 offset:64
	s_waitcnt lgkmcnt(0)
	v_mfma_f32_16x16x32_bf16 v[32:35], v[48:51], v[64:67], v[32:35]
	s_nop 7
	v_mul_f32_e32 v48, v32, v32
	s_nop 1
	v_mov_b32_dpp v48, v48 quad_perm:[1,0,3,2] row_mask:0xf bank_mask:0xf bound_ctrl:1
	v_fmac_f32_e32 v48, v32, v32
	s_nop 1
	v_add_f32_dpp v48, v48, v48 quad_perm:[2,3,0,1] row_mask:0xf bank_mask:0xf bound_ctrl:1
	s_nop 1
	v_add_f32_dpp v48, v48, v48 row_half_mirror row_mask:0xf bank_mask:0xf bound_ctrl:1
	s_nop 1
	v_mov_b32_dpp v49, v48 row_mirror row_mask:0xf bank_mask:0xf bound_ctrl:1
	s_and_saveexec_b64 s[0:1], vcc
	v_add_f32_e32 v48, v48, v49
	ds_write_b32 v148, v48 offset:192
	s_or_b64 exec, exec, s[0:1]
	v_mul_f32_e32 v48, v33, v33
	s_nop 1
	v_mov_b32_dpp v48, v48 quad_perm:[1,0,3,2] row_mask:0xf bank_mask:0xf bound_ctrl:1
	v_fmac_f32_e32 v48, v33, v33
	s_nop 1
	v_add_f32_dpp v48, v48, v48 quad_perm:[2,3,0,1] row_mask:0xf bank_mask:0xf bound_ctrl:1
	s_nop 1
	v_add_f32_dpp v48, v48, v48 row_half_mirror row_mask:0xf bank_mask:0xf bound_ctrl:1
	s_nop 1
	v_mov_b32_dpp v49, v48 row_mirror row_mask:0xf bank_mask:0xf bound_ctrl:1
	s_and_saveexec_b64 s[0:1], vcc
	v_add_f32_e32 v48, v48, v49
	ds_write_b32 v148, v48 offset:196
	s_or_b64 exec, exec, s[0:1]
	v_mul_f32_e32 v48, v34, v34
	s_nop 1
	v_mov_b32_dpp v48, v48 quad_perm:[1,0,3,2] row_mask:0xf bank_mask:0xf bound_ctrl:1
	v_fmac_f32_e32 v48, v34, v34
	s_nop 1
	v_add_f32_dpp v48, v48, v48 quad_perm:[2,3,0,1] row_mask:0xf bank_mask:0xf bound_ctrl:1
	s_nop 1
	v_add_f32_dpp v48, v48, v48 row_half_mirror row_mask:0xf bank_mask:0xf bound_ctrl:1
	s_nop 1
	v_mov_b32_dpp v49, v48 row_mirror row_mask:0xf bank_mask:0xf bound_ctrl:1
	s_and_saveexec_b64 s[0:1], vcc
	v_add_f32_e32 v48, v48, v49
	ds_write_b32 v148, v48 offset:200
	s_or_b64 exec, exec, s[0:1]
	v_mul_f32_e32 v48, v35, v35
	s_nop 1
	v_mov_b32_dpp v48, v48 quad_perm:[1,0,3,2] row_mask:0xf bank_mask:0xf bound_ctrl:1
	v_fmac_f32_e32 v48, v35, v35
	s_nop 1
	v_add_f32_dpp v48, v48, v48 quad_perm:[2,3,0,1] row_mask:0xf bank_mask:0xf bound_ctrl:1
	s_nop 1
	v_add_f32_dpp v48, v48, v48 row_half_mirror row_mask:0xf bank_mask:0xf bound_ctrl:1
	s_nop 1
	v_mov_b32_dpp v49, v48 row_mirror row_mask:0xf bank_mask:0xf bound_ctrl:1
	s_and_saveexec_b64 s[0:1], vcc
	s_cbranch_execz .LBB0_414
	v_add_f32_e32 v48, v48, v49
	ds_write_b32 v148, v48 offset:204
	s_branch .LBB0_414
